# peeled first K-iteration with C=0 in all zero-init GEMM instances (drops 128 v_mov per unit) on top of barrier early-invalidate
# speedup vs baseline: 1.0079x; 1.0079x over previous
; #define PG8_STAGE(bufoff, gbase, voff) do { _Pragma("unroll") for (int _i = 0; _i < 2; ++_i) \
;         __builtin_amdgcn_global_load_lds((const unsigned*)((const char*)(gbase) + (voff)[_i]), (LAS unsigned*)(lds + (bufoff) + ldsw + _i * 8192), 16, 0, 0); } while (0)
; #define PG8_LDA(dst, b, h) do { _Pragma("unroll") for (int m = 0; m < 4; ++m) _Pragma("unroll") for (int k = 0; k < 2; ++k) dst[m][k] = *(const LAS bf16x8*)(lds + PG8_SA(b, h) + aoff + m * 2048 + k * 1024); } while (0)
; #define PG8_LDB(dst, b, h) do { _Pragma("unroll") for (int n = 0; n < 2; ++n) _Pragma("unroll") for (int k = 0; k < 2; ++k) dst[n][k] = *(const LAS bf16x8*)(lds + PG8_SB(b, h) + boff + n * 2048 + k * 1024); } while (0)
; #define PG8_MMA(ai, bj, At, Bt) do { __builtin_amdgcn_s_setprio(1); _Pragma("unroll") for (int m = 0; m < 4; ++m) _Pragma("unroll") for (int n = 0; n < 2; ++n) _Pragma("unroll") for (int k = 0; k < 2; ++k) \
;         acc[ai][bj][m][n] = __builtin_amdgcn_mfma_f32_16x16x32_bf16(Bt[n][k], At[m][k], acc[ai][bj][m][n], 0, 0, 0); __builtin_amdgcn_s_setprio(0); } while (0)
; #define PG8_WAIT_V(n) asm volatile("s_waitcnt vmcnt(" #n ")" ::: "memory")
; #define PG8_WAIT_L(n) asm volatile("s_waitcnt lgkmcnt(" #n ")" ::: "memory")
; #define PG8_BAR __builtin_amdgcn_s_barrier()
; template <class Epi, class Sched>
; __device__ __forceinline__ void gemm_phase(const int tid, LAS unsigned char* lds, const int lda, const int ldb, const int K, const Sched& S, const Epi& E) {
;     ...
;         for (int t = 0; t < nt; t += 2) {
;             const bool last = (t == nt - 2);
;             const char* a1 = cA + (size_t)(t + 1) * kstep;
;             const char* a2 = last ? nA : cA + (size_t)(t + 2) * kstep; const char* b2 = last ? nB : cB + (size_t)(t + 2) * kstep;
;             const char* a3 = a2 + kstep; const char* b3 = b2 + kstep;
;             PG8_LDB(B0, 0, 0); PG8_LDB(B1, 0, 1); PG8_SCHED; PG8_LDA(At, 0, 0); PG8_STAGE(PG8_SA(1, 1), a1 + hstepA, voffA);
;             PG8_WAIT_V(8); PG8_WAIT_L(0); PG8_BAR; PG8_MMA(0, 0, At, B0); PG8_MMA(0, 1, At, B1); PG8_BAR; PG8_SCHED;
;             PG8_LDA(At, 0, 1); PG8_STAGE(PG8_SB(0, 0), b2, voffB); PG8_STAGE(PG8_SB(0, 1), b2 + hstepB, voffB); PG8_STAGE(PG8_SA(0, 0), a2, voffA);
;             PG8_WAIT_V(8); PG8_WAIT_L(0); PG8_BAR; if (!cur.half) { PG8_MMA(1, 0, At, B0); PG8_MMA(1, 1, At, B1); } PG8_BAR; PG8_SCHED;
.LBB0_195:
	s_andn2_b64 vcc, exec, s[42:43]
	s_cbranch_vccnz .LBB0_203
	s_add_u32 s38, s38, 0x40080
	s_addc_u32 s39, s39, 0
	s_add_u32 s47, s52, 0x100
	s_addc_u32 s67, s53, 0
	s_mov_b32 s52, 0
	s_add_i32 s68, s52, 2
	s_add_u32 s14, s38, 0xfffc0080
	s_addc_u32 s15, s39, -1
	s_add_i32 s24, 0, 0x10000
	s_cmp_eq_u32 s64, s52
	s_cselect_b32 s55, s3, s15
	s_cselect_b32 s54, s2, s14
	v_add_u32_e32 v155, s24, v146
	s_cselect_b32 s53, s23, s67
	s_cselect_b32 s52, s22, s47
	s_add_i32 s14, 0, 0x14000
	ds_read_b128 v[156:159], v155
	ds_read_b128 v[160:163], v155 offset:1024
	ds_read_b128 v[164:167], v155 offset:2048
	ds_read_b128 v[180:183], v155 offset:3072
	v_add_u32_e32 v155, s14, v146
	ds_read_b128 v[184:187], v155
	ds_read_b128 v[190:193], v155 offset:1024
	ds_read_b128 v[194:197], v155 offset:2048
	ds_read_b128 v[206:209], v155 offset:3072
	v_lshl_add_u64 v[242:243], s[38:39], 0, v[136:137]
	s_add_i32 m0, s57, 0xc000
	ds_read_b128 v[210:213], v154
	ds_read_b128 v[214:217], v154 offset:1024
	ds_read_b128 v[218:221], v154 offset:2048
	ds_read_b128 v[222:225], v154 offset:3072
	ds_read_b128 v[226:229], v154 offset:4096
	ds_read_b128 v[230:233], v154 offset:5120
	ds_read_b128 v[234:237], v154 offset:6144
	ds_read_b128 v[238:241], v154 offset:7168
	global_load_lds_dwordx4 v[242:243], off
	v_lshl_add_u64 v[242:243], s[38:39], 0, v[138:139]
	s_add_i32 m0, s57, 0xe000
	s_nop 0
	global_load_lds_dwordx4 v[242:243], off
	s_waitcnt vmcnt(8)
	s_waitcnt lgkmcnt(0)
	s_barrier
	s_setprio 1
	s_waitcnt lgkmcnt(0)
	v_mfma_f32_16x16x32_bf16 v[124:127], v[156:159], v[210:213], 0
	v_mfma_f32_16x16x32_bf16 v[120:123], v[164:167], v[210:213], 0
	v_mfma_f32_16x16x32_bf16 v[108:111], v[156:159], v[218:221], 0
	v_mfma_f32_16x16x32_bf16 v[104:107], v[164:167], v[218:221], 0
	v_mfma_f32_16x16x32_bf16 v[92:95], v[156:159], v[226:229], 0
	v_mfma_f32_16x16x32_bf16 v[88:91], v[164:167], v[226:229], 0
	v_mfma_f32_16x16x32_bf16 v[76:79], v[156:159], v[234:237], 0
	v_mfma_f32_16x16x32_bf16 v[72:75], v[164:167], v[234:237], 0
	v_mfma_f32_16x16x32_bf16 v[124:127], v[160:163], v[214:217], v[124:127]
	v_mfma_f32_16x16x32_bf16 v[120:123], v[180:183], v[214:217], v[120:123]
	v_mfma_f32_16x16x32_bf16 v[108:111], v[160:163], v[222:225], v[108:111]
	v_mfma_f32_16x16x32_bf16 v[104:107], v[180:183], v[222:225], v[104:107]
	v_mfma_f32_16x16x32_bf16 v[92:95], v[160:163], v[230:233], v[92:95]
	v_mfma_f32_16x16x32_bf16 v[88:91], v[180:183], v[230:233], v[88:91]
	v_mfma_f32_16x16x32_bf16 v[76:79], v[160:163], v[238:241], v[76:79]
	v_mfma_f32_16x16x32_bf16 v[72:75], v[180:183], v[238:241], v[72:75]
	s_setprio 0
	s_setprio 1
	v_mfma_f32_16x16x32_bf16 v[116:119], v[184:187], v[210:213], 0
	v_mfma_f32_16x16x32_bf16 v[112:115], v[194:197], v[210:213], 0
	v_mfma_f32_16x16x32_bf16 v[100:103], v[184:187], v[218:221], 0
	v_mfma_f32_16x16x32_bf16 v[96:99], v[194:197], v[218:221], 0
	v_mfma_f32_16x16x32_bf16 v[84:87], v[184:187], v[226:229], 0
	v_mfma_f32_16x16x32_bf16 v[80:83], v[194:197], v[226:229], 0
	v_mfma_f32_16x16x32_bf16 v[68:71], v[184:187], v[234:237], 0
	v_mfma_f32_16x16x32_bf16 v[64:67], v[194:197], v[234:237], 0
	v_mfma_f32_16x16x32_bf16 v[116:119], v[190:193], v[214:217], v[116:119]
	v_mfma_f32_16x16x32_bf16 v[112:115], v[206:209], v[214:217], v[112:115]
	v_mfma_f32_16x16x32_bf16 v[100:103], v[190:193], v[222:225], v[100:103]
	v_mfma_f32_16x16x32_bf16 v[96:99], v[206:209], v[222:225], v[96:99]
	v_mfma_f32_16x16x32_bf16 v[84:87], v[190:193], v[230:233], v[84:87]
	v_mfma_f32_16x16x32_bf16 v[80:83], v[206:209], v[230:233], v[80:83]
	v_mfma_f32_16x16x32_bf16 v[68:71], v[190:193], v[238:241], v[68:71]
	v_mfma_f32_16x16x32_bf16 v[64:67], v[206:209], v[238:241], v[64:67]
	s_setprio 0
	s_barrier
	s_add_i32 s15, s24, s56
	v_lshl_add_u64 v[242:243], s[52:53], 0, v[130:131]
	s_mov_b32 m0, s15
	ds_read_b128 v[210:213], v154 offset:16384
	ds_read_b128 v[214:217], v154 offset:17408
	ds_read_b128 v[218:221], v154 offset:18432
	ds_read_b128 v[222:225], v154 offset:19456
	ds_read_b128 v[226:229], v154 offset:20480
	ds_read_b128 v[230:233], v154 offset:21504
	ds_read_b128 v[234:237], v154 offset:22528
	ds_read_b128 v[238:241], v154 offset:23552
	global_load_lds_dwordx4 v[242:243], off
	s_add_i32 m0, s15, 0x2000
	s_add_u32 s70, s52, 0x40000
	v_lshl_add_u64 v[244:245], s[52:53], 0, v[134:135]
	s_addc_u32 s71, s53, 0
	s_add_i32 s14, s14, s56
	global_load_lds_dwordx4 v[244:245], off
	v_lshl_add_u64 v[246:247], s[70:71], 0, v[130:131]
	s_mov_b32 m0, s14
	v_lshl_add_u64 v[248:249], s[54:55], 0, v[132:133]
	global_load_lds_dwordx4 v[246:247], off
	v_lshl_add_u64 v[246:247], s[70:71], 0, v[134:135]
	s_add_i32 m0, s14, 0x2000
	s_nop 0
	global_load_lds_dwordx4 v[246:247], off
	v_lshl_add_u64 v[246:247], s[54:55], 0, v[128:129]
	s_mov_b32 m0, s57
	s_nop 0
	global_load_lds_dwordx4 v[246:247], off
	s_mov_b32 m0, s58
	s_nop 0
	global_load_lds_dwordx4 v[248:249], off
	s_waitcnt vmcnt(8)
	s_waitcnt lgkmcnt(0)
	s_barrier
; #define PG8_STAGE(bufoff, gbase, voff) do { _Pragma("unroll") for (int _i = 0; _i < 2; ++_i) \
;         __builtin_amdgcn_global_load_lds((const unsigned*)((const char*)(gbase) + (voff)[_i]), (LAS unsigned*)(lds + (bufoff) + ldsw + _i * 8192), 16, 0, 0); } while (0)
; #define PG8_LDA(dst, b, h) do { _Pragma("unroll") for (int m = 0; m < 4; ++m) _Pragma("unroll") for (int k = 0; k < 2; ++k) dst[m][k] = *(const LAS bf16x8*)(lds + PG8_SA(b, h) + aoff + m * 2048 + k * 1024); } while (0)
; #define PG8_LDB(dst, b, h) do { _Pragma("unroll") for (int n = 0; n < 2; ++n) _Pragma("unroll") for (int k = 0; k < 2; ++k) dst[n][k] = *(const LAS bf16x8*)(lds + PG8_SB(b, h) + boff + n * 2048 + k * 1024); } while (0)
; #define PG8_MMA(ai, bj, At, Bt) do { __builtin_amdgcn_s_setprio(1); _Pragma("unroll") for (int m = 0; m < 4; ++m) _Pragma("unroll") for (int n = 0; n < 2; ++n) _Pragma("unroll") for (int k = 0; k < 2; ++k) \
;         acc[ai][bj][m][n] = __builtin_amdgcn_mfma_f32_16x16x32_bf16(Bt[n][k], At[m][k], acc[ai][bj][m][n], 0, 0, 0); __builtin_amdgcn_s_setprio(0); } while (0)
; #define PG8_WAIT_V(n) asm volatile("s_waitcnt vmcnt(" #n ")" ::: "memory")
; #define PG8_WAIT_L(n) asm volatile("s_waitcnt lgkmcnt(" #n ")" ::: "memory")
; #define PG8_BAR __builtin_amdgcn_s_barrier()
; #define PG8_SCHED __builtin_amdgcn_sched_barrier(0)
; template <class Epi, class Sched>
; __device__ __forceinline__ void gemm_phase(const int tid, LAS unsigned char* lds, const int lda, const int ldb, const int K, const Sched& S, const Epi& E) {
;     ...
;             PG8_WAIT_V(8); PG8_WAIT_L(0); PG8_BAR; if (!cur.half) { PG8_MMA(1, 0, At, B0); PG8_MMA(1, 1, At, B1); } PG8_BAR; PG8_SCHED;
;             PG8_LDB(B0, 1, 0); PG8_LDB(B1, 1, 1); PG8_SCHED; PG8_LDA(At, 1, 0); PG8_STAGE(PG8_SA(0, 1), a2 + hstepA, voffA);
;             PG8_WAIT_V(8); PG8_WAIT_L(0); PG8_BAR; PG8_MMA(0, 0, At, B0); PG8_MMA(0, 1, At, B1); PG8_BAR; PG8_SCHED;
	s_setprio 1
	s_waitcnt lgkmcnt(0)
	v_mfma_f32_16x16x32_bf16 v[60:63], v[156:159], v[210:213], 0
	v_mfma_f32_16x16x32_bf16 v[56:59], v[164:167], v[210:213], 0
	v_mfma_f32_16x16x32_bf16 v[44:47], v[156:159], v[218:221], 0
	v_mfma_f32_16x16x32_bf16 v[40:43], v[164:167], v[218:221], 0
	v_mfma_f32_16x16x32_bf16 v[28:31], v[156:159], v[226:229], 0
	v_mfma_f32_16x16x32_bf16 v[24:27], v[164:167], v[226:229], 0
	v_mfma_f32_16x16x32_bf16 v[12:15], v[156:159], v[234:237], 0
	v_mfma_f32_16x16x32_bf16 v[8:11], v[164:167], v[234:237], 0
	v_mfma_f32_16x16x32_bf16 v[60:63], v[160:163], v[214:217], v[60:63]
	v_mfma_f32_16x16x32_bf16 v[56:59], v[180:183], v[214:217], v[56:59]
	v_mfma_f32_16x16x32_bf16 v[44:47], v[160:163], v[222:225], v[44:47]
	v_mfma_f32_16x16x32_bf16 v[40:43], v[180:183], v[222:225], v[40:43]
	v_mfma_f32_16x16x32_bf16 v[28:31], v[160:163], v[230:233], v[28:31]
	v_mfma_f32_16x16x32_bf16 v[24:27], v[180:183], v[230:233], v[24:27]
	v_mfma_f32_16x16x32_bf16 v[12:15], v[160:163], v[238:241], v[12:15]
	v_mfma_f32_16x16x32_bf16 v[8:11], v[180:183], v[238:241], v[8:11]
	s_setprio 0
	s_setprio 1
	v_mfma_f32_16x16x32_bf16 v[52:55], v[184:187], v[210:213], 0
	v_mfma_f32_16x16x32_bf16 v[48:51], v[194:197], v[210:213], 0
	v_mfma_f32_16x16x32_bf16 v[36:39], v[184:187], v[218:221], 0
	v_mfma_f32_16x16x32_bf16 v[32:35], v[194:197], v[218:221], 0
	v_mfma_f32_16x16x32_bf16 v[20:23], v[184:187], v[226:229], 0
	v_mfma_f32_16x16x32_bf16 v[16:19], v[194:197], v[226:229], 0
	v_mfma_f32_16x16x32_bf16 v[4:7], v[184:187], v[234:237], 0
	v_mfma_f32_16x16x32_bf16 v[0:3], v[194:197], v[234:237], 0
	v_mfma_f32_16x16x32_bf16 v[52:55], v[190:193], v[214:217], v[52:55]
	v_mfma_f32_16x16x32_bf16 v[48:51], v[206:209], v[214:217], v[48:51]
	v_mfma_f32_16x16x32_bf16 v[36:39], v[190:193], v[222:225], v[36:39]
	v_mfma_f32_16x16x32_bf16 v[32:35], v[206:209], v[222:225], v[32:35]
	v_mfma_f32_16x16x32_bf16 v[20:23], v[190:193], v[230:233], v[20:23]
	v_mfma_f32_16x16x32_bf16 v[16:19], v[206:209], v[230:233], v[16:19]
	v_mfma_f32_16x16x32_bf16 v[4:7], v[190:193], v[238:241], v[4:7]
	v_mfma_f32_16x16x32_bf16 v[0:3], v[206:209], v[238:241], v[0:3]
	s_setprio 0
	s_barrier
	s_add_i32 s14, 0, 0x18000
	v_add_u32_e32 v155, s14, v146
	s_add_i32 s15, 0, 0x1c000
	ds_read_b128 v[156:159], v155
	ds_read_b128 v[160:163], v155 offset:1024
	ds_read_b128 v[164:167], v155 offset:2048
	ds_read_b128 v[180:183], v155 offset:3072
	v_add_u32_e32 v155, s15, v146
	ds_read_b128 v[184:187], v155
	ds_read_b128 v[190:193], v155 offset:1024
	ds_read_b128 v[194:197], v155 offset:2048
	ds_read_b128 v[206:209], v155 offset:3072
	s_add_u32 s54, s54, 0x40000
	s_addc_u32 s55, s55, 0
	s_mov_b32 m0, s59
	v_lshl_add_u64 v[250:251], s[54:55], 0, v[128:129]
	ds_read_b128 v[210:213], v154 offset:32768
	ds_read_b128 v[214:217], v154 offset:33792
	ds_read_b128 v[218:221], v154 offset:34816
	ds_read_b128 v[222:225], v154 offset:35840
	ds_read_b128 v[226:229], v154 offset:36864
	ds_read_b128 v[230:233], v154 offset:37888
	ds_read_b128 v[234:237], v154 offset:38912
	ds_read_b128 v[238:241], v154 offset:39936
	global_load_lds_dwordx4 v[250:251], off
	v_lshl_add_u64 v[250:251], s[54:55], 0, v[132:133]
	s_mov_b32 m0, s60
	s_nop 0
	global_load_lds_dwordx4 v[250:251], off
	s_waitcnt vmcnt(8)
	s_waitcnt lgkmcnt(0)
	s_barrier
	s_setprio 1
	s_waitcnt lgkmcnt(0)
	v_mfma_f32_16x16x32_bf16 v[124:127], v[156:159], v[210:213], v[124:127]
	v_mfma_f32_16x16x32_bf16 v[120:123], v[164:167], v[210:213], v[120:123]
	v_mfma_f32_16x16x32_bf16 v[108:111], v[156:159], v[218:221], v[108:111]
	v_mfma_f32_16x16x32_bf16 v[104:107], v[164:167], v[218:221], v[104:107]
	v_mfma_f32_16x16x32_bf16 v[92:95], v[156:159], v[226:229], v[92:95]
	v_mfma_f32_16x16x32_bf16 v[88:91], v[164:167], v[226:229], v[88:91]
	v_mfma_f32_16x16x32_bf16 v[76:79], v[156:159], v[234:237], v[76:79]
	v_mfma_f32_16x16x32_bf16 v[72:75], v[164:167], v[234:237], v[72:75]
	v_mfma_f32_16x16x32_bf16 v[124:127], v[160:163], v[214:217], v[124:127]
	v_mfma_f32_16x16x32_bf16 v[120:123], v[180:183], v[214:217], v[120:123]
	v_mfma_f32_16x16x32_bf16 v[108:111], v[160:163], v[222:225], v[108:111]
	v_mfma_f32_16x16x32_bf16 v[104:107], v[180:183], v[222:225], v[104:107]
	v_mfma_f32_16x16x32_bf16 v[92:95], v[160:163], v[230:233], v[92:95]
	v_mfma_f32_16x16x32_bf16 v[88:91], v[180:183], v[230:233], v[88:91]
	v_mfma_f32_16x16x32_bf16 v[76:79], v[160:163], v[238:241], v[76:79]
	v_mfma_f32_16x16x32_bf16 v[72:75], v[180:183], v[238:241], v[72:75]
	s_setprio 0
	s_setprio 1
	v_mfma_f32_16x16x32_bf16 v[116:119], v[184:187], v[210:213], v[116:119]
	v_mfma_f32_16x16x32_bf16 v[112:115], v[194:197], v[210:213], v[112:115]
	v_mfma_f32_16x16x32_bf16 v[100:103], v[184:187], v[218:221], v[100:103]
	v_mfma_f32_16x16x32_bf16 v[96:99], v[194:197], v[218:221], v[96:99]
	v_mfma_f32_16x16x32_bf16 v[84:87], v[184:187], v[226:229], v[84:87]
	v_mfma_f32_16x16x32_bf16 v[80:83], v[194:197], v[226:229], v[80:83]
	v_mfma_f32_16x16x32_bf16 v[68:71], v[184:187], v[234:237], v[68:71]
	v_mfma_f32_16x16x32_bf16 v[64:67], v[194:197], v[234:237], v[64:67]
	v_mfma_f32_16x16x32_bf16 v[116:119], v[190:193], v[214:217], v[116:119]
	v_mfma_f32_16x16x32_bf16 v[112:115], v[206:209], v[214:217], v[112:115]
	v_mfma_f32_16x16x32_bf16 v[100:103], v[190:193], v[222:225], v[100:103]
	v_mfma_f32_16x16x32_bf16 v[96:99], v[206:209], v[222:225], v[96:99]
	v_mfma_f32_16x16x32_bf16 v[84:87], v[190:193], v[230:233], v[84:87]
	v_mfma_f32_16x16x32_bf16 v[80:83], v[206:209], v[230:233], v[80:83]
	v_mfma_f32_16x16x32_bf16 v[68:71], v[190:193], v[238:241], v[68:71]
	v_mfma_f32_16x16x32_bf16 v[64:67], v[206:209], v[238:241], v[64:67]
	s_setprio 0
	s_barrier
; #define PG8_STAGE(bufoff, gbase, voff) do { _Pragma("unroll") for (int _i = 0; _i < 2; ++_i) \
;         __builtin_amdgcn_global_load_lds((const unsigned*)((const char*)(gbase) + (voff)[_i]), (LAS unsigned*)(lds + (bufoff) + ldsw + _i * 8192), 16, 0, 0); } while (0)
; #define PG8_LDA(dst, b, h) do { _Pragma("unroll") for (int m = 0; m < 4; ++m) _Pragma("unroll") for (int k = 0; k < 2; ++k) dst[m][k] = *(const LAS bf16x8*)(lds + PG8_SA(b, h) + aoff + m * 2048 + k * 1024); } while (0)
; #define PG8_MMA(ai, bj, At, Bt) do { __builtin_amdgcn_s_setprio(1); _Pragma("unroll") for (int m = 0; m < 4; ++m) _Pragma("unroll") for (int n = 0; n < 2; ++n) _Pragma("unroll") for (int k = 0; k < 2; ++k) \
;         acc[ai][bj][m][n] = __builtin_amdgcn_mfma_f32_16x16x32_bf16(Bt[n][k], At[m][k], acc[ai][bj][m][n], 0, 0, 0); __builtin_amdgcn_s_setprio(0); } while (0)
; #define PG8_WAIT_V(n) asm volatile("s_waitcnt vmcnt(" #n ")" ::: "memory")
; #define PG8_WAIT_L(n) asm volatile("s_waitcnt lgkmcnt(" #n ")" ::: "memory")
; #define PG8_BAR __builtin_amdgcn_s_barrier()
; #define PG8_SCHED __builtin_amdgcn_sched_barrier(0)
; template <class Epi, class Sched>
; __device__ __forceinline__ void gemm_phase(const int tid, LAS unsigned char* lds, const int lda, const int ldb, const int K, const Sched& S, const Epi& E) {
;     ...
;             PG8_LDA(At, 1, 1); PG8_STAGE(PG8_SB(1, 0), b3, voffB); PG8_STAGE(PG8_SB(1, 1), b3 + hstepB, voffB); PG8_STAGE(PG8_SA(1, 0), a3, voffA);
;             PG8_WAIT_V(8); PG8_WAIT_L(0); PG8_BAR; if (!cur.half) { PG8_MMA(1, 0, At, B0); PG8_MMA(1, 1, At, B1); } PG8_BAR; PG8_SCHED;
;         }
	s_add_i32 s14, s14, s56
	v_lshl_add_u64 v[242:243], v[242:243], 0, s[6:7]
	s_mov_b32 m0, s14
	ds_read_b128 v[210:213], v154 offset:49152
	ds_read_b128 v[214:217], v154 offset:50176
	ds_read_b128 v[218:221], v154 offset:51200
	ds_read_b128 v[222:225], v154 offset:52224
	ds_read_b128 v[226:229], v154 offset:53248
	ds_read_b128 v[230:233], v154 offset:54272
	ds_read_b128 v[234:237], v154 offset:55296
	ds_read_b128 v[238:241], v154 offset:56320
	global_load_lds_dwordx4 v[242:243], off
	s_add_i32 m0, s14, 0x2000
	s_add_u32 s52, s52, 0x40080
	v_lshl_add_u64 v[242:243], v[244:245], 0, s[6:7]
	s_addc_u32 s53, s53, 0
	s_add_i32 s14, s15, s56
	global_load_lds_dwordx4 v[242:243], off
	v_lshl_add_u64 v[242:243], s[52:53], 0, v[130:131]
	s_mov_b32 m0, s14
	s_nop 0
	global_load_lds_dwordx4 v[242:243], off
	v_lshl_add_u64 v[242:243], s[52:53], 0, v[134:135]
	s_add_i32 m0, s14, 0x2000
	s_nop 0
	global_load_lds_dwordx4 v[242:243], off
	v_lshl_add_u64 v[242:243], v[246:247], 0, s[6:7]
	s_mov_b32 m0, s61
	s_nop 0
	global_load_lds_dwordx4 v[242:243], off
	v_lshl_add_u64 v[242:243], v[248:249], 0, s[6:7]
	s_mov_b32 m0, s62
	s_nop 0
	global_load_lds_dwordx4 v[242:243], off
	s_waitcnt vmcnt(8)
	s_waitcnt lgkmcnt(0)
	s_barrier
	s_setprio 1
	s_waitcnt lgkmcnt(0)
	v_mfma_f32_16x16x32_bf16 v[60:63], v[156:159], v[210:213], v[60:63]
	v_mfma_f32_16x16x32_bf16 v[56:59], v[164:167], v[210:213], v[56:59]
	v_mfma_f32_16x16x32_bf16 v[44:47], v[156:159], v[218:221], v[44:47]
	v_mfma_f32_16x16x32_bf16 v[40:43], v[164:167], v[218:221], v[40:43]
	v_mfma_f32_16x16x32_bf16 v[28:31], v[156:159], v[226:229], v[28:31]
	v_mfma_f32_16x16x32_bf16 v[24:27], v[164:167], v[226:229], v[24:27]
	v_mfma_f32_16x16x32_bf16 v[12:15], v[156:159], v[234:237], v[12:15]
	v_mfma_f32_16x16x32_bf16 v[8:11], v[164:167], v[234:237], v[8:11]
	v_mfma_f32_16x16x32_bf16 v[60:63], v[160:163], v[214:217], v[60:63]
	v_mfma_f32_16x16x32_bf16 v[56:59], v[180:183], v[214:217], v[56:59]
	v_mfma_f32_16x16x32_bf16 v[44:47], v[160:163], v[222:225], v[44:47]
	v_mfma_f32_16x16x32_bf16 v[40:43], v[180:183], v[222:225], v[40:43]
	v_mfma_f32_16x16x32_bf16 v[28:31], v[160:163], v[230:233], v[28:31]
	v_mfma_f32_16x16x32_bf16 v[24:27], v[180:183], v[230:233], v[24:27]
	v_mfma_f32_16x16x32_bf16 v[12:15], v[160:163], v[238:241], v[12:15]
	v_mfma_f32_16x16x32_bf16 v[8:11], v[180:183], v[238:241], v[8:11]
	s_setprio 0
	s_setprio 1
	v_mfma_f32_16x16x32_bf16 v[52:55], v[184:187], v[210:213], v[52:55]
	v_mfma_f32_16x16x32_bf16 v[48:51], v[194:197], v[210:213], v[48:51]
	v_mfma_f32_16x16x32_bf16 v[36:39], v[184:187], v[218:221], v[36:39]
	v_mfma_f32_16x16x32_bf16 v[32:35], v[194:197], v[218:221], v[32:35]
	v_mfma_f32_16x16x32_bf16 v[20:23], v[184:187], v[226:229], v[20:23]
	v_mfma_f32_16x16x32_bf16 v[16:19], v[194:197], v[226:229], v[16:19]
	v_mfma_f32_16x16x32_bf16 v[4:7], v[184:187], v[234:237], v[4:7]
	v_mfma_f32_16x16x32_bf16 v[0:3], v[194:197], v[234:237], v[0:3]
	v_mfma_f32_16x16x32_bf16 v[52:55], v[190:193], v[214:217], v[52:55]
	v_mfma_f32_16x16x32_bf16 v[48:51], v[206:209], v[214:217], v[48:51]
	v_mfma_f32_16x16x32_bf16 v[36:39], v[190:193], v[222:225], v[36:39]
	v_mfma_f32_16x16x32_bf16 v[32:35], v[206:209], v[222:225], v[32:35]
	v_mfma_f32_16x16x32_bf16 v[20:23], v[190:193], v[230:233], v[20:23]
	v_mfma_f32_16x16x32_bf16 v[16:19], v[206:209], v[230:233], v[16:19]
	v_mfma_f32_16x16x32_bf16 v[4:7], v[190:193], v[238:241], v[4:7]
	v_mfma_f32_16x16x32_bf16 v[0:3], v[206:209], v[238:241], v[0:3]
	s_setprio 0
	s_barrier
	s_add_u32 s38, s38, 0x100
	s_addc_u32 s39, s39, 0
	s_add_u32 s47, s47, 0x100
	s_addc_u32 s67, s67, 0
	s_cmp_ge_i32 s68, s4
	s_mov_b32 s52, s68
	s_cbranch_scc1 .Lkexit_197

; #define PG8_BAR __builtin_amdgcn_s_barrier()
; template <class Epi, class Sched>
; __device__ __forceinline__ void gemm_phase(const int tid, LAS unsigned char* lds, const int lda, const int ldb, const int K, const Sched& S, const Epi& E) {
;     ...
;         if (wr == 0) PG8_BAR;
;         if (MK_EPI2 && Epi::IDEM) E(acc, cur, wr, wc, fr, fq, es0, es1);
;         E(acc, cur, wr, wc, fr, fq, es0, es1);
.Lkexit_197:
	s_load_dword s70, s[0:1], 0x108
	v_readlane_b32 s68, v255, 13
	v_readlane_b32 s69, v255, 14
	s_movk_i32 s71, 0x1600
	s_mov_b32 s67, 0x18000
	s_and_b64 vcc, exec, s[44:45]
	s_cbranch_vccz .LBB0_200

; #define PG8_STAGE(bufoff, gbase, voff) do { _Pragma("unroll") for (int _i = 0; _i < 2; ++_i) \
;         __builtin_amdgcn_global_load_lds((const unsigned*)((const char*)(gbase) + (voff)[_i]), (LAS unsigned*)(lds + (bufoff) + ldsw + _i * 8192), 16, 0, 0); } while (0)
; #define PG8_LDA(dst, b, h) do { _Pragma("unroll") for (int m = 0; m < 4; ++m) _Pragma("unroll") for (int k = 0; k < 2; ++k) dst[m][k] = *(const LAS bf16x8*)(lds + PG8_SA(b, h) + aoff + m * 2048 + k * 1024); } while (0)
; #define PG8_LDB(dst, b, h) do { _Pragma("unroll") for (int n = 0; n < 2; ++n) _Pragma("unroll") for (int k = 0; k < 2; ++k) dst[n][k] = *(const LAS bf16x8*)(lds + PG8_SB(b, h) + boff + n * 2048 + k * 1024); } while (0)
; #define PG8_MMA(ai, bj, At, Bt) do { __builtin_amdgcn_s_setprio(1); _Pragma("unroll") for (int m = 0; m < 4; ++m) _Pragma("unroll") for (int n = 0; n < 2; ++n) _Pragma("unroll") for (int k = 0; k < 2; ++k) \
;         acc[ai][bj][m][n] = __builtin_amdgcn_mfma_f32_16x16x32_bf16(Bt[n][k], At[m][k], acc[ai][bj][m][n], 0, 0, 0); __builtin_amdgcn_s_setprio(0); } while (0)
; #define PG8_WAIT_V(n) asm volatile("s_waitcnt vmcnt(" #n ")" ::: "memory")
; #define PG8_WAIT_L(n) asm volatile("s_waitcnt lgkmcnt(" #n ")" ::: "memory")
; #define PG8_BAR __builtin_amdgcn_s_barrier()
; template <class Epi, class Sched>
; __device__ __forceinline__ void gemm_phase(const int tid, LAS unsigned char* lds, const int lda, const int ldb, const int K, const Sched& S, const Epi& E) {
;     ...
;         for (int t = 0; t < nt; t += 2) {
;             const bool last = (t == nt - 2);
;             const char* a1 = cA + (size_t)(t + 1) * kstep;
;             const char* a2 = last ? nA : cA + (size_t)(t + 2) * kstep; const char* b2 = last ? nB : cB + (size_t)(t + 2) * kstep;
;             const char* a3 = a2 + kstep; const char* b3 = b2 + kstep;
;             PG8_LDB(B0, 0, 0); PG8_LDB(B1, 0, 1); PG8_SCHED; PG8_LDA(At, 0, 0); PG8_STAGE(PG8_SA(1, 1), a1 + hstepA, voffA);
;             PG8_WAIT_V(8); PG8_WAIT_L(0); PG8_BAR; PG8_MMA(0, 0, At, B0); PG8_MMA(0, 1, At, B1); PG8_BAR; PG8_SCHED;
;             PG8_LDA(At, 0, 1); PG8_STAGE(PG8_SB(0, 0), b2, voffB); PG8_STAGE(PG8_SB(0, 1), b2 + hstepB, voffB); PG8_STAGE(PG8_SA(0, 0), a2, voffA);
;             PG8_WAIT_V(8); PG8_WAIT_L(0); PG8_BAR; if (!cur.half) { PG8_MMA(1, 0, At, B0); PG8_MMA(1, 1, At, B1); } PG8_BAR; PG8_SCHED;
.LBB0_213:
	s_andn2_b64 vcc, exec, s[40:41]
	s_cbranch_vccnz .LBB0_221
	s_add_u32 s54, s54, 0x40080
	s_addc_u32 s55, s55, 0
	s_add_u32 s23, s56, 0x100
	v_mov_b64_e32 v[204:205], 0xff
	v_mov_b64_e32 v[174:175], 0x100
	v_mov_b64_e32 v[172:173], 0x1ff
	v_mov_b64_e32 v[178:179], 0x200
	s_addc_u32 s27, s57, 0
	s_mov_b32 s45, 0
	s_add_i32 s69, s45, 2
	s_add_u32 s14, s54, 0xfffc0080
	s_addc_u32 s15, s55, -1
	s_add_i32 s24, 0, 0x10000
	s_cmp_eq_u32 s68, s45
	s_cselect_b32 s59, s53, s15
	s_cselect_b32 s58, s52, s14
	v_add_u32_e32 v176, s24, v151
	s_cselect_b32 s57, s3, s27
	s_cselect_b32 s56, s2, s23
	s_add_i32 s14, 0, 0x14000
	ds_read_b128 v[140:143], v176
	ds_read_b128 v[144:147], v176 offset:1024
	ds_read_b128 v[180:183], v176 offset:2048
	ds_read_b128 v[184:187], v176 offset:3072
	v_add_u32_e32 v176, s14, v151
	ds_read_b128 v[190:193], v176
	ds_read_b128 v[194:197], v176 offset:1024
	ds_read_b128 v[206:209], v176 offset:2048
	ds_read_b128 v[210:213], v176 offset:3072
	v_lshl_add_u64 v[246:247], s[54:55], 0, v[136:137]
	s_add_i32 m0, s51, 0xc000
	ds_read_b128 v[214:217], v166
	ds_read_b128 v[218:221], v166 offset:1024
	ds_read_b128 v[222:225], v166 offset:2048
	ds_read_b128 v[226:229], v166 offset:3072
	ds_read_b128 v[230:233], v166 offset:4096
	ds_read_b128 v[234:237], v166 offset:5120
	ds_read_b128 v[238:241], v166 offset:6144
	ds_read_b128 v[242:245], v166 offset:7168
	global_load_lds_dwordx4 v[246:247], off
	v_lshl_add_u64 v[246:247], s[54:55], 0, v[138:139]
	s_add_i32 m0, s51, 0xe000
	s_nop 0
	global_load_lds_dwordx4 v[246:247], off
	s_waitcnt vmcnt(8)
	s_waitcnt lgkmcnt(0)
	s_barrier
	s_setprio 1
	s_waitcnt lgkmcnt(0)
	v_mfma_f32_16x16x32_bf16 v[124:127], v[140:143], v[214:217], 0
	v_mfma_f32_16x16x32_bf16 v[120:123], v[180:183], v[214:217], 0
	v_mfma_f32_16x16x32_bf16 v[116:119], v[140:143], v[222:225], 0
	v_mfma_f32_16x16x32_bf16 v[112:115], v[180:183], v[222:225], 0
	v_mfma_f32_16x16x32_bf16 v[108:111], v[140:143], v[230:233], 0
	v_mfma_f32_16x16x32_bf16 v[104:107], v[180:183], v[230:233], 0
	v_mfma_f32_16x16x32_bf16 v[100:103], v[140:143], v[238:241], 0
	v_mfma_f32_16x16x32_bf16 v[96:99], v[180:183], v[238:241], 0
	v_mfma_f32_16x16x32_bf16 v[124:127], v[144:147], v[218:221], v[124:127]
	v_mfma_f32_16x16x32_bf16 v[120:123], v[184:187], v[218:221], v[120:123]
	v_mfma_f32_16x16x32_bf16 v[116:119], v[144:147], v[226:229], v[116:119]
	v_mfma_f32_16x16x32_bf16 v[112:115], v[184:187], v[226:229], v[112:115]
	v_mfma_f32_16x16x32_bf16 v[108:111], v[144:147], v[234:237], v[108:111]
	v_mfma_f32_16x16x32_bf16 v[104:107], v[184:187], v[234:237], v[104:107]
	v_mfma_f32_16x16x32_bf16 v[100:103], v[144:147], v[242:245], v[100:103]
	v_mfma_f32_16x16x32_bf16 v[96:99], v[184:187], v[242:245], v[96:99]
	s_setprio 0
	s_setprio 1
	v_mfma_f32_16x16x32_bf16 v[60:63], v[190:193], v[214:217], 0
	v_mfma_f32_16x16x32_bf16 v[56:59], v[206:209], v[214:217], 0
	v_mfma_f32_16x16x32_bf16 v[52:55], v[190:193], v[222:225], 0
	v_mfma_f32_16x16x32_bf16 v[48:51], v[206:209], v[222:225], 0
	v_mfma_f32_16x16x32_bf16 v[44:47], v[190:193], v[230:233], 0
	v_mfma_f32_16x16x32_bf16 v[40:43], v[206:209], v[230:233], 0
	v_mfma_f32_16x16x32_bf16 v[36:39], v[190:193], v[238:241], 0
	v_mfma_f32_16x16x32_bf16 v[32:35], v[206:209], v[238:241], 0
	v_mfma_f32_16x16x32_bf16 v[60:63], v[194:197], v[218:221], v[60:63]
	v_mfma_f32_16x16x32_bf16 v[56:59], v[210:213], v[218:221], v[56:59]
	v_mfma_f32_16x16x32_bf16 v[52:55], v[194:197], v[226:229], v[52:55]
	v_mfma_f32_16x16x32_bf16 v[48:51], v[210:213], v[226:229], v[48:51]
	v_mfma_f32_16x16x32_bf16 v[44:47], v[194:197], v[234:237], v[44:47]
	v_mfma_f32_16x16x32_bf16 v[40:43], v[210:213], v[234:237], v[40:43]
	v_mfma_f32_16x16x32_bf16 v[36:39], v[194:197], v[242:245], v[36:39]
	v_mfma_f32_16x16x32_bf16 v[32:35], v[210:213], v[242:245], v[32:35]
	s_setprio 0
	s_barrier
	s_add_i32 s15, s24, s60
	v_lshl_add_u64 v[246:247], s[56:57], 0, v[132:133]
	s_mov_b32 m0, s15
	ds_read_b128 v[214:217], v166 offset:16384
	ds_read_b128 v[218:221], v166 offset:17408
	ds_read_b128 v[222:225], v166 offset:18432
	ds_read_b128 v[226:229], v166 offset:19456
	ds_read_b128 v[230:233], v166 offset:20480
	ds_read_b128 v[234:237], v166 offset:21504
	ds_read_b128 v[238:241], v166 offset:22528
	ds_read_b128 v[242:245], v166 offset:23552
	global_load_lds_dwordx4 v[246:247], off
	s_add_i32 m0, s15, 0x2000
	s_add_u32 s70, s56, 0x40000
	v_lshl_add_u64 v[248:249], s[56:57], 0, v[128:129]
	s_addc_u32 s71, s57, 0
	s_add_i32 s14, s14, s60
	global_load_lds_dwordx4 v[248:249], off
	v_lshl_add_u64 v[250:251], s[70:71], 0, v[132:133]
	s_mov_b32 m0, s14
	v_lshl_add_u64 v[252:253], s[58:59], 0, v[130:131]
	global_load_lds_dwordx4 v[250:251], off
	v_lshl_add_u64 v[250:251], s[70:71], 0, v[128:129]
	s_add_i32 m0, s14, 0x2000
	s_nop 0
	global_load_lds_dwordx4 v[250:251], off
	v_lshl_add_u64 v[250:251], s[58:59], 0, v[134:135]
	s_mov_b32 m0, s51
	s_nop 0
	global_load_lds_dwordx4 v[250:251], off
	s_mov_b32 m0, s62
	s_nop 0
	global_load_lds_dwordx4 v[252:253], off
	s_waitcnt vmcnt(8)
	s_waitcnt lgkmcnt(0)
	s_barrier
; #define PG8_STAGE(bufoff, gbase, voff) do { _Pragma("unroll") for (int _i = 0; _i < 2; ++_i) \
;         __builtin_amdgcn_global_load_lds((const unsigned*)((const char*)(gbase) + (voff)[_i]), (LAS unsigned*)(lds + (bufoff) + ldsw + _i * 8192), 16, 0, 0); } while (0)
; #define PG8_LDA(dst, b, h) do { _Pragma("unroll") for (int m = 0; m < 4; ++m) _Pragma("unroll") for (int k = 0; k < 2; ++k) dst[m][k] = *(const LAS bf16x8*)(lds + PG8_SA(b, h) + aoff + m * 2048 + k * 1024); } while (0)
; #define PG8_LDB(dst, b, h) do { _Pragma("unroll") for (int n = 0; n < 2; ++n) _Pragma("unroll") for (int k = 0; k < 2; ++k) dst[n][k] = *(const LAS bf16x8*)(lds + PG8_SB(b, h) + boff + n * 2048 + k * 1024); } while (0)
; #define PG8_MMA(ai, bj, At, Bt) do { __builtin_amdgcn_s_setprio(1); _Pragma("unroll") for (int m = 0; m < 4; ++m) _Pragma("unroll") for (int n = 0; n < 2; ++n) _Pragma("unroll") for (int k = 0; k < 2; ++k) \
;         acc[ai][bj][m][n] = __builtin_amdgcn_mfma_f32_16x16x32_bf16(Bt[n][k], At[m][k], acc[ai][bj][m][n], 0, 0, 0); __builtin_amdgcn_s_setprio(0); } while (0)
; #define PG8_WAIT_V(n) asm volatile("s_waitcnt vmcnt(" #n ")" ::: "memory")
; #define PG8_WAIT_L(n) asm volatile("s_waitcnt lgkmcnt(" #n ")" ::: "memory")
; #define PG8_BAR __builtin_amdgcn_s_barrier()
; #define PG8_SCHED __builtin_amdgcn_sched_barrier(0)
; template <class Epi, class Sched>
; __device__ __forceinline__ void gemm_phase(const int tid, LAS unsigned char* lds, const int lda, const int ldb, const int K, const Sched& S, const Epi& E) {
;     ...
;             PG8_WAIT_V(8); PG8_WAIT_L(0); PG8_BAR; if (!cur.half) { PG8_MMA(1, 0, At, B0); PG8_MMA(1, 1, At, B1); } PG8_BAR; PG8_SCHED;
;             PG8_LDB(B0, 1, 0); PG8_LDB(B1, 1, 1); PG8_SCHED; PG8_LDA(At, 1, 0); PG8_STAGE(PG8_SA(0, 1), a2 + hstepA, voffA);
;             PG8_WAIT_V(8); PG8_WAIT_L(0); PG8_BAR; PG8_MMA(0, 0, At, B0); PG8_MMA(0, 1, At, B1); PG8_BAR; PG8_SCHED;
	s_setprio 1
	s_waitcnt lgkmcnt(0)
	v_mfma_f32_16x16x32_bf16 v[92:95], v[140:143], v[214:217], 0
	v_mfma_f32_16x16x32_bf16 v[88:91], v[180:183], v[214:217], 0
	v_mfma_f32_16x16x32_bf16 v[84:87], v[140:143], v[222:225], 0
	v_mfma_f32_16x16x32_bf16 v[80:83], v[180:183], v[222:225], 0
	v_mfma_f32_16x16x32_bf16 v[76:79], v[140:143], v[230:233], 0
	v_mfma_f32_16x16x32_bf16 v[72:75], v[180:183], v[230:233], 0
	v_mfma_f32_16x16x32_bf16 v[68:71], v[140:143], v[238:241], 0
	v_mfma_f32_16x16x32_bf16 v[64:67], v[180:183], v[238:241], 0
	v_mfma_f32_16x16x32_bf16 v[92:95], v[144:147], v[218:221], v[92:95]
	v_mfma_f32_16x16x32_bf16 v[88:91], v[184:187], v[218:221], v[88:91]
	v_mfma_f32_16x16x32_bf16 v[84:87], v[144:147], v[226:229], v[84:87]
	v_mfma_f32_16x16x32_bf16 v[80:83], v[184:187], v[226:229], v[80:83]
	v_mfma_f32_16x16x32_bf16 v[76:79], v[144:147], v[234:237], v[76:79]
	v_mfma_f32_16x16x32_bf16 v[72:75], v[184:187], v[234:237], v[72:75]
	v_mfma_f32_16x16x32_bf16 v[68:71], v[144:147], v[242:245], v[68:71]
	v_mfma_f32_16x16x32_bf16 v[64:67], v[184:187], v[242:245], v[64:67]
	s_setprio 0
	s_setprio 1
	v_mfma_f32_16x16x32_bf16 v[28:31], v[190:193], v[214:217], 0
	v_mfma_f32_16x16x32_bf16 v[24:27], v[206:209], v[214:217], 0
	v_mfma_f32_16x16x32_bf16 v[20:23], v[190:193], v[222:225], 0
	v_mfma_f32_16x16x32_bf16 v[16:19], v[206:209], v[222:225], 0
	v_mfma_f32_16x16x32_bf16 v[12:15], v[190:193], v[230:233], 0
	v_mfma_f32_16x16x32_bf16 v[8:11], v[206:209], v[230:233], 0
	v_mfma_f32_16x16x32_bf16 v[4:7], v[190:193], v[238:241], 0
	v_mfma_f32_16x16x32_bf16 v[0:3], v[206:209], v[238:241], 0
	v_mfma_f32_16x16x32_bf16 v[28:31], v[194:197], v[218:221], v[28:31]
	v_mfma_f32_16x16x32_bf16 v[24:27], v[210:213], v[218:221], v[24:27]
	v_mfma_f32_16x16x32_bf16 v[20:23], v[194:197], v[226:229], v[20:23]
	v_mfma_f32_16x16x32_bf16 v[16:19], v[210:213], v[226:229], v[16:19]
	v_mfma_f32_16x16x32_bf16 v[12:15], v[194:197], v[234:237], v[12:15]
	v_mfma_f32_16x16x32_bf16 v[8:11], v[210:213], v[234:237], v[8:11]
	v_mfma_f32_16x16x32_bf16 v[4:7], v[194:197], v[242:245], v[4:7]
	v_mfma_f32_16x16x32_bf16 v[0:3], v[210:213], v[242:245], v[0:3]
	s_setprio 0
	s_barrier
	s_add_i32 s14, 0, 0x18000
	v_add_u32_e32 v176, s14, v151
	s_add_i32 s15, 0, 0x1c000
	ds_read_b128 v[140:143], v176
	ds_read_b128 v[144:147], v176 offset:1024
	ds_read_b128 v[180:183], v176 offset:2048
	ds_read_b128 v[184:187], v176 offset:3072
	v_add_u32_e32 v176, s15, v151
	ds_read_b128 v[190:193], v176
	ds_read_b128 v[194:197], v176 offset:1024
	ds_read_b128 v[206:209], v176 offset:2048
	ds_read_b128 v[210:213], v176 offset:3072
	s_add_u32 s58, s58, 0x40000
	s_addc_u32 s59, s59, 0
	s_mov_b32 m0, s63
	v_lshl_add_u64 v[176:177], s[58:59], 0, v[134:135]
	ds_read_b128 v[214:217], v166 offset:32768
	ds_read_b128 v[218:221], v166 offset:33792
	ds_read_b128 v[222:225], v166 offset:34816
	ds_read_b128 v[226:229], v166 offset:35840
	ds_read_b128 v[230:233], v166 offset:36864
	ds_read_b128 v[234:237], v166 offset:37888
	ds_read_b128 v[238:241], v166 offset:38912
	ds_read_b128 v[242:245], v166 offset:39936
	global_load_lds_dwordx4 v[176:177], off
	v_lshl_add_u64 v[176:177], s[58:59], 0, v[130:131]
	s_mov_b32 m0, s64
	s_nop 0
	global_load_lds_dwordx4 v[176:177], off
	s_waitcnt vmcnt(8)
	s_waitcnt lgkmcnt(0)
	s_barrier
	s_setprio 1
	s_waitcnt lgkmcnt(0)
	v_mfma_f32_16x16x32_bf16 v[124:127], v[140:143], v[214:217], v[124:127]
	v_mfma_f32_16x16x32_bf16 v[120:123], v[180:183], v[214:217], v[120:123]
	v_mfma_f32_16x16x32_bf16 v[116:119], v[140:143], v[222:225], v[116:119]
	v_mfma_f32_16x16x32_bf16 v[112:115], v[180:183], v[222:225], v[112:115]
	v_mfma_f32_16x16x32_bf16 v[108:111], v[140:143], v[230:233], v[108:111]
	v_mfma_f32_16x16x32_bf16 v[104:107], v[180:183], v[230:233], v[104:107]
	v_mfma_f32_16x16x32_bf16 v[100:103], v[140:143], v[238:241], v[100:103]
	v_mfma_f32_16x16x32_bf16 v[96:99], v[180:183], v[238:241], v[96:99]
	v_mfma_f32_16x16x32_bf16 v[124:127], v[144:147], v[218:221], v[124:127]
	v_mfma_f32_16x16x32_bf16 v[120:123], v[184:187], v[218:221], v[120:123]
	v_mfma_f32_16x16x32_bf16 v[116:119], v[144:147], v[226:229], v[116:119]
	v_mfma_f32_16x16x32_bf16 v[112:115], v[184:187], v[226:229], v[112:115]
	v_mfma_f32_16x16x32_bf16 v[108:111], v[144:147], v[234:237], v[108:111]
	v_mfma_f32_16x16x32_bf16 v[104:107], v[184:187], v[234:237], v[104:107]
	v_mfma_f32_16x16x32_bf16 v[100:103], v[144:147], v[242:245], v[100:103]
	v_mfma_f32_16x16x32_bf16 v[96:99], v[184:187], v[242:245], v[96:99]
	s_setprio 0
	s_setprio 1
	v_mfma_f32_16x16x32_bf16 v[60:63], v[190:193], v[214:217], v[60:63]
	v_mfma_f32_16x16x32_bf16 v[56:59], v[206:209], v[214:217], v[56:59]
	v_mfma_f32_16x16x32_bf16 v[52:55], v[190:193], v[222:225], v[52:55]
	v_mfma_f32_16x16x32_bf16 v[48:51], v[206:209], v[222:225], v[48:51]
	v_mfma_f32_16x16x32_bf16 v[44:47], v[190:193], v[230:233], v[44:47]
	v_mfma_f32_16x16x32_bf16 v[40:43], v[206:209], v[230:233], v[40:43]
	v_mfma_f32_16x16x32_bf16 v[36:39], v[190:193], v[238:241], v[36:39]
	v_mfma_f32_16x16x32_bf16 v[32:35], v[206:209], v[238:241], v[32:35]
	v_mfma_f32_16x16x32_bf16 v[60:63], v[194:197], v[218:221], v[60:63]
	v_mfma_f32_16x16x32_bf16 v[56:59], v[210:213], v[218:221], v[56:59]
	v_mfma_f32_16x16x32_bf16 v[52:55], v[194:197], v[226:229], v[52:55]
	v_mfma_f32_16x16x32_bf16 v[48:51], v[210:213], v[226:229], v[48:51]
	v_mfma_f32_16x16x32_bf16 v[44:47], v[194:197], v[234:237], v[44:47]
	v_mfma_f32_16x16x32_bf16 v[40:43], v[210:213], v[234:237], v[40:43]
	v_mfma_f32_16x16x32_bf16 v[36:39], v[194:197], v[242:245], v[36:39]
	v_mfma_f32_16x16x32_bf16 v[32:35], v[210:213], v[242:245], v[32:35]
	s_setprio 0
	s_barrier
; #define PG8_STAGE(bufoff, gbase, voff) do { _Pragma("unroll") for (int _i = 0; _i < 2; ++_i) \
;         __builtin_amdgcn_global_load_lds((const unsigned*)((const char*)(gbase) + (voff)[_i]), (LAS unsigned*)(lds + (bufoff) + ldsw + _i * 8192), 16, 0, 0); } while (0)
; #define PG8_LDA(dst, b, h) do { _Pragma("unroll") for (int m = 0; m < 4; ++m) _Pragma("unroll") for (int k = 0; k < 2; ++k) dst[m][k] = *(const LAS bf16x8*)(lds + PG8_SA(b, h) + aoff + m * 2048 + k * 1024); } while (0)
; #define PG8_MMA(ai, bj, At, Bt) do { __builtin_amdgcn_s_setprio(1); _Pragma("unroll") for (int m = 0; m < 4; ++m) _Pragma("unroll") for (int n = 0; n < 2; ++n) _Pragma("unroll") for (int k = 0; k < 2; ++k) \
;         acc[ai][bj][m][n] = __builtin_amdgcn_mfma_f32_16x16x32_bf16(Bt[n][k], At[m][k], acc[ai][bj][m][n], 0, 0, 0); __builtin_amdgcn_s_setprio(0); } while (0)
; #define PG8_WAIT_V(n) asm volatile("s_waitcnt vmcnt(" #n ")" ::: "memory")
; #define PG8_WAIT_L(n) asm volatile("s_waitcnt lgkmcnt(" #n ")" ::: "memory")
; #define PG8_BAR __builtin_amdgcn_s_barrier()
; #define PG8_SCHED __builtin_amdgcn_sched_barrier(0)
; template <class Epi, class Sched>
; __device__ __forceinline__ void gemm_phase(const int tid, LAS unsigned char* lds, const int lda, const int ldb, const int K, const Sched& S, const Epi& E) {
;     ...
;             PG8_LDA(At, 1, 1); PG8_STAGE(PG8_SB(1, 0), b3, voffB); PG8_STAGE(PG8_SB(1, 1), b3 + hstepB, voffB); PG8_STAGE(PG8_SA(1, 0), a3, voffA);
;             PG8_WAIT_V(8); PG8_WAIT_L(0); PG8_BAR; if (!cur.half) { PG8_MMA(1, 0, At, B0); PG8_MMA(1, 1, At, B1); } PG8_BAR; PG8_SCHED;
;         }
	s_add_i32 s14, s14, s60
	v_lshl_add_u64 v[176:177], v[246:247], 0, s[6:7]
	s_mov_b32 m0, s14
	ds_read_b128 v[214:217], v166 offset:49152
	ds_read_b128 v[218:221], v166 offset:50176
	ds_read_b128 v[222:225], v166 offset:51200
	ds_read_b128 v[226:229], v166 offset:52224
	ds_read_b128 v[230:233], v166 offset:53248
	ds_read_b128 v[234:237], v166 offset:54272
	ds_read_b128 v[238:241], v166 offset:55296
	ds_read_b128 v[242:245], v166 offset:56320
	global_load_lds_dwordx4 v[176:177], off
	s_add_i32 m0, s14, 0x2000
	s_add_u32 s56, s56, 0x40080
	v_lshl_add_u64 v[176:177], v[248:249], 0, s[6:7]
	s_addc_u32 s57, s57, 0
	s_add_i32 s14, s15, s60
	global_load_lds_dwordx4 v[176:177], off
	v_lshl_add_u64 v[176:177], s[56:57], 0, v[132:133]
	s_mov_b32 m0, s14
	s_nop 0
	global_load_lds_dwordx4 v[176:177], off
	v_lshl_add_u64 v[176:177], s[56:57], 0, v[128:129]
	s_add_i32 m0, s14, 0x2000
	s_nop 0
	global_load_lds_dwordx4 v[176:177], off
	v_lshl_add_u64 v[176:177], v[250:251], 0, s[6:7]
	s_mov_b32 m0, s65
	s_nop 0
	global_load_lds_dwordx4 v[176:177], off
	v_lshl_add_u64 v[176:177], v[252:253], 0, s[6:7]
	s_mov_b32 m0, s66
	s_nop 0
	global_load_lds_dwordx4 v[176:177], off
	s_waitcnt vmcnt(8)
	s_waitcnt lgkmcnt(0)
	s_barrier
	s_setprio 1
	s_waitcnt lgkmcnt(0)
	v_mfma_f32_16x16x32_bf16 v[92:95], v[140:143], v[214:217], v[92:95]
	v_mfma_f32_16x16x32_bf16 v[88:91], v[180:183], v[214:217], v[88:91]
	v_mfma_f32_16x16x32_bf16 v[84:87], v[140:143], v[222:225], v[84:87]
	v_mfma_f32_16x16x32_bf16 v[80:83], v[180:183], v[222:225], v[80:83]
	v_mfma_f32_16x16x32_bf16 v[76:79], v[140:143], v[230:233], v[76:79]
	v_mfma_f32_16x16x32_bf16 v[72:75], v[180:183], v[230:233], v[72:75]
	v_mfma_f32_16x16x32_bf16 v[68:71], v[140:143], v[238:241], v[68:71]
	v_mfma_f32_16x16x32_bf16 v[64:67], v[180:183], v[238:241], v[64:67]
	v_mfma_f32_16x16x32_bf16 v[92:95], v[144:147], v[218:221], v[92:95]
	v_mfma_f32_16x16x32_bf16 v[88:91], v[184:187], v[218:221], v[88:91]
	v_mfma_f32_16x16x32_bf16 v[84:87], v[144:147], v[226:229], v[84:87]
	v_mfma_f32_16x16x32_bf16 v[80:83], v[184:187], v[226:229], v[80:83]
	v_mfma_f32_16x16x32_bf16 v[76:79], v[144:147], v[234:237], v[76:79]
	v_mfma_f32_16x16x32_bf16 v[72:75], v[184:187], v[234:237], v[72:75]
	v_mfma_f32_16x16x32_bf16 v[68:71], v[144:147], v[242:245], v[68:71]
	v_mfma_f32_16x16x32_bf16 v[64:67], v[184:187], v[242:245], v[64:67]
	s_setprio 0
	s_setprio 1
	v_mfma_f32_16x16x32_bf16 v[28:31], v[190:193], v[214:217], v[28:31]
	v_mfma_f32_16x16x32_bf16 v[24:27], v[206:209], v[214:217], v[24:27]
	v_mfma_f32_16x16x32_bf16 v[20:23], v[190:193], v[222:225], v[20:23]
	v_mfma_f32_16x16x32_bf16 v[16:19], v[206:209], v[222:225], v[16:19]
	v_mfma_f32_16x16x32_bf16 v[12:15], v[190:193], v[230:233], v[12:15]
	v_mfma_f32_16x16x32_bf16 v[8:11], v[206:209], v[230:233], v[8:11]
	v_mfma_f32_16x16x32_bf16 v[4:7], v[190:193], v[238:241], v[4:7]
	v_mfma_f32_16x16x32_bf16 v[0:3], v[206:209], v[238:241], v[0:3]
	v_mfma_f32_16x16x32_bf16 v[28:31], v[194:197], v[218:221], v[28:31]
	v_mfma_f32_16x16x32_bf16 v[24:27], v[210:213], v[218:221], v[24:27]
	v_mfma_f32_16x16x32_bf16 v[20:23], v[194:197], v[226:229], v[20:23]
	v_mfma_f32_16x16x32_bf16 v[16:19], v[210:213], v[226:229], v[16:19]
	v_mfma_f32_16x16x32_bf16 v[12:15], v[194:197], v[234:237], v[12:15]
	v_mfma_f32_16x16x32_bf16 v[8:11], v[210:213], v[234:237], v[8:11]
	v_mfma_f32_16x16x32_bf16 v[4:7], v[194:197], v[242:245], v[4:7]
	v_mfma_f32_16x16x32_bf16 v[0:3], v[210:213], v[242:245], v[0:3]
	s_setprio 0
	s_barrier
	s_add_u32 s54, s54, 0x100
	s_addc_u32 s55, s55, 0
	s_add_u32 s23, s23, 0x100
	s_addc_u32 s27, s27, 0
	s_cmp_ge_i32 s69, s13
	s_mov_b32 s45, s69
	s_cbranch_scc1 .Lkexit_215

; #define PG8_BAR __builtin_amdgcn_s_barrier()
; template <class Epi, class Sched>
; __device__ __forceinline__ void gemm_phase(const int tid, LAS unsigned char* lds, const int lda, const int ldb, const int K, const Sched& S, const Epi& E) {
;     ...
;         }
;         if (wr == 0) PG8_BAR;
;         if (MK_EPI2 && Epi::IDEM) E(acc, cur, wr, wc, fr, fq, es0, es1);
;         E(acc, cur, wr, wc, fr, fq, es0, es1);
.Lkexit_215:
	s_load_dword s70, s[0:1], 0x108
	s_movk_i32 s71, 0x1600
	s_mov_b32 s58, 0x1a000
	s_mov_b32 s59, 0xa000
	v_mov_b64_e32 v[252:253], v[178:179]
	v_mov_b64_e32 v[178:179], v[172:173]
	v_mov_b64_e32 v[172:173], v[174:175]
	v_mov_b64_e32 v[174:175], v[204:205]
	s_and_b64 vcc, exec, s[42:43]
	s_cbranch_vccz .LBB0_218

; #define PG8_STAGE(bufoff, gbase, voff) do { _Pragma("unroll") for (int _i = 0; _i < 2; ++_i) \
;         __builtin_amdgcn_global_load_lds((const unsigned*)((const char*)(gbase) + (voff)[_i]), (LAS unsigned*)(lds + (bufoff) + ldsw + _i * 8192), 16, 0, 0); } while (0)
; #define PG8_LDA(dst, b, h) do { _Pragma("unroll") for (int m = 0; m < 4; ++m) _Pragma("unroll") for (int k = 0; k < 2; ++k) dst[m][k] = *(const LAS bf16x8*)(lds + PG8_SA(b, h) + aoff + m * 2048 + k * 1024); } while (0)
; #define PG8_LDB(dst, b, h) do { _Pragma("unroll") for (int n = 0; n < 2; ++n) _Pragma("unroll") for (int k = 0; k < 2; ++k) dst[n][k] = *(const LAS bf16x8*)(lds + PG8_SB(b, h) + boff + n * 2048 + k * 1024); } while (0)
; #define PG8_MMA(ai, bj, At, Bt) do { __builtin_amdgcn_s_setprio(1); _Pragma("unroll") for (int m = 0; m < 4; ++m) _Pragma("unroll") for (int n = 0; n < 2; ++n) _Pragma("unroll") for (int k = 0; k < 2; ++k) \
;         acc[ai][bj][m][n] = __builtin_amdgcn_mfma_f32_16x16x32_bf16(Bt[n][k], At[m][k], acc[ai][bj][m][n], 0, 0, 0); __builtin_amdgcn_s_setprio(0); } while (0)
; #define PG8_WAIT_V(n) asm volatile("s_waitcnt vmcnt(" #n ")" ::: "memory")
; #define PG8_WAIT_L(n) asm volatile("s_waitcnt lgkmcnt(" #n ")" ::: "memory")
; #define PG8_BAR __builtin_amdgcn_s_barrier()
; template <class Epi, class Sched>
; __device__ __forceinline__ void gemm_phase(const int tid, LAS unsigned char* lds, const int lda, const int ldb, const int K, const Sched& S, const Epi& E) {
;     ...
;         for (int t = 0; t < nt; t += 2) {
;             const bool last = (t == nt - 2);
;             const char* a1 = cA + (size_t)(t + 1) * kstep;
;             const char* a2 = last ? nA : cA + (size_t)(t + 2) * kstep; const char* b2 = last ? nB : cB + (size_t)(t + 2) * kstep;
;             const char* a3 = a2 + kstep; const char* b3 = b2 + kstep;
;             PG8_LDB(B0, 0, 0); PG8_LDB(B1, 0, 1); PG8_SCHED; PG8_LDA(At, 0, 0); PG8_STAGE(PG8_SA(1, 1), a1 + hstepA, voffA);
;             PG8_WAIT_V(8); PG8_WAIT_L(0); PG8_BAR; PG8_MMA(0, 0, At, B0); PG8_MMA(0, 1, At, B1); PG8_BAR; PG8_SCHED;
;             PG8_LDA(At, 0, 1); PG8_STAGE(PG8_SB(0, 0), b2, voffB); PG8_STAGE(PG8_SB(0, 1), b2 + hstepB, voffB); PG8_STAGE(PG8_SA(0, 0), a2, voffA);
;             PG8_WAIT_V(8); PG8_WAIT_L(0); PG8_BAR; if (!cur.half) { PG8_MMA(1, 0, At, B0); PG8_MMA(1, 1, At, B1); } PG8_BAR; PG8_SCHED;
.LBB0_309:
	s_andn2_b64 vcc, exec, s[56:57]
	s_cbranch_vccnz .LBB0_312
	s_add_u32 s66, s66, 0x40080
	s_addc_u32 s67, s67, 0
	s_add_u32 s53, s68, 0x100
	s_addc_u32 s61, s69, 0
	s_mov_b32 s68, 0
	s_add_i32 vcc_lo, s68, 2
	s_add_u32 s14, s66, 0xfffc0080
	s_addc_u32 s15, s67, -1
	s_add_i32 s24, 0, 0x10000
	s_cmp_eq_u32 s45, s68
	s_cselect_b32 s71, s3, s15
	s_cselect_b32 s70, s2, s14
	s_cselect_b32 s69, s39, s61
	s_cselect_b32 s68, s38, s53
	s_add_i32 s14, 0, 0x14000
	v_add_u32_e32 v150, s24, v163
	v_add_u32_e32 v176, s14, v163
	ds_read_b128 v[104:107], v150
	ds_read_b128 v[112:115], v150 offset:1024
	ds_read_b128 v[136:139], v150 offset:2048
	ds_read_b128 v[150:153], v150 offset:3072
	ds_read_b128 v[154:157], v176
	ds_read_b128 v[158:161], v176 offset:1024
	ds_read_b128 v[182:185], v176 offset:2048
	ds_read_b128 v[190:193], v176 offset:3072
	v_lshl_add_u64 v[176:177], s[66:67], 0, v[146:147]
	s_add_i32 m0, s72, 0xc000
	ds_read_b128 v[194:197], v180
	ds_read_b128 v[206:209], v180 offset:1024
	ds_read_b128 v[210:213], v180 offset:2048
	ds_read_b128 v[214:217], v180 offset:3072
	ds_read_b128 v[218:221], v180 offset:4096
	ds_read_b128 v[222:225], v180 offset:5120
	ds_read_b128 v[226:229], v180 offset:6144
	ds_read_b128 v[230:233], v180 offset:7168
	global_load_lds_dwordx4 v[176:177], off
	v_lshl_add_u64 v[176:177], s[66:67], 0, v[148:149]
	s_add_i32 m0, s72, 0xe000
	s_nop 0
	global_load_lds_dwordx4 v[176:177], off
	s_waitcnt vmcnt(8)
	s_waitcnt lgkmcnt(0)
	s_barrier
	s_setprio 1
	s_waitcnt lgkmcnt(0)
	v_mfma_f32_16x16x32_bf16 v[132:135], v[104:107], v[194:197], 0
	v_mfma_f32_16x16x32_bf16 v[60:63], v[136:139], v[194:197], 0
	v_mfma_f32_16x16x32_bf16 v[124:127], v[104:107], v[210:213], 0
	v_mfma_f32_16x16x32_bf16 v[52:55], v[136:139], v[210:213], 0
	v_mfma_f32_16x16x32_bf16 v[116:119], v[104:107], v[218:221], 0
	v_mfma_f32_16x16x32_bf16 v[44:47], v[136:139], v[218:221], 0
	v_mfma_f32_16x16x32_bf16 v[100:103], v[104:107], v[226:229], 0
	v_mfma_f32_16x16x32_bf16 v[36:39], v[136:139], v[226:229], 0
	v_mfma_f32_16x16x32_bf16 v[132:135], v[112:115], v[206:209], v[132:135]
	v_mfma_f32_16x16x32_bf16 v[60:63], v[150:153], v[206:209], v[60:63]
	v_mfma_f32_16x16x32_bf16 v[124:127], v[112:115], v[214:217], v[124:127]
	v_mfma_f32_16x16x32_bf16 v[52:55], v[150:153], v[214:217], v[52:55]
	v_mfma_f32_16x16x32_bf16 v[116:119], v[112:115], v[222:225], v[116:119]
	v_mfma_f32_16x16x32_bf16 v[44:47], v[150:153], v[222:225], v[44:47]
	v_mfma_f32_16x16x32_bf16 v[100:103], v[112:115], v[230:233], v[100:103]
	v_mfma_f32_16x16x32_bf16 v[36:39], v[150:153], v[230:233], v[36:39]
	s_setprio 0
	s_setprio 1
	v_mfma_f32_16x16x32_bf16 v[128:131], v[154:157], v[194:197], 0
	v_mfma_f32_16x16x32_bf16 v[56:59], v[182:185], v[194:197], 0
	v_mfma_f32_16x16x32_bf16 v[120:123], v[154:157], v[210:213], 0
	v_mfma_f32_16x16x32_bf16 v[48:51], v[182:185], v[210:213], 0
	v_mfma_f32_16x16x32_bf16 v[108:111], v[154:157], v[218:221], 0
	v_mfma_f32_16x16x32_bf16 v[40:43], v[182:185], v[218:221], 0
	v_mfma_f32_16x16x32_bf16 v[96:99], v[154:157], v[226:229], 0
	v_mfma_f32_16x16x32_bf16 v[32:35], v[182:185], v[226:229], 0
	v_mfma_f32_16x16x32_bf16 v[128:131], v[158:161], v[206:209], v[128:131]
	v_mfma_f32_16x16x32_bf16 v[56:59], v[190:193], v[206:209], v[56:59]
	v_mfma_f32_16x16x32_bf16 v[120:123], v[158:161], v[214:217], v[120:123]
	v_mfma_f32_16x16x32_bf16 v[48:51], v[190:193], v[214:217], v[48:51]
	v_mfma_f32_16x16x32_bf16 v[108:111], v[158:161], v[222:225], v[108:111]
	v_mfma_f32_16x16x32_bf16 v[40:43], v[190:193], v[222:225], v[40:43]
	v_mfma_f32_16x16x32_bf16 v[96:99], v[158:161], v[230:233], v[96:99]
	v_mfma_f32_16x16x32_bf16 v[32:35], v[190:193], v[230:233], v[32:35]
	s_setprio 0
	s_barrier
	s_add_i32 s15, s24, s31
	v_lshl_add_u64 v[176:177], s[68:69], 0, v[168:169]
	s_mov_b32 m0, s15
	ds_read_b128 v[194:197], v180 offset:16384
	ds_read_b128 v[206:209], v180 offset:17408
	ds_read_b128 v[210:213], v180 offset:18432
	ds_read_b128 v[214:217], v180 offset:19456
	ds_read_b128 v[218:221], v180 offset:20480
	ds_read_b128 v[222:225], v180 offset:21504
	ds_read_b128 v[226:229], v180 offset:22528
	ds_read_b128 v[230:233], v180 offset:23552
	global_load_lds_dwordx4 v[176:177], off
	s_add_i32 m0, s15, 0x2000
	s_add_u32 s42, s68, 0x10000
	v_lshl_add_u64 v[186:187], s[68:69], 0, v[144:145]
	s_addc_u32 s43, s69, 0
	s_add_i32 s14, s14, s31
	global_load_lds_dwordx4 v[186:187], off
	v_lshl_add_u64 v[234:235], s[42:43], 0, v[168:169]
	s_mov_b32 m0, s14
	v_lshl_add_u64 v[236:237], s[70:71], 0, v[142:143]
	global_load_lds_dwordx4 v[234:235], off
	v_lshl_add_u64 v[234:235], s[42:43], 0, v[144:145]
	s_add_i32 m0, s14, 0x2000
	s_nop 0
	global_load_lds_dwordx4 v[234:235], off
	v_lshl_add_u64 v[234:235], s[70:71], 0, v[140:141]
	s_mov_b32 m0, s72
	s_nop 0
	global_load_lds_dwordx4 v[234:235], off
	s_mov_b32 m0, s73
	s_nop 0
	global_load_lds_dwordx4 v[236:237], off
	s_waitcnt vmcnt(8)
	s_waitcnt lgkmcnt(0)
	s_barrier
; #define PG8_STAGE(bufoff, gbase, voff) do { _Pragma("unroll") for (int _i = 0; _i < 2; ++_i) \
;         __builtin_amdgcn_global_load_lds((const unsigned*)((const char*)(gbase) + (voff)[_i]), (LAS unsigned*)(lds + (bufoff) + ldsw + _i * 8192), 16, 0, 0); } while (0)
; #define PG8_LDA(dst, b, h) do { _Pragma("unroll") for (int m = 0; m < 4; ++m) _Pragma("unroll") for (int k = 0; k < 2; ++k) dst[m][k] = *(const LAS bf16x8*)(lds + PG8_SA(b, h) + aoff + m * 2048 + k * 1024); } while (0)
; #define PG8_LDB(dst, b, h) do { _Pragma("unroll") for (int n = 0; n < 2; ++n) _Pragma("unroll") for (int k = 0; k < 2; ++k) dst[n][k] = *(const LAS bf16x8*)(lds + PG8_SB(b, h) + boff + n * 2048 + k * 1024); } while (0)
; #define PG8_MMA(ai, bj, At, Bt) do { __builtin_amdgcn_s_setprio(1); _Pragma("unroll") for (int m = 0; m < 4; ++m) _Pragma("unroll") for (int n = 0; n < 2; ++n) _Pragma("unroll") for (int k = 0; k < 2; ++k) \
;         acc[ai][bj][m][n] = __builtin_amdgcn_mfma_f32_16x16x32_bf16(Bt[n][k], At[m][k], acc[ai][bj][m][n], 0, 0, 0); __builtin_amdgcn_s_setprio(0); } while (0)
; #define PG8_WAIT_V(n) asm volatile("s_waitcnt vmcnt(" #n ")" ::: "memory")
; #define PG8_WAIT_L(n) asm volatile("s_waitcnt lgkmcnt(" #n ")" ::: "memory")
; #define PG8_BAR __builtin_amdgcn_s_barrier()
; #define PG8_SCHED __builtin_amdgcn_sched_barrier(0)
; template <class Epi, class Sched>
; __device__ __forceinline__ void gemm_phase(const int tid, LAS unsigned char* lds, const int lda, const int ldb, const int K, const Sched& S, const Epi& E) {
;     ...
;             PG8_WAIT_V(8); PG8_WAIT_L(0); PG8_BAR; if (!cur.half) { PG8_MMA(1, 0, At, B0); PG8_MMA(1, 1, At, B1); } PG8_BAR; PG8_SCHED;
;             PG8_LDB(B0, 1, 0); PG8_LDB(B1, 1, 1); PG8_SCHED; PG8_LDA(At, 1, 0); PG8_STAGE(PG8_SA(0, 1), a2 + hstepA, voffA);
;             PG8_WAIT_V(8); PG8_WAIT_L(0); PG8_BAR; PG8_MMA(0, 0, At, B0); PG8_MMA(0, 1, At, B1); PG8_BAR; PG8_SCHED;
	s_setprio 1
	s_waitcnt lgkmcnt(0)
	v_mfma_f32_16x16x32_bf16 v[92:95], v[104:107], v[194:197], 0
	v_mfma_f32_16x16x32_bf16 v[28:31], v[136:139], v[194:197], 0
	v_mfma_f32_16x16x32_bf16 v[84:87], v[104:107], v[210:213], 0
	v_mfma_f32_16x16x32_bf16 v[20:23], v[136:139], v[210:213], 0
	v_mfma_f32_16x16x32_bf16 v[76:79], v[104:107], v[218:221], 0
	v_mfma_f32_16x16x32_bf16 v[12:15], v[136:139], v[218:221], 0
	v_mfma_f32_16x16x32_bf16 v[68:71], v[104:107], v[226:229], 0
	v_mfma_f32_16x16x32_bf16 v[4:7], v[136:139], v[226:229], 0
	v_mfma_f32_16x16x32_bf16 v[92:95], v[112:115], v[206:209], v[92:95]
	v_mfma_f32_16x16x32_bf16 v[28:31], v[150:153], v[206:209], v[28:31]
	v_mfma_f32_16x16x32_bf16 v[84:87], v[112:115], v[214:217], v[84:87]
	v_mfma_f32_16x16x32_bf16 v[20:23], v[150:153], v[214:217], v[20:23]
	v_mfma_f32_16x16x32_bf16 v[76:79], v[112:115], v[222:225], v[76:79]
	v_mfma_f32_16x16x32_bf16 v[12:15], v[150:153], v[222:225], v[12:15]
	v_mfma_f32_16x16x32_bf16 v[68:71], v[112:115], v[230:233], v[68:71]
	v_mfma_f32_16x16x32_bf16 v[4:7], v[150:153], v[230:233], v[4:7]
	s_setprio 0
	s_setprio 1
	v_mfma_f32_16x16x32_bf16 v[88:91], v[154:157], v[194:197], 0
	v_mfma_f32_16x16x32_bf16 v[24:27], v[182:185], v[194:197], 0
	v_mfma_f32_16x16x32_bf16 v[80:83], v[154:157], v[210:213], 0
	v_mfma_f32_16x16x32_bf16 v[16:19], v[182:185], v[210:213], 0
	v_mfma_f32_16x16x32_bf16 v[72:75], v[154:157], v[218:221], 0
	v_mfma_f32_16x16x32_bf16 v[8:11], v[182:185], v[218:221], 0
	v_mfma_f32_16x16x32_bf16 v[64:67], v[154:157], v[226:229], 0
	v_mfma_f32_16x16x32_bf16 v[0:3], v[182:185], v[226:229], 0
	v_mfma_f32_16x16x32_bf16 v[88:91], v[158:161], v[206:209], v[88:91]
	v_mfma_f32_16x16x32_bf16 v[24:27], v[190:193], v[206:209], v[24:27]
	v_mfma_f32_16x16x32_bf16 v[80:83], v[158:161], v[214:217], v[80:83]
	v_mfma_f32_16x16x32_bf16 v[16:19], v[190:193], v[214:217], v[16:19]
	v_mfma_f32_16x16x32_bf16 v[72:75], v[158:161], v[222:225], v[72:75]
	v_mfma_f32_16x16x32_bf16 v[8:11], v[190:193], v[222:225], v[8:11]
	v_mfma_f32_16x16x32_bf16 v[64:67], v[158:161], v[230:233], v[64:67]
	v_mfma_f32_16x16x32_bf16 v[0:3], v[190:193], v[230:233], v[0:3]
	s_setprio 0
	s_barrier
	s_add_i32 s14, 0, 0x18000
	s_add_i32 s15, 0, 0x1c000
	v_add_u32_e32 v150, s14, v163
	v_add_u32_e32 v181, s15, v163
	ds_read_b128 v[104:107], v150
	ds_read_b128 v[112:115], v150 offset:1024
	ds_read_b128 v[136:139], v150 offset:2048
	ds_read_b128 v[150:153], v150 offset:3072
	ds_read_b128 v[154:157], v181
	ds_read_b128 v[158:161], v181 offset:1024
	ds_read_b128 v[182:185], v181 offset:2048
	ds_read_b128 v[190:193], v181 offset:3072
	s_add_u32 s42, s70, 0x40000
	s_addc_u32 s43, s71, 0
	s_mov_b32 m0, s74
	v_lshl_add_u64 v[238:239], s[42:43], 0, v[140:141]
	ds_read_b128 v[194:197], v180 offset:32768
	ds_read_b128 v[206:209], v180 offset:33792
	ds_read_b128 v[210:213], v180 offset:34816
	ds_read_b128 v[214:217], v180 offset:35840
	ds_read_b128 v[218:221], v180 offset:36864
	ds_read_b128 v[222:225], v180 offset:37888
	ds_read_b128 v[226:229], v180 offset:38912
	ds_read_b128 v[230:233], v180 offset:39936
	global_load_lds_dwordx4 v[238:239], off
	v_lshl_add_u64 v[238:239], s[42:43], 0, v[142:143]
	s_mov_b32 m0, s75
	s_nop 0
	global_load_lds_dwordx4 v[238:239], off
	s_waitcnt vmcnt(8)
	s_waitcnt lgkmcnt(0)
	s_barrier
	s_setprio 1
	s_waitcnt lgkmcnt(0)
	v_mfma_f32_16x16x32_bf16 v[132:135], v[104:107], v[194:197], v[132:135]
	v_mfma_f32_16x16x32_bf16 v[60:63], v[136:139], v[194:197], v[60:63]
	v_mfma_f32_16x16x32_bf16 v[124:127], v[104:107], v[210:213], v[124:127]
	v_mfma_f32_16x16x32_bf16 v[52:55], v[136:139], v[210:213], v[52:55]
	v_mfma_f32_16x16x32_bf16 v[116:119], v[104:107], v[218:221], v[116:119]
	v_mfma_f32_16x16x32_bf16 v[44:47], v[136:139], v[218:221], v[44:47]
	v_mfma_f32_16x16x32_bf16 v[100:103], v[104:107], v[226:229], v[100:103]
	v_mfma_f32_16x16x32_bf16 v[36:39], v[136:139], v[226:229], v[36:39]
	v_mfma_f32_16x16x32_bf16 v[132:135], v[112:115], v[206:209], v[132:135]
	v_mfma_f32_16x16x32_bf16 v[60:63], v[150:153], v[206:209], v[60:63]
	v_mfma_f32_16x16x32_bf16 v[124:127], v[112:115], v[214:217], v[124:127]
	v_mfma_f32_16x16x32_bf16 v[52:55], v[150:153], v[214:217], v[52:55]
	v_mfma_f32_16x16x32_bf16 v[116:119], v[112:115], v[222:225], v[116:119]
	v_mfma_f32_16x16x32_bf16 v[44:47], v[150:153], v[222:225], v[44:47]
	v_mfma_f32_16x16x32_bf16 v[100:103], v[112:115], v[230:233], v[100:103]
	v_mfma_f32_16x16x32_bf16 v[36:39], v[150:153], v[230:233], v[36:39]
	s_setprio 0
	s_setprio 1
	v_mfma_f32_16x16x32_bf16 v[128:131], v[154:157], v[194:197], v[128:131]
	v_mfma_f32_16x16x32_bf16 v[56:59], v[182:185], v[194:197], v[56:59]
	v_mfma_f32_16x16x32_bf16 v[120:123], v[154:157], v[210:213], v[120:123]
	v_mfma_f32_16x16x32_bf16 v[48:51], v[182:185], v[210:213], v[48:51]
	v_mfma_f32_16x16x32_bf16 v[108:111], v[154:157], v[218:221], v[108:111]
	v_mfma_f32_16x16x32_bf16 v[40:43], v[182:185], v[218:221], v[40:43]
	v_mfma_f32_16x16x32_bf16 v[96:99], v[154:157], v[226:229], v[96:99]
	v_mfma_f32_16x16x32_bf16 v[32:35], v[182:185], v[226:229], v[32:35]
	v_mfma_f32_16x16x32_bf16 v[128:131], v[158:161], v[206:209], v[128:131]
	v_mfma_f32_16x16x32_bf16 v[56:59], v[190:193], v[206:209], v[56:59]
	v_mfma_f32_16x16x32_bf16 v[120:123], v[158:161], v[214:217], v[120:123]
	v_mfma_f32_16x16x32_bf16 v[48:51], v[190:193], v[214:217], v[48:51]
	v_mfma_f32_16x16x32_bf16 v[108:111], v[158:161], v[222:225], v[108:111]
	v_mfma_f32_16x16x32_bf16 v[40:43], v[190:193], v[222:225], v[40:43]
	v_mfma_f32_16x16x32_bf16 v[96:99], v[158:161], v[230:233], v[96:99]
	v_mfma_f32_16x16x32_bf16 v[32:35], v[190:193], v[230:233], v[32:35]
	s_setprio 0
	s_barrier
; #define PG8_STAGE(bufoff, gbase, voff) do { _Pragma("unroll") for (int _i = 0; _i < 2; ++_i) \
;         __builtin_amdgcn_global_load_lds((const unsigned*)((const char*)(gbase) + (voff)[_i]), (LAS unsigned*)(lds + (bufoff) + ldsw + _i * 8192), 16, 0, 0); } while (0)
; #define PG8_LDA(dst, b, h) do { _Pragma("unroll") for (int m = 0; m < 4; ++m) _Pragma("unroll") for (int k = 0; k < 2; ++k) dst[m][k] = *(const LAS bf16x8*)(lds + PG8_SA(b, h) + aoff + m * 2048 + k * 1024); } while (0)
; #define PG8_LDB(dst, b, h) do { _Pragma("unroll") for (int n = 0; n < 2; ++n) _Pragma("unroll") for (int k = 0; k < 2; ++k) dst[n][k] = *(const LAS bf16x8*)(lds + PG8_SB(b, h) + boff + n * 2048 + k * 1024); } while (0)
; #define PG8_MMA(ai, bj, At, Bt) do { __builtin_amdgcn_s_setprio(1); _Pragma("unroll") for (int m = 0; m < 4; ++m) _Pragma("unroll") for (int n = 0; n < 2; ++n) _Pragma("unroll") for (int k = 0; k < 2; ++k) \
;         acc[ai][bj][m][n] = __builtin_amdgcn_mfma_f32_16x16x32_bf16(Bt[n][k], At[m][k], acc[ai][bj][m][n], 0, 0, 0); __builtin_amdgcn_s_setprio(0); } while (0)
; #define PG8_WAIT_V(n) asm volatile("s_waitcnt vmcnt(" #n ")" ::: "memory")
; #define PG8_WAIT_L(n) asm volatile("s_waitcnt lgkmcnt(" #n ")" ::: "memory")
; #define PG8_BAR __builtin_amdgcn_s_barrier()
; #define PG8_SCHED __builtin_amdgcn_sched_barrier(0)
; template <class Epi, class Sched>
; __device__ __forceinline__ void gemm_phase(const int tid, LAS unsigned char* lds, const int lda, const int ldb, const int K, const Sched& S, const Epi& E) {
;     ...
;             PG8_LDB(B0, 1, 0); PG8_LDB(B1, 1, 1); PG8_SCHED; PG8_LDA(At, 1, 0); PG8_STAGE(PG8_SA(0, 1), a2 + hstepA, voffA);
;             PG8_WAIT_V(8); PG8_WAIT_L(0); PG8_BAR; PG8_MMA(0, 0, At, B0); PG8_MMA(0, 1, At, B1); PG8_BAR; PG8_SCHED;
;             PG8_LDA(At, 1, 1); PG8_STAGE(PG8_SB(1, 0), b3, voffB); PG8_STAGE(PG8_SB(1, 1), b3 + hstepB, voffB); PG8_STAGE(PG8_SA(1, 0), a3, voffA);
;             PG8_WAIT_V(8); PG8_WAIT_L(0); PG8_BAR; if (!cur.half) { PG8_MMA(1, 0, At, B0); PG8_MMA(1, 1, At, B1); } PG8_BAR; PG8_SCHED;
;         }
	s_add_i32 s14, s14, s31
	v_lshl_add_u64 v[176:177], v[176:177], 0, s[6:7]
	s_mov_b32 m0, s14
	ds_read_b128 v[194:197], v180 offset:49152
	ds_read_b128 v[206:209], v180 offset:50176
	ds_read_b128 v[210:213], v180 offset:51200
	ds_read_b128 v[214:217], v180 offset:52224
	ds_read_b128 v[218:221], v180 offset:53248
	ds_read_b128 v[222:225], v180 offset:54272
	ds_read_b128 v[226:229], v180 offset:55296
	ds_read_b128 v[230:233], v180 offset:56320
	global_load_lds_dwordx4 v[176:177], off
	s_add_i32 m0, s14, 0x2000
	s_add_u32 s42, s68, 0x10080
	v_lshl_add_u64 v[176:177], v[186:187], 0, s[6:7]
	s_addc_u32 s43, s69, 0
	s_add_i32 s14, s15, s31
	global_load_lds_dwordx4 v[176:177], off
	v_lshl_add_u64 v[176:177], s[42:43], 0, v[168:169]
	s_mov_b32 m0, s14
	s_nop 0
	global_load_lds_dwordx4 v[176:177], off
	v_lshl_add_u64 v[176:177], s[42:43], 0, v[144:145]
	s_add_i32 m0, s14, 0x2000
	s_nop 0
	global_load_lds_dwordx4 v[176:177], off
	v_lshl_add_u64 v[176:177], v[234:235], 0, s[6:7]
	s_mov_b32 m0, s20
	s_nop 0
	global_load_lds_dwordx4 v[176:177], off
	v_lshl_add_u64 v[176:177], v[236:237], 0, s[6:7]
	s_mov_b32 m0, s13
	s_nop 0
	global_load_lds_dwordx4 v[176:177], off
	s_waitcnt vmcnt(8)
	s_waitcnt lgkmcnt(0)
	s_barrier
	s_setprio 1
	s_waitcnt lgkmcnt(0)
	v_mfma_f32_16x16x32_bf16 v[92:95], v[104:107], v[194:197], v[92:95]
	v_mfma_f32_16x16x32_bf16 v[28:31], v[136:139], v[194:197], v[28:31]
	v_mfma_f32_16x16x32_bf16 v[84:87], v[104:107], v[210:213], v[84:87]
	v_mfma_f32_16x16x32_bf16 v[20:23], v[136:139], v[210:213], v[20:23]
	v_mfma_f32_16x16x32_bf16 v[76:79], v[104:107], v[218:221], v[76:79]
	v_mfma_f32_16x16x32_bf16 v[12:15], v[136:139], v[218:221], v[12:15]
	v_mfma_f32_16x16x32_bf16 v[68:71], v[104:107], v[226:229], v[68:71]
	v_mfma_f32_16x16x32_bf16 v[4:7], v[136:139], v[226:229], v[4:7]
	v_mfma_f32_16x16x32_bf16 v[92:95], v[112:115], v[206:209], v[92:95]
	v_mfma_f32_16x16x32_bf16 v[28:31], v[150:153], v[206:209], v[28:31]
	v_mfma_f32_16x16x32_bf16 v[84:87], v[112:115], v[214:217], v[84:87]
	v_mfma_f32_16x16x32_bf16 v[20:23], v[150:153], v[214:217], v[20:23]
	v_mfma_f32_16x16x32_bf16 v[76:79], v[112:115], v[222:225], v[76:79]
	v_mfma_f32_16x16x32_bf16 v[12:15], v[150:153], v[222:225], v[12:15]
	v_mfma_f32_16x16x32_bf16 v[68:71], v[112:115], v[230:233], v[68:71]
	v_mfma_f32_16x16x32_bf16 v[4:7], v[150:153], v[230:233], v[4:7]
	s_setprio 0
	s_setprio 1
	v_mfma_f32_16x16x32_bf16 v[88:91], v[154:157], v[194:197], v[88:91]
	v_mfma_f32_16x16x32_bf16 v[24:27], v[182:185], v[194:197], v[24:27]
	v_mfma_f32_16x16x32_bf16 v[80:83], v[154:157], v[210:213], v[80:83]
	v_mfma_f32_16x16x32_bf16 v[16:19], v[182:185], v[210:213], v[16:19]
	v_mfma_f32_16x16x32_bf16 v[72:75], v[154:157], v[218:221], v[72:75]
	v_mfma_f32_16x16x32_bf16 v[8:11], v[182:185], v[218:221], v[8:11]
	v_mfma_f32_16x16x32_bf16 v[64:67], v[154:157], v[226:229], v[64:67]
	v_mfma_f32_16x16x32_bf16 v[0:3], v[182:185], v[226:229], v[0:3]
	v_mfma_f32_16x16x32_bf16 v[88:91], v[158:161], v[206:209], v[88:91]
	v_mfma_f32_16x16x32_bf16 v[24:27], v[190:193], v[206:209], v[24:27]
	v_mfma_f32_16x16x32_bf16 v[80:83], v[158:161], v[214:217], v[80:83]
	v_mfma_f32_16x16x32_bf16 v[16:19], v[190:193], v[214:217], v[16:19]
	v_mfma_f32_16x16x32_bf16 v[72:75], v[158:161], v[222:225], v[72:75]
	v_mfma_f32_16x16x32_bf16 v[8:11], v[190:193], v[222:225], v[8:11]
	v_mfma_f32_16x16x32_bf16 v[64:67], v[158:161], v[230:233], v[64:67]
	v_mfma_f32_16x16x32_bf16 v[0:3], v[190:193], v[230:233], v[0:3]
	s_setprio 0
	s_barrier
	s_add_u32 s66, s66, 0x100
	s_addc_u32 s67, s67, 0
	s_add_u32 s53, s53, 0x100
	s_addc_u32 s61, s61, 0
	s_cmp_ge_i32 vcc_lo, s29
	s_mov_b32 s68, vcc_lo
	s_cbranch_scc1 .Lkexit_311
.LBB0_311:
	s_add_i32 vcc_lo, s68, 2
	s_add_u32 s14, s66, 0xfffc0080
	s_addc_u32 s15, s67, -1
	s_add_i32 s24, 0, 0x10000
	s_cmp_eq_u32 s45, s68
	s_cselect_b32 s71, s3, s15
	s_cselect_b32 s70, s2, s14
	s_cselect_b32 s69, s39, s61
	s_cselect_b32 s68, s38, s53
	s_add_i32 s14, 0, 0x14000
	v_add_u32_e32 v150, s24, v163
	v_add_u32_e32 v176, s14, v163
	ds_read_b128 v[104:107], v150
	ds_read_b128 v[112:115], v150 offset:1024
	ds_read_b128 v[136:139], v150 offset:2048
	ds_read_b128 v[150:153], v150 offset:3072
	ds_read_b128 v[154:157], v176
	ds_read_b128 v[158:161], v176 offset:1024
	ds_read_b128 v[182:185], v176 offset:2048
	ds_read_b128 v[190:193], v176 offset:3072
	v_lshl_add_u64 v[176:177], s[66:67], 0, v[146:147]
	s_add_i32 m0, s72, 0xc000
	ds_read_b128 v[194:197], v180
	ds_read_b128 v[206:209], v180 offset:1024
	ds_read_b128 v[210:213], v180 offset:2048
	ds_read_b128 v[214:217], v180 offset:3072
	ds_read_b128 v[218:221], v180 offset:4096
	ds_read_b128 v[222:225], v180 offset:5120
	ds_read_b128 v[226:229], v180 offset:6144
	ds_read_b128 v[230:233], v180 offset:7168
	global_load_lds_dwordx4 v[176:177], off
	v_lshl_add_u64 v[176:177], s[66:67], 0, v[148:149]
	s_add_i32 m0, s72, 0xe000
	s_nop 0
	global_load_lds_dwordx4 v[176:177], off
	s_waitcnt vmcnt(8)
	s_waitcnt lgkmcnt(0)
	s_barrier
; #define PG8_STAGE(bufoff, gbase, voff) do { _Pragma("unroll") for (int _i = 0; _i < 2; ++_i) \
;         __builtin_amdgcn_global_load_lds((const unsigned*)((const char*)(gbase) + (voff)[_i]), (LAS unsigned*)(lds + (bufoff) + ldsw + _i * 8192), 16, 0, 0); } while (0)
; #define PG8_LDA(dst, b, h) do { _Pragma("unroll") for (int m = 0; m < 4; ++m) _Pragma("unroll") for (int k = 0; k < 2; ++k) dst[m][k] = *(const LAS bf16x8*)(lds + PG8_SA(b, h) + aoff + m * 2048 + k * 1024); } while (0)
; #define PG8_LDB(dst, b, h) do { _Pragma("unroll") for (int n = 0; n < 2; ++n) _Pragma("unroll") for (int k = 0; k < 2; ++k) dst[n][k] = *(const LAS bf16x8*)(lds + PG8_SB(b, h) + boff + n * 2048 + k * 1024); } while (0)
; #define PG8_MMA(ai, bj, At, Bt) do { __builtin_amdgcn_s_setprio(1); _Pragma("unroll") for (int m = 0; m < 4; ++m) _Pragma("unroll") for (int n = 0; n < 2; ++n) _Pragma("unroll") for (int k = 0; k < 2; ++k) \
;         acc[ai][bj][m][n] = __builtin_amdgcn_mfma_f32_16x16x32_bf16(Bt[n][k], At[m][k], acc[ai][bj][m][n], 0, 0, 0); __builtin_amdgcn_s_setprio(0); } while (0)
; #define PG8_WAIT_V(n) asm volatile("s_waitcnt vmcnt(" #n ")" ::: "memory")
; #define PG8_WAIT_L(n) asm volatile("s_waitcnt lgkmcnt(" #n ")" ::: "memory")
; #define PG8_BAR __builtin_amdgcn_s_barrier()
; #define PG8_SCHED __builtin_amdgcn_sched_barrier(0)
; template <class Epi, class Sched>
; __device__ __forceinline__ void gemm_phase(const int tid, LAS unsigned char* lds, const int lda, const int ldb, const int K, const Sched& S, const Epi& E) {
;     ...
;             PG8_WAIT_V(8); PG8_WAIT_L(0); PG8_BAR; PG8_MMA(0, 0, At, B0); PG8_MMA(0, 1, At, B1); PG8_BAR; PG8_SCHED;
;             PG8_LDA(At, 0, 1); PG8_STAGE(PG8_SB(0, 0), b2, voffB); PG8_STAGE(PG8_SB(0, 1), b2 + hstepB, voffB); PG8_STAGE(PG8_SA(0, 0), a2, voffA);
;             PG8_WAIT_V(8); PG8_WAIT_L(0); PG8_BAR; if (!cur.half) { PG8_MMA(1, 0, At, B0); PG8_MMA(1, 1, At, B1); } PG8_BAR; PG8_SCHED;
;             PG8_LDB(B0, 1, 0); PG8_LDB(B1, 1, 1); PG8_SCHED; PG8_LDA(At, 1, 0); PG8_STAGE(PG8_SA(0, 1), a2 + hstepA, voffA);
;             PG8_WAIT_V(8); PG8_WAIT_L(0); PG8_BAR; PG8_MMA(0, 0, At, B0); PG8_MMA(0, 1, At, B1); PG8_BAR; PG8_SCHED;
	s_setprio 1
	s_waitcnt lgkmcnt(0)
	v_mfma_f32_16x16x32_bf16 v[132:135], v[104:107], v[194:197], v[132:135]
	v_mfma_f32_16x16x32_bf16 v[60:63], v[136:139], v[194:197], v[60:63]
	v_mfma_f32_16x16x32_bf16 v[124:127], v[104:107], v[210:213], v[124:127]
	v_mfma_f32_16x16x32_bf16 v[52:55], v[136:139], v[210:213], v[52:55]
	v_mfma_f32_16x16x32_bf16 v[116:119], v[104:107], v[218:221], v[116:119]
	v_mfma_f32_16x16x32_bf16 v[44:47], v[136:139], v[218:221], v[44:47]
	v_mfma_f32_16x16x32_bf16 v[100:103], v[104:107], v[226:229], v[100:103]
	v_mfma_f32_16x16x32_bf16 v[36:39], v[136:139], v[226:229], v[36:39]
	v_mfma_f32_16x16x32_bf16 v[132:135], v[112:115], v[206:209], v[132:135]
	v_mfma_f32_16x16x32_bf16 v[60:63], v[150:153], v[206:209], v[60:63]
	v_mfma_f32_16x16x32_bf16 v[124:127], v[112:115], v[214:217], v[124:127]
	v_mfma_f32_16x16x32_bf16 v[52:55], v[150:153], v[214:217], v[52:55]
	v_mfma_f32_16x16x32_bf16 v[116:119], v[112:115], v[222:225], v[116:119]
	v_mfma_f32_16x16x32_bf16 v[44:47], v[150:153], v[222:225], v[44:47]
	v_mfma_f32_16x16x32_bf16 v[100:103], v[112:115], v[230:233], v[100:103]
	v_mfma_f32_16x16x32_bf16 v[36:39], v[150:153], v[230:233], v[36:39]
	s_setprio 0
	s_setprio 1
	v_mfma_f32_16x16x32_bf16 v[128:131], v[154:157], v[194:197], v[128:131]
	v_mfma_f32_16x16x32_bf16 v[56:59], v[182:185], v[194:197], v[56:59]
	v_mfma_f32_16x16x32_bf16 v[120:123], v[154:157], v[210:213], v[120:123]
	v_mfma_f32_16x16x32_bf16 v[48:51], v[182:185], v[210:213], v[48:51]
	v_mfma_f32_16x16x32_bf16 v[108:111], v[154:157], v[218:221], v[108:111]
	v_mfma_f32_16x16x32_bf16 v[40:43], v[182:185], v[218:221], v[40:43]
	v_mfma_f32_16x16x32_bf16 v[96:99], v[154:157], v[226:229], v[96:99]
	v_mfma_f32_16x16x32_bf16 v[32:35], v[182:185], v[226:229], v[32:35]
	v_mfma_f32_16x16x32_bf16 v[128:131], v[158:161], v[206:209], v[128:131]
	v_mfma_f32_16x16x32_bf16 v[56:59], v[190:193], v[206:209], v[56:59]
	v_mfma_f32_16x16x32_bf16 v[120:123], v[158:161], v[214:217], v[120:123]
	v_mfma_f32_16x16x32_bf16 v[48:51], v[190:193], v[214:217], v[48:51]
	v_mfma_f32_16x16x32_bf16 v[108:111], v[158:161], v[222:225], v[108:111]
	v_mfma_f32_16x16x32_bf16 v[40:43], v[190:193], v[222:225], v[40:43]
	v_mfma_f32_16x16x32_bf16 v[96:99], v[158:161], v[230:233], v[96:99]
	v_mfma_f32_16x16x32_bf16 v[32:35], v[190:193], v[230:233], v[32:35]
	s_setprio 0
	s_barrier
	s_add_i32 s15, s24, s31
	v_lshl_add_u64 v[176:177], s[68:69], 0, v[168:169]
	s_mov_b32 m0, s15
	ds_read_b128 v[194:197], v180 offset:16384
	ds_read_b128 v[206:209], v180 offset:17408
	ds_read_b128 v[210:213], v180 offset:18432
	ds_read_b128 v[214:217], v180 offset:19456
	ds_read_b128 v[218:221], v180 offset:20480
	ds_read_b128 v[222:225], v180 offset:21504
	ds_read_b128 v[226:229], v180 offset:22528
	ds_read_b128 v[230:233], v180 offset:23552
	global_load_lds_dwordx4 v[176:177], off
	s_add_i32 m0, s15, 0x2000
	s_add_u32 s42, s68, 0x10000
	v_lshl_add_u64 v[186:187], s[68:69], 0, v[144:145]
	s_addc_u32 s43, s69, 0
	s_add_i32 s14, s14, s31
	global_load_lds_dwordx4 v[186:187], off
	v_lshl_add_u64 v[234:235], s[42:43], 0, v[168:169]
	s_mov_b32 m0, s14
	v_lshl_add_u64 v[236:237], s[70:71], 0, v[142:143]
	global_load_lds_dwordx4 v[234:235], off
	v_lshl_add_u64 v[234:235], s[42:43], 0, v[144:145]
	s_add_i32 m0, s14, 0x2000
	s_nop 0
	global_load_lds_dwordx4 v[234:235], off
	v_lshl_add_u64 v[234:235], s[70:71], 0, v[140:141]
	s_mov_b32 m0, s72
	s_nop 0
	global_load_lds_dwordx4 v[234:235], off
	s_mov_b32 m0, s73
	s_nop 0
	global_load_lds_dwordx4 v[236:237], off
	s_waitcnt vmcnt(8)
	s_waitcnt lgkmcnt(0)
	s_barrier
	s_setprio 1
	s_waitcnt lgkmcnt(0)
	v_mfma_f32_16x16x32_bf16 v[92:95], v[104:107], v[194:197], v[92:95]
	v_mfma_f32_16x16x32_bf16 v[28:31], v[136:139], v[194:197], v[28:31]
	v_mfma_f32_16x16x32_bf16 v[84:87], v[104:107], v[210:213], v[84:87]
	v_mfma_f32_16x16x32_bf16 v[20:23], v[136:139], v[210:213], v[20:23]
	v_mfma_f32_16x16x32_bf16 v[76:79], v[104:107], v[218:221], v[76:79]
	v_mfma_f32_16x16x32_bf16 v[12:15], v[136:139], v[218:221], v[12:15]
	v_mfma_f32_16x16x32_bf16 v[68:71], v[104:107], v[226:229], v[68:71]
	v_mfma_f32_16x16x32_bf16 v[4:7], v[136:139], v[226:229], v[4:7]
	v_mfma_f32_16x16x32_bf16 v[92:95], v[112:115], v[206:209], v[92:95]
	v_mfma_f32_16x16x32_bf16 v[28:31], v[150:153], v[206:209], v[28:31]
	v_mfma_f32_16x16x32_bf16 v[84:87], v[112:115], v[214:217], v[84:87]
	v_mfma_f32_16x16x32_bf16 v[20:23], v[150:153], v[214:217], v[20:23]
	v_mfma_f32_16x16x32_bf16 v[76:79], v[112:115], v[222:225], v[76:79]
	v_mfma_f32_16x16x32_bf16 v[12:15], v[150:153], v[222:225], v[12:15]
	v_mfma_f32_16x16x32_bf16 v[68:71], v[112:115], v[230:233], v[68:71]
	v_mfma_f32_16x16x32_bf16 v[4:7], v[150:153], v[230:233], v[4:7]
	s_setprio 0
	s_setprio 1
	v_mfma_f32_16x16x32_bf16 v[88:91], v[154:157], v[194:197], v[88:91]
	v_mfma_f32_16x16x32_bf16 v[24:27], v[182:185], v[194:197], v[24:27]
	v_mfma_f32_16x16x32_bf16 v[80:83], v[154:157], v[210:213], v[80:83]
	v_mfma_f32_16x16x32_bf16 v[16:19], v[182:185], v[210:213], v[16:19]
	v_mfma_f32_16x16x32_bf16 v[72:75], v[154:157], v[218:221], v[72:75]
	v_mfma_f32_16x16x32_bf16 v[8:11], v[182:185], v[218:221], v[8:11]
	v_mfma_f32_16x16x32_bf16 v[64:67], v[154:157], v[226:229], v[64:67]
	v_mfma_f32_16x16x32_bf16 v[0:3], v[182:185], v[226:229], v[0:3]
	v_mfma_f32_16x16x32_bf16 v[88:91], v[158:161], v[206:209], v[88:91]
	v_mfma_f32_16x16x32_bf16 v[24:27], v[190:193], v[206:209], v[24:27]
	v_mfma_f32_16x16x32_bf16 v[80:83], v[158:161], v[214:217], v[80:83]
	v_mfma_f32_16x16x32_bf16 v[16:19], v[190:193], v[214:217], v[16:19]
	v_mfma_f32_16x16x32_bf16 v[72:75], v[158:161], v[222:225], v[72:75]
	v_mfma_f32_16x16x32_bf16 v[8:11], v[190:193], v[222:225], v[8:11]
	v_mfma_f32_16x16x32_bf16 v[64:67], v[158:161], v[230:233], v[64:67]
	v_mfma_f32_16x16x32_bf16 v[0:3], v[190:193], v[230:233], v[0:3]
	s_setprio 0
	s_barrier
; #define PG8_STAGE(bufoff, gbase, voff) do { _Pragma("unroll") for (int _i = 0; _i < 2; ++_i) \
;         __builtin_amdgcn_global_load_lds((const unsigned*)((const char*)(gbase) + (voff)[_i]), (LAS unsigned*)(lds + (bufoff) + ldsw + _i * 8192), 16, 0, 0); } while (0)
; #define PG8_LDA(dst, b, h) do { _Pragma("unroll") for (int m = 0; m < 4; ++m) _Pragma("unroll") for (int k = 0; k < 2; ++k) dst[m][k] = *(const LAS bf16x8*)(lds + PG8_SA(b, h) + aoff + m * 2048 + k * 1024); } while (0)
; #define PG8_LDB(dst, b, h) do { _Pragma("unroll") for (int n = 0; n < 2; ++n) _Pragma("unroll") for (int k = 0; k < 2; ++k) dst[n][k] = *(const LAS bf16x8*)(lds + PG8_SB(b, h) + boff + n * 2048 + k * 1024); } while (0)
; #define PG8_MMA(ai, bj, At, Bt) do { __builtin_amdgcn_s_setprio(1); _Pragma("unroll") for (int m = 0; m < 4; ++m) _Pragma("unroll") for (int n = 0; n < 2; ++n) _Pragma("unroll") for (int k = 0; k < 2; ++k) \
;         acc[ai][bj][m][n] = __builtin_amdgcn_mfma_f32_16x16x32_bf16(Bt[n][k], At[m][k], acc[ai][bj][m][n], 0, 0, 0); __builtin_amdgcn_s_setprio(0); } while (0)
; #define PG8_WAIT_V(n) asm volatile("s_waitcnt vmcnt(" #n ")" ::: "memory")
; #define PG8_WAIT_L(n) asm volatile("s_waitcnt lgkmcnt(" #n ")" ::: "memory")
; #define PG8_BAR __builtin_amdgcn_s_barrier()
; #define PG8_SCHED __builtin_amdgcn_sched_barrier(0)
; template <class Epi, class Sched>
; __device__ __forceinline__ void gemm_phase(const int tid, LAS unsigned char* lds, const int lda, const int ldb, const int K, const Sched& S, const Epi& E) {
;     ...
;             PG8_LDB(B0, 1, 0); PG8_LDB(B1, 1, 1); PG8_SCHED; PG8_LDA(At, 1, 0); PG8_STAGE(PG8_SA(0, 1), a2 + hstepA, voffA);
;             PG8_WAIT_V(8); PG8_WAIT_L(0); PG8_BAR; PG8_MMA(0, 0, At, B0); PG8_MMA(0, 1, At, B1); PG8_BAR; PG8_SCHED;
;             PG8_LDA(At, 1, 1); PG8_STAGE(PG8_SB(1, 0), b3, voffB); PG8_STAGE(PG8_SB(1, 1), b3 + hstepB, voffB); PG8_STAGE(PG8_SA(1, 0), a3, voffA);
;             PG8_WAIT_V(8); PG8_WAIT_L(0); PG8_BAR; if (!cur.half) { PG8_MMA(1, 0, At, B0); PG8_MMA(1, 1, At, B1); } PG8_BAR; PG8_SCHED;
	s_add_i32 s14, 0, 0x18000
	s_add_i32 s15, 0, 0x1c000
	v_add_u32_e32 v150, s14, v163
	v_add_u32_e32 v181, s15, v163
	ds_read_b128 v[104:107], v150
	ds_read_b128 v[112:115], v150 offset:1024
	ds_read_b128 v[136:139], v150 offset:2048
	ds_read_b128 v[150:153], v150 offset:3072
	ds_read_b128 v[154:157], v181
	ds_read_b128 v[158:161], v181 offset:1024
	ds_read_b128 v[182:185], v181 offset:2048
	ds_read_b128 v[190:193], v181 offset:3072
	s_add_u32 s42, s70, 0x40000
	s_addc_u32 s43, s71, 0
	s_mov_b32 m0, s74
	v_lshl_add_u64 v[238:239], s[42:43], 0, v[140:141]
	ds_read_b128 v[194:197], v180 offset:32768
	ds_read_b128 v[206:209], v180 offset:33792
	ds_read_b128 v[210:213], v180 offset:34816
	ds_read_b128 v[214:217], v180 offset:35840
	ds_read_b128 v[218:221], v180 offset:36864
	ds_read_b128 v[222:225], v180 offset:37888
	ds_read_b128 v[226:229], v180 offset:38912
	ds_read_b128 v[230:233], v180 offset:39936
	global_load_lds_dwordx4 v[238:239], off
	v_lshl_add_u64 v[238:239], s[42:43], 0, v[142:143]
	s_mov_b32 m0, s75
	s_nop 0
	global_load_lds_dwordx4 v[238:239], off
	s_waitcnt vmcnt(8)
	s_waitcnt lgkmcnt(0)
	s_barrier
	s_setprio 1
	s_waitcnt lgkmcnt(0)
	v_mfma_f32_16x16x32_bf16 v[132:135], v[104:107], v[194:197], v[132:135]
	v_mfma_f32_16x16x32_bf16 v[60:63], v[136:139], v[194:197], v[60:63]
	v_mfma_f32_16x16x32_bf16 v[124:127], v[104:107], v[210:213], v[124:127]
	v_mfma_f32_16x16x32_bf16 v[52:55], v[136:139], v[210:213], v[52:55]
	v_mfma_f32_16x16x32_bf16 v[116:119], v[104:107], v[218:221], v[116:119]
	v_mfma_f32_16x16x32_bf16 v[44:47], v[136:139], v[218:221], v[44:47]
	v_mfma_f32_16x16x32_bf16 v[100:103], v[104:107], v[226:229], v[100:103]
	v_mfma_f32_16x16x32_bf16 v[36:39], v[136:139], v[226:229], v[36:39]
	v_mfma_f32_16x16x32_bf16 v[132:135], v[112:115], v[206:209], v[132:135]
	v_mfma_f32_16x16x32_bf16 v[60:63], v[150:153], v[206:209], v[60:63]
	v_mfma_f32_16x16x32_bf16 v[124:127], v[112:115], v[214:217], v[124:127]
	v_mfma_f32_16x16x32_bf16 v[52:55], v[150:153], v[214:217], v[52:55]
	v_mfma_f32_16x16x32_bf16 v[116:119], v[112:115], v[222:225], v[116:119]
	v_mfma_f32_16x16x32_bf16 v[44:47], v[150:153], v[222:225], v[44:47]
	v_mfma_f32_16x16x32_bf16 v[100:103], v[112:115], v[230:233], v[100:103]
	v_mfma_f32_16x16x32_bf16 v[36:39], v[150:153], v[230:233], v[36:39]
	s_setprio 0
	s_setprio 1
	v_mfma_f32_16x16x32_bf16 v[128:131], v[154:157], v[194:197], v[128:131]
	v_mfma_f32_16x16x32_bf16 v[56:59], v[182:185], v[194:197], v[56:59]
	v_mfma_f32_16x16x32_bf16 v[120:123], v[154:157], v[210:213], v[120:123]
	v_mfma_f32_16x16x32_bf16 v[48:51], v[182:185], v[210:213], v[48:51]
	v_mfma_f32_16x16x32_bf16 v[108:111], v[154:157], v[218:221], v[108:111]
	v_mfma_f32_16x16x32_bf16 v[40:43], v[182:185], v[218:221], v[40:43]
	v_mfma_f32_16x16x32_bf16 v[96:99], v[154:157], v[226:229], v[96:99]
	v_mfma_f32_16x16x32_bf16 v[32:35], v[182:185], v[226:229], v[32:35]
	v_mfma_f32_16x16x32_bf16 v[128:131], v[158:161], v[206:209], v[128:131]
	v_mfma_f32_16x16x32_bf16 v[56:59], v[190:193], v[206:209], v[56:59]
	v_mfma_f32_16x16x32_bf16 v[120:123], v[158:161], v[214:217], v[120:123]
	v_mfma_f32_16x16x32_bf16 v[48:51], v[190:193], v[214:217], v[48:51]
	v_mfma_f32_16x16x32_bf16 v[108:111], v[158:161], v[222:225], v[108:111]
	v_mfma_f32_16x16x32_bf16 v[40:43], v[190:193], v[222:225], v[40:43]
	v_mfma_f32_16x16x32_bf16 v[96:99], v[158:161], v[230:233], v[96:99]
	v_mfma_f32_16x16x32_bf16 v[32:35], v[190:193], v[230:233], v[32:35]
	s_setprio 0
	s_barrier
	s_add_i32 s14, s14, s31
	v_lshl_add_u64 v[176:177], v[176:177], 0, s[6:7]
	s_mov_b32 m0, s14
	ds_read_b128 v[194:197], v180 offset:49152
	ds_read_b128 v[206:209], v180 offset:50176
	ds_read_b128 v[210:213], v180 offset:51200
	ds_read_b128 v[214:217], v180 offset:52224
	ds_read_b128 v[218:221], v180 offset:53248
	ds_read_b128 v[222:225], v180 offset:54272
	ds_read_b128 v[226:229], v180 offset:55296
	ds_read_b128 v[230:233], v180 offset:56320
	global_load_lds_dwordx4 v[176:177], off
	s_add_i32 m0, s14, 0x2000
	s_add_u32 s42, s68, 0x10080
	v_lshl_add_u64 v[176:177], v[186:187], 0, s[6:7]
	s_addc_u32 s43, s69, 0
	s_add_i32 s14, s15, s31
	global_load_lds_dwordx4 v[176:177], off
	v_lshl_add_u64 v[176:177], s[42:43], 0, v[168:169]
	s_mov_b32 m0, s14
	s_nop 0
	global_load_lds_dwordx4 v[176:177], off
	v_lshl_add_u64 v[176:177], s[42:43], 0, v[144:145]
	s_add_i32 m0, s14, 0x2000
	s_nop 0
	global_load_lds_dwordx4 v[176:177], off
	v_lshl_add_u64 v[176:177], v[234:235], 0, s[6:7]
	s_mov_b32 m0, s20
	s_nop 0
	global_load_lds_dwordx4 v[176:177], off
	v_lshl_add_u64 v[176:177], v[236:237], 0, s[6:7]
	s_mov_b32 m0, s13
	s_nop 0
	global_load_lds_dwordx4 v[176:177], off
	s_waitcnt vmcnt(8)
	s_waitcnt lgkmcnt(0)
	s_barrier
; #define PG8_MMA(ai, bj, At, Bt) do { __builtin_amdgcn_s_setprio(1); _Pragma("unroll") for (int m = 0; m < 4; ++m) _Pragma("unroll") for (int n = 0; n < 2; ++n) _Pragma("unroll") for (int k = 0; k < 2; ++k) \
;         acc[ai][bj][m][n] = __builtin_amdgcn_mfma_f32_16x16x32_bf16(Bt[n][k], At[m][k], acc[ai][bj][m][n], 0, 0, 0); __builtin_amdgcn_s_setprio(0); } while (0)
; #define PG8_WAIT_V(n) asm volatile("s_waitcnt vmcnt(" #n ")" ::: "memory")
; #define PG8_WAIT_L(n) asm volatile("s_waitcnt lgkmcnt(" #n ")" ::: "memory")
; #define PG8_BAR __builtin_amdgcn_s_barrier()
; #define PG8_SCHED __builtin_amdgcn_sched_barrier(0)
; template <class Epi, class Sched>
; __device__ __forceinline__ void gemm_phase(const int tid, LAS unsigned char* lds, const int lda, const int ldb, const int K, const Sched& S, const Epi& E) {
;     ...
;             PG8_WAIT_V(8); PG8_WAIT_L(0); PG8_BAR; if (!cur.half) { PG8_MMA(1, 0, At, B0); PG8_MMA(1, 1, At, B1); } PG8_BAR; PG8_SCHED;
;         }
; __device__ __forceinline__ void acc_zero(f32x4 (&acc)[2][2][4][2]) {
; #pragma unroll
;     for (int a = 0; a < 2; ++a)
; #pragma unroll
;         for (int b = 0; b < 2; ++b)
; #pragma unroll
;             for (int m = 0; m < 4; ++m)
; #pragma unroll
;                 for (int n = 0; n < 2; ++n) acc[a][b][m][n] = (f32x4){0.f, 0.f, 0.f, 0.f};
	s_setprio 1
	s_waitcnt lgkmcnt(0)
	v_mfma_f32_16x16x32_bf16 v[92:95], v[104:107], v[194:197], v[92:95]
	v_mfma_f32_16x16x32_bf16 v[28:31], v[136:139], v[194:197], v[28:31]
	v_mfma_f32_16x16x32_bf16 v[84:87], v[104:107], v[210:213], v[84:87]
	v_mfma_f32_16x16x32_bf16 v[20:23], v[136:139], v[210:213], v[20:23]
	v_mfma_f32_16x16x32_bf16 v[76:79], v[104:107], v[218:221], v[76:79]
	v_mfma_f32_16x16x32_bf16 v[12:15], v[136:139], v[218:221], v[12:15]
	v_mfma_f32_16x16x32_bf16 v[68:71], v[104:107], v[226:229], v[68:71]
	v_mfma_f32_16x16x32_bf16 v[4:7], v[136:139], v[226:229], v[4:7]
	v_mfma_f32_16x16x32_bf16 v[92:95], v[112:115], v[206:209], v[92:95]
	v_mfma_f32_16x16x32_bf16 v[28:31], v[150:153], v[206:209], v[28:31]
	v_mfma_f32_16x16x32_bf16 v[84:87], v[112:115], v[214:217], v[84:87]
	v_mfma_f32_16x16x32_bf16 v[20:23], v[150:153], v[214:217], v[20:23]
	v_mfma_f32_16x16x32_bf16 v[76:79], v[112:115], v[222:225], v[76:79]
	v_mfma_f32_16x16x32_bf16 v[12:15], v[150:153], v[222:225], v[12:15]
	v_mfma_f32_16x16x32_bf16 v[68:71], v[112:115], v[230:233], v[68:71]
	v_mfma_f32_16x16x32_bf16 v[4:7], v[150:153], v[230:233], v[4:7]
	s_setprio 0
	s_setprio 1
	v_mfma_f32_16x16x32_bf16 v[88:91], v[154:157], v[194:197], v[88:91]
	v_mfma_f32_16x16x32_bf16 v[24:27], v[182:185], v[194:197], v[24:27]
	v_mfma_f32_16x16x32_bf16 v[80:83], v[154:157], v[210:213], v[80:83]
	v_mfma_f32_16x16x32_bf16 v[16:19], v[182:185], v[210:213], v[16:19]
	v_mfma_f32_16x16x32_bf16 v[72:75], v[154:157], v[218:221], v[72:75]
	v_mfma_f32_16x16x32_bf16 v[8:11], v[182:185], v[218:221], v[8:11]
	v_mfma_f32_16x16x32_bf16 v[64:67], v[154:157], v[226:229], v[64:67]
	v_mfma_f32_16x16x32_bf16 v[0:3], v[182:185], v[226:229], v[0:3]
	v_mfma_f32_16x16x32_bf16 v[88:91], v[158:161], v[206:209], v[88:91]
	v_mfma_f32_16x16x32_bf16 v[24:27], v[190:193], v[206:209], v[24:27]
	v_mfma_f32_16x16x32_bf16 v[80:83], v[158:161], v[214:217], v[80:83]
	v_mfma_f32_16x16x32_bf16 v[16:19], v[190:193], v[214:217], v[16:19]
	v_mfma_f32_16x16x32_bf16 v[72:75], v[158:161], v[222:225], v[72:75]
	v_mfma_f32_16x16x32_bf16 v[8:11], v[190:193], v[222:225], v[8:11]
	v_mfma_f32_16x16x32_bf16 v[64:67], v[158:161], v[230:233], v[64:67]
	v_mfma_f32_16x16x32_bf16 v[0:3], v[190:193], v[230:233], v[0:3]
	s_setprio 0
	s_barrier
	s_add_u32 s66, s66, 0x100
	s_addc_u32 s67, s67, 0
	s_add_u32 s53, s53, 0x100
	s_addc_u32 s61, s61, 0
	s_cmp_ge_i32 vcc_lo, s29
	s_mov_b32 s68, vcc_lo
	s_cbranch_scc0 .LBB0_311
.Lkexit_311:
	s_branch .LBB0_313
.LBB0_312:
	v_mov_b32_e32 v135, 0
	v_mov_b32_e32 v134, v135
	v_mov_b32_e32 v133, v135
	v_mov_b32_e32 v132, v135
	v_mov_b32_e32 v63, v135
	v_mov_b32_e32 v62, v135
	v_mov_b32_e32 v61, v135
	v_mov_b32_e32 v60, v135
	v_mov_b32_e32 v127, v135
	v_mov_b32_e32 v126, v135
	v_mov_b32_e32 v125, v135
	v_mov_b32_e32 v124, v135
	v_mov_b32_e32 v55, v135
	v_mov_b32_e32 v54, v135
	v_mov_b32_e32 v53, v135
	v_mov_b32_e32 v52, v135
	v_mov_b32_e32 v119, v135
	v_mov_b32_e32 v118, v135
	v_mov_b32_e32 v117, v135
	v_mov_b32_e32 v116, v135
	v_mov_b32_e32 v47, v135
	v_mov_b32_e32 v46, v135
	v_mov_b32_e32 v45, v135
	v_mov_b32_e32 v44, v135
	v_mov_b32_e32 v103, v135
	v_mov_b32_e32 v102, v135
	v_mov_b32_e32 v101, v135
	v_mov_b32_e32 v100, v135
	v_mov_b32_e32 v39, v135
	v_mov_b32_e32 v38, v135
	v_mov_b32_e32 v37, v135
	v_mov_b32_e32 v36, v135
	v_mov_b32_e32 v131, v135
	v_mov_b32_e32 v130, v135
	v_mov_b32_e32 v129, v135
	v_mov_b32_e32 v128, v135
	v_mov_b32_e32 v59, v135
	v_mov_b32_e32 v58, v135
	v_mov_b32_e32 v57, v135
	v_mov_b32_e32 v56, v135
	v_mov_b32_e32 v123, v135
	v_mov_b32_e32 v122, v135
	v_mov_b32_e32 v121, v135
	v_mov_b32_e32 v120, v135
	v_mov_b32_e32 v51, v135
	v_mov_b32_e32 v50, v135
	v_mov_b32_e32 v49, v135
	v_mov_b32_e32 v48, v135
	v_mov_b32_e32 v111, v135
	v_mov_b32_e32 v110, v135
	v_mov_b32_e32 v109, v135
	v_mov_b32_e32 v108, v135
	v_mov_b32_e32 v43, v135
	v_mov_b32_e32 v42, v135
	v_mov_b32_e32 v41, v135
	v_mov_b32_e32 v40, v135
	v_mov_b32_e32 v99, v135
	v_mov_b32_e32 v98, v135
	v_mov_b32_e32 v97, v135
	v_mov_b32_e32 v96, v135
	v_mov_b32_e32 v35, v135
	v_mov_b32_e32 v34, v135
	v_mov_b32_e32 v33, v135
	v_mov_b32_e32 v32, v135
	v_mov_b32_e32 v95, v135
	v_mov_b32_e32 v94, v135
	v_mov_b32_e32 v93, v135
	v_mov_b32_e32 v92, v135
	v_mov_b32_e32 v31, v135
	v_mov_b32_e32 v30, v135
	v_mov_b32_e32 v29, v135
	v_mov_b32_e32 v28, v135
	v_mov_b32_e32 v87, v135
	v_mov_b32_e32 v86, v135
	v_mov_b32_e32 v85, v135
	v_mov_b32_e32 v84, v135
	v_mov_b32_e32 v23, v135
	v_mov_b32_e32 v22, v135
	v_mov_b32_e32 v21, v135
	v_mov_b32_e32 v20, v135
	v_mov_b32_e32 v79, v135
	v_mov_b32_e32 v78, v135
	v_mov_b32_e32 v77, v135
	v_mov_b32_e32 v76, v135
	v_mov_b32_e32 v15, v135
	v_mov_b32_e32 v14, v135
	v_mov_b32_e32 v13, v135
	v_mov_b32_e32 v12, v135
	v_mov_b32_e32 v71, v135
	v_mov_b32_e32 v70, v135
	v_mov_b32_e32 v69, v135
	v_mov_b32_e32 v68, v135
	v_mov_b32_e32 v7, v135
	v_mov_b32_e32 v6, v135
	v_mov_b32_e32 v5, v135
	v_mov_b32_e32 v4, v135
	v_mov_b32_e32 v91, v135
	v_mov_b32_e32 v90, v135
	v_mov_b32_e32 v89, v135
	v_mov_b32_e32 v88, v135
	v_mov_b32_e32 v27, v135
	v_mov_b32_e32 v26, v135
	v_mov_b32_e32 v25, v135
	v_mov_b32_e32 v24, v135
	v_mov_b32_e32 v83, v135
	v_mov_b32_e32 v82, v135
	v_mov_b32_e32 v81, v135
	v_mov_b32_e32 v80, v135
	v_mov_b32_e32 v19, v135
	v_mov_b32_e32 v18, v135
	v_mov_b32_e32 v17, v135
	v_mov_b32_e32 v16, v135
	v_mov_b32_e32 v75, v135
	v_mov_b32_e32 v74, v135
	v_mov_b32_e32 v73, v135
	v_mov_b32_e32 v72, v135
	v_mov_b32_e32 v11, v135
	v_mov_b32_e32 v10, v135
	v_mov_b32_e32 v9, v135
	v_mov_b32_e32 v8, v135
	v_mov_b32_e32 v67, v135
	v_mov_b32_e32 v66, v135
	v_mov_b32_e32 v65, v135
	v_mov_b32_e32 v64, v135
	v_mov_b32_e32 v3, v135
	v_mov_b32_e32 v2, v135
	v_mov_b32_e32 v1, v135
	v_mov_b32_e32 v0, v135

; #define PG8_WAIT_V(n) asm volatile("s_waitcnt vmcnt(" #n ")" ::: "memory")
; #define PG8_BAR __builtin_amdgcn_s_barrier()
; template <class Epi, class Sched>
; __device__ __forceinline__ void gemm_phase(const int tid, LAS unsigned char* lds, const int lda, const int ldb, const int K, const Sched& S, const Epi& E) {
;     ...
;         if (wr == 1) PG8_BAR;
;     }
;     PG8_WAIT_V(0);
;     PG8_BAR;
;     __device__ __forceinline__ void init(f32x4 (&acc)[2][2][4][2], const Unit& u, int wr, int wc, int fr, int fq) const {
; #pragma unroll
;         for (int ai = 0; ai < 2; ++ai)
; #pragma unroll
;             for (int m = 0; m < 4; ++m) {
;                 const int row = EPI_ROWS(ai, m);
; #pragma unroll
;                 for (int bj = 0; bj < 2; ++bj) { const float* p = h + (size_t)row * D + u.pn * 256 + bj * 128 + wc * 32 + 8 * fq; acc[ai][bj][m][0] = *(const f32x4*)p; acc[ai][bj][m][1] = *(const f32x4*)(p + 4); }
;             }
.LBB0_655:
	s_or_b64 exec, exec, s[48:49]
	s_andn2_b64 vcc, exec, s[38:39]
	s_mov_b64 s[38:39], -1
	s_cbranch_vccnz .LBB0_610
	s_lshl_b32 s14, s69, 8
	v_add_u32_e32 v0, s14, v146
	s_waitcnt lgkmcnt(0)
	v_ashrrev_i32_e32 v1, 31, v0
	s_lshl_b32 s38, s42, 8
	v_lshlrev_b64 v[2:3], 12, v[0:1]
	s_ashr_i32 s39, s38, 31
	v_lshl_add_u64 v[2:3], s[34:35], 0, v[2:3]
	s_lshl_b64 s[38:39], s[38:39], 2
	v_lshl_add_u64 v[2:3], v[2:3], 0, s[38:39]
	v_lshl_add_u64 v[2:3], v[2:3], 0, s[4:5]
	v_lshl_add_u64 v[2:3], v[2:3], 0, v[168:169]
	global_load_dwordx4 v[120:123], v[2:3], off offset:16
	global_load_dwordx4 v[124:127], v[2:3], off
	global_load_dwordx4 v[112:115], v[2:3], off offset:528
	global_load_dwordx4 v[116:119], v[2:3], off offset:512
	v_add_u32_e32 v2, s14, v147
	v_ashrrev_i32_e32 v3, 31, v2
	v_lshlrev_b64 v[4:5], 12, v[2:3]
	v_lshl_add_u64 v[4:5], s[34:35], 0, v[4:5]
	v_lshl_add_u64 v[4:5], v[4:5], 0, s[38:39]
	v_lshl_add_u64 v[4:5], v[4:5], 0, s[4:5]
	v_lshl_add_u64 v[4:5], v[4:5], 0, v[168:169]
	global_load_dwordx4 v[104:107], v[4:5], off offset:16
	global_load_dwordx4 v[108:111], v[4:5], off
	global_load_dwordx4 v[96:99], v[4:5], off offset:528
	global_load_dwordx4 v[100:103], v[4:5], off offset:512
	v_add_u32_e32 v4, s14, v148
	v_ashrrev_i32_e32 v5, 31, v4
	v_lshlrev_b64 v[6:7], 12, v[4:5]
	v_lshl_add_u64 v[6:7], s[34:35], 0, v[6:7]
	v_lshl_add_u64 v[6:7], v[6:7], 0, s[38:39]
	v_lshl_add_u64 v[6:7], v[6:7], 0, s[4:5]
	v_lshl_add_u64 v[6:7], v[6:7], 0, v[168:169]
	global_load_dwordx4 v[88:91], v[6:7], off offset:16
	global_load_dwordx4 v[92:95], v[6:7], off
	global_load_dwordx4 v[80:83], v[6:7], off offset:528
	global_load_dwordx4 v[84:87], v[6:7], off offset:512
	v_add_u32_e32 v6, s14, v149
	v_add_u32_e32 v0, 0x80, v0
	v_ashrrev_i32_e32 v7, 31, v6
	v_ashrrev_i32_e32 v1, 31, v0
	v_lshlrev_b64 v[8:9], 12, v[6:7]
	v_lshlrev_b64 v[0:1], 12, v[0:1]
	v_lshl_add_u64 v[8:9], s[34:35], 0, v[8:9]
	v_lshl_add_u64 v[0:1], s[34:35], 0, v[0:1]
	v_lshl_add_u64 v[8:9], v[8:9], 0, s[38:39]
	v_lshl_add_u64 v[0:1], v[0:1], 0, s[38:39]
	v_lshl_add_u64 v[8:9], v[8:9], 0, s[4:5]
	v_lshl_add_u64 v[0:1], v[0:1], 0, s[4:5]
	v_lshl_add_u64 v[8:9], v[8:9], 0, v[168:169]
	v_lshl_add_u64 v[0:1], v[0:1], 0, v[168:169]
	global_load_dwordx4 v[72:75], v[8:9], off offset:16
	global_load_dwordx4 v[76:79], v[8:9], off
	global_load_dwordx4 v[64:67], v[8:9], off offset:528
	global_load_dwordx4 v[68:71], v[8:9], off offset:512
	global_load_dwordx4 v[56:59], v[0:1], off offset:16
	global_load_dwordx4 v[60:63], v[0:1], off
	global_load_dwordx4 v[48:51], v[0:1], off offset:528
	global_load_dwordx4 v[52:55], v[0:1], off offset:512
	v_add_u32_e32 v0, 0x80, v2
	v_ashrrev_i32_e32 v1, 31, v0
	v_lshlrev_b64 v[0:1], 12, v[0:1]
	v_lshl_add_u64 v[0:1], s[34:35], 0, v[0:1]
	v_lshl_add_u64 v[0:1], v[0:1], 0, s[38:39]
	v_lshl_add_u64 v[0:1], v[0:1], 0, s[4:5]
	v_lshl_add_u64 v[0:1], v[0:1], 0, v[168:169]
	global_load_dwordx4 v[40:43], v[0:1], off offset:16
	global_load_dwordx4 v[44:47], v[0:1], off
	global_load_dwordx4 v[32:35], v[0:1], off offset:528
	global_load_dwordx4 v[36:39], v[0:1], off offset:512
	v_add_u32_e32 v0, 0x80, v4
	v_ashrrev_i32_e32 v1, 31, v0
	v_lshlrev_b64 v[0:1], 12, v[0:1]
	v_lshl_add_u64 v[0:1], s[34:35], 0, v[0:1]
	v_lshl_add_u64 v[0:1], v[0:1], 0, s[38:39]
	v_lshl_add_u64 v[0:1], v[0:1], 0, s[4:5]
	v_lshl_add_u64 v[0:1], v[0:1], 0, v[168:169]
	global_load_dwordx4 v[24:27], v[0:1], off offset:16
	global_load_dwordx4 v[28:31], v[0:1], off
	global_load_dwordx4 v[16:19], v[0:1], off offset:528
	global_load_dwordx4 v[20:23], v[0:1], off offset:512
	v_add_u32_e32 v0, 0x80, v6
	v_ashrrev_i32_e32 v1, 31, v0
	v_lshlrev_b64 v[0:1], 12, v[0:1]
	v_lshl_add_u64 v[0:1], s[34:35], 0, v[0:1]
	v_lshl_add_u64 v[0:1], v[0:1], 0, s[38:39]
	v_lshl_add_u64 v[0:1], v[0:1], 0, s[4:5]
	v_lshl_add_u64 v[4:5], v[0:1], 0, v[168:169]
	global_load_dwordx4 v[8:11], v[4:5], off offset:16
	global_load_dwordx4 v[12:15], v[4:5], off
	global_load_dwordx4 v[0:3], v[4:5], off offset:528
	s_nop 0
	global_load_dwordx4 v[4:7], v[4:5], off offset:512
	s_andn2_b64 vcc, exec, s[2:3]
	s_cbranch_vccnz .LBB0_609
	s_barrier
	s_branch .LBB0_609
.Ltramp_885:
	s_branch .LBB0_885
.LBB0_658:
	s_waitcnt vmcnt(0)
	v_readlane_b32 s68, v255, 13
	v_readlane_b32 s60, v254, 56
	v_readlane_b32 s69, v255, 14
	v_readlane_b32 s61, v254, 57
	s_mov_b32 s65, 0x12000
	s_mov_b32 s64, 0x14000
	s_mov_b32 s66, 0x16000
	s_mov_b32 s67, 0x18000
	s_mov_b32 s58, 0x1a000
	s_mov_b32 s59, 0xa000
	v_readlane_b32 s44, v255, 15
	s_barrier

; #define PG8_STAGE(bufoff, gbase, voff) do { _Pragma("unroll") for (int _i = 0; _i < 2; ++_i) \
;         __builtin_amdgcn_global_load_lds((const unsigned*)((const char*)(gbase) + (voff)[_i]), (LAS unsigned*)(lds + (bufoff) + ldsw + _i * 8192), 16, 0, 0); } while (0)
; #define PG8_LDA(dst, b, h) do { _Pragma("unroll") for (int m = 0; m < 4; ++m) _Pragma("unroll") for (int k = 0; k < 2; ++k) dst[m][k] = *(const LAS bf16x8*)(lds + PG8_SA(b, h) + aoff + m * 2048 + k * 1024); } while (0)
; #define PG8_LDB(dst, b, h) do { _Pragma("unroll") for (int n = 0; n < 2; ++n) _Pragma("unroll") for (int k = 0; k < 2; ++k) dst[n][k] = *(const LAS bf16x8*)(lds + PG8_SB(b, h) + boff + n * 2048 + k * 1024); } while (0)
; #define PG8_MMA(ai, bj, At, Bt) do { __builtin_amdgcn_s_setprio(1); _Pragma("unroll") for (int m = 0; m < 4; ++m) _Pragma("unroll") for (int n = 0; n < 2; ++n) _Pragma("unroll") for (int k = 0; k < 2; ++k) \
;         acc[ai][bj][m][n] = __builtin_amdgcn_mfma_f32_16x16x32_bf16(Bt[n][k], At[m][k], acc[ai][bj][m][n], 0, 0, 0); __builtin_amdgcn_s_setprio(0); } while (0)
; #define PG8_WAIT_V(n) asm volatile("s_waitcnt vmcnt(" #n ")" ::: "memory")
; #define PG8_WAIT_L(n) asm volatile("s_waitcnt lgkmcnt(" #n ")" ::: "memory")
; #define PG8_BAR __builtin_amdgcn_s_barrier()
; template <class Epi, class Sched>
; __device__ __forceinline__ void gemm_phase(const int tid, LAS unsigned char* lds, const int lda, const int ldb, const int K, const Sched& S, const Epi& E) {
;     ...
;         for (int t = 0; t < nt; t += 2) {
;             const bool last = (t == nt - 2);
;             const char* a1 = cA + (size_t)(t + 1) * kstep;
;             const char* a2 = last ? nA : cA + (size_t)(t + 2) * kstep; const char* b2 = last ? nB : cB + (size_t)(t + 2) * kstep;
;             const char* a3 = a2 + kstep; const char* b3 = b2 + kstep;
;             PG8_LDB(B0, 0, 0); PG8_LDB(B1, 0, 1); PG8_SCHED; PG8_LDA(At, 0, 0); PG8_STAGE(PG8_SA(1, 1), a1 + hstepA, voffA);
;             PG8_WAIT_V(8); PG8_WAIT_L(0); PG8_BAR; PG8_MMA(0, 0, At, B0); PG8_MMA(0, 1, At, B1); PG8_BAR; PG8_SCHED;
;             PG8_LDA(At, 0, 1); PG8_STAGE(PG8_SB(0, 0), b2, voffB); PG8_STAGE(PG8_SB(0, 1), b2 + hstepB, voffB); PG8_STAGE(PG8_SA(0, 0), a2, voffA);
;             PG8_WAIT_V(8); PG8_WAIT_L(0); PG8_BAR; if (!cur.half) { PG8_MMA(1, 0, At, B0); PG8_MMA(1, 1, At, B1); } PG8_BAR; PG8_SCHED;
.LBB0_679:
	s_andn2_b64 vcc, exec, s[40:41]
	s_cbranch_vccnz .LBB0_727
	s_add_u32 s50, s50, 0x40080
	s_addc_u32 s51, s51, 0
	s_add_u32 s26, s52, 0x100
	s_addc_u32 s27, s53, 0
	s_mov_b32 s45, 0
	s_add_i32 s67, s45, 2
	s_add_u32 s14, s50, 0xfffc0080
	s_addc_u32 s15, s51, -1
	s_add_i32 s24, 0, 0x10000
	s_cmp_eq_u32 s63, s45
	s_cselect_b32 s55, s3, s15
	s_cselect_b32 s54, s2, s14
	v_add_u32_e32 v146, s24, v152
	s_cselect_b32 s53, s39, s27
	s_cselect_b32 s52, s38, s26
	s_add_i32 s14, 0, 0x14000
	ds_read_b128 v[142:145], v146
	ds_read_b128 v[162:165], v146 offset:1024
	ds_read_b128 v[180:183], v146 offset:2048
	ds_read_b128 v[184:187], v146 offset:3072
	v_add_u32_e32 v146, s14, v152
	ds_read_b128 v[190:193], v146
	ds_read_b128 v[194:197], v146 offset:1024
	ds_read_b128 v[206:209], v146 offset:2048
	ds_read_b128 v[210:213], v146 offset:3072
	v_lshl_add_u64 v[146:147], s[50:51], 0, v[136:137]
	s_add_i32 m0, s56, 0xc000
	ds_read_b128 v[214:217], v160
	ds_read_b128 v[218:221], v160 offset:1024
	ds_read_b128 v[222:225], v160 offset:2048
	ds_read_b128 v[226:229], v160 offset:3072
	ds_read_b128 v[230:233], v160 offset:4096
	ds_read_b128 v[234:237], v160 offset:5120
	ds_read_b128 v[238:241], v160 offset:6144
	ds_read_b128 v[242:245], v160 offset:7168
	global_load_lds_dwordx4 v[146:147], off
	v_lshl_add_u64 v[146:147], s[50:51], 0, v[138:139]
	s_add_i32 m0, s56, 0xe000
	s_nop 0
	global_load_lds_dwordx4 v[146:147], off
	s_waitcnt vmcnt(8)
	s_waitcnt lgkmcnt(0)
	s_barrier
	s_setprio 1
	s_waitcnt lgkmcnt(0)
	v_mfma_f32_16x16x32_bf16 v[124:127], v[142:145], v[214:217], 0
	v_mfma_f32_16x16x32_bf16 v[120:123], v[180:183], v[214:217], 0
	v_mfma_f32_16x16x32_bf16 v[108:111], v[142:145], v[222:225], 0
	v_mfma_f32_16x16x32_bf16 v[104:107], v[180:183], v[222:225], 0
	v_mfma_f32_16x16x32_bf16 v[92:95], v[142:145], v[230:233], 0
	v_mfma_f32_16x16x32_bf16 v[88:91], v[180:183], v[230:233], 0
	v_mfma_f32_16x16x32_bf16 v[76:79], v[142:145], v[238:241], 0
	v_mfma_f32_16x16x32_bf16 v[72:75], v[180:183], v[238:241], 0
	v_mfma_f32_16x16x32_bf16 v[124:127], v[162:165], v[218:221], v[124:127]
	v_mfma_f32_16x16x32_bf16 v[120:123], v[184:187], v[218:221], v[120:123]
	v_mfma_f32_16x16x32_bf16 v[108:111], v[162:165], v[226:229], v[108:111]
	v_mfma_f32_16x16x32_bf16 v[104:107], v[184:187], v[226:229], v[104:107]
	v_mfma_f32_16x16x32_bf16 v[92:95], v[162:165], v[234:237], v[92:95]
	v_mfma_f32_16x16x32_bf16 v[88:91], v[184:187], v[234:237], v[88:91]
	v_mfma_f32_16x16x32_bf16 v[76:79], v[162:165], v[242:245], v[76:79]
	v_mfma_f32_16x16x32_bf16 v[72:75], v[184:187], v[242:245], v[72:75]
	s_setprio 0
	s_setprio 1
	v_mfma_f32_16x16x32_bf16 v[116:119], v[190:193], v[214:217], 0
	v_mfma_f32_16x16x32_bf16 v[112:115], v[206:209], v[214:217], 0
	v_mfma_f32_16x16x32_bf16 v[100:103], v[190:193], v[222:225], 0
	v_mfma_f32_16x16x32_bf16 v[96:99], v[206:209], v[222:225], 0
	v_mfma_f32_16x16x32_bf16 v[84:87], v[190:193], v[230:233], 0
	v_mfma_f32_16x16x32_bf16 v[80:83], v[206:209], v[230:233], 0
	v_mfma_f32_16x16x32_bf16 v[68:71], v[190:193], v[238:241], 0
	v_mfma_f32_16x16x32_bf16 v[64:67], v[206:209], v[238:241], 0
	v_mfma_f32_16x16x32_bf16 v[116:119], v[194:197], v[218:221], v[116:119]
	v_mfma_f32_16x16x32_bf16 v[112:115], v[210:213], v[218:221], v[112:115]
	v_mfma_f32_16x16x32_bf16 v[100:103], v[194:197], v[226:229], v[100:103]
	v_mfma_f32_16x16x32_bf16 v[96:99], v[210:213], v[226:229], v[96:99]
	v_mfma_f32_16x16x32_bf16 v[84:87], v[194:197], v[234:237], v[84:87]
	v_mfma_f32_16x16x32_bf16 v[80:83], v[210:213], v[234:237], v[80:83]
	v_mfma_f32_16x16x32_bf16 v[68:71], v[194:197], v[242:245], v[68:71]
	v_mfma_f32_16x16x32_bf16 v[64:67], v[210:213], v[242:245], v[64:67]
	s_setprio 0
	s_barrier
	s_add_i32 s15, s24, s31
	v_lshl_add_u64 v[146:147], s[52:53], 0, v[130:131]
	s_mov_b32 m0, s15
	ds_read_b128 v[214:217], v160 offset:16384
	ds_read_b128 v[218:221], v160 offset:17408
	ds_read_b128 v[222:225], v160 offset:18432
	ds_read_b128 v[226:229], v160 offset:19456
	ds_read_b128 v[230:233], v160 offset:20480
	ds_read_b128 v[234:237], v160 offset:21504
	ds_read_b128 v[238:241], v160 offset:22528
	ds_read_b128 v[242:245], v160 offset:23552
	global_load_lds_dwordx4 v[146:147], off
	s_add_i32 m0, s15, 0x2000
	s_add_u32 s68, s52, 0x40000
	v_lshl_add_u64 v[166:167], s[52:53], 0, v[134:135]
	s_addc_u32 s69, s53, 0
	s_add_i32 s14, s14, s31
	global_load_lds_dwordx4 v[166:167], off
	v_lshl_add_u64 v[176:177], s[68:69], 0, v[130:131]
	s_mov_b32 m0, s14
	v_lshl_add_u64 v[246:247], s[54:55], 0, v[132:133]
	global_load_lds_dwordx4 v[176:177], off
	v_lshl_add_u64 v[176:177], s[68:69], 0, v[134:135]
	s_add_i32 m0, s14, 0x2000
	s_nop 0
	global_load_lds_dwordx4 v[176:177], off
	v_lshl_add_u64 v[176:177], s[54:55], 0, v[128:129]
	s_mov_b32 m0, s56
	s_nop 0
	global_load_lds_dwordx4 v[176:177], off
	s_mov_b32 m0, s57
	s_nop 0
	global_load_lds_dwordx4 v[246:247], off
	s_waitcnt vmcnt(8)
	s_waitcnt lgkmcnt(0)
	s_barrier
; #define PG8_STAGE(bufoff, gbase, voff) do { _Pragma("unroll") for (int _i = 0; _i < 2; ++_i) \
;         __builtin_amdgcn_global_load_lds((const unsigned*)((const char*)(gbase) + (voff)[_i]), (LAS unsigned*)(lds + (bufoff) + ldsw + _i * 8192), 16, 0, 0); } while (0)
; #define PG8_LDA(dst, b, h) do { _Pragma("unroll") for (int m = 0; m < 4; ++m) _Pragma("unroll") for (int k = 0; k < 2; ++k) dst[m][k] = *(const LAS bf16x8*)(lds + PG8_SA(b, h) + aoff + m * 2048 + k * 1024); } while (0)
; #define PG8_LDB(dst, b, h) do { _Pragma("unroll") for (int n = 0; n < 2; ++n) _Pragma("unroll") for (int k = 0; k < 2; ++k) dst[n][k] = *(const LAS bf16x8*)(lds + PG8_SB(b, h) + boff + n * 2048 + k * 1024); } while (0)
; #define PG8_MMA(ai, bj, At, Bt) do { __builtin_amdgcn_s_setprio(1); _Pragma("unroll") for (int m = 0; m < 4; ++m) _Pragma("unroll") for (int n = 0; n < 2; ++n) _Pragma("unroll") for (int k = 0; k < 2; ++k) \
;         acc[ai][bj][m][n] = __builtin_amdgcn_mfma_f32_16x16x32_bf16(Bt[n][k], At[m][k], acc[ai][bj][m][n], 0, 0, 0); __builtin_amdgcn_s_setprio(0); } while (0)
; #define PG8_WAIT_V(n) asm volatile("s_waitcnt vmcnt(" #n ")" ::: "memory")
; #define PG8_WAIT_L(n) asm volatile("s_waitcnt lgkmcnt(" #n ")" ::: "memory")
; #define PG8_BAR __builtin_amdgcn_s_barrier()
; #define PG8_SCHED __builtin_amdgcn_sched_barrier(0)
; template <class Epi, class Sched>
; __device__ __forceinline__ void gemm_phase(const int tid, LAS unsigned char* lds, const int lda, const int ldb, const int K, const Sched& S, const Epi& E) {
;     ...
;             PG8_WAIT_V(8); PG8_WAIT_L(0); PG8_BAR; if (!cur.half) { PG8_MMA(1, 0, At, B0); PG8_MMA(1, 1, At, B1); } PG8_BAR; PG8_SCHED;
;             PG8_LDB(B0, 1, 0); PG8_LDB(B1, 1, 1); PG8_SCHED; PG8_LDA(At, 1, 0); PG8_STAGE(PG8_SA(0, 1), a2 + hstepA, voffA);
;             PG8_WAIT_V(8); PG8_WAIT_L(0); PG8_BAR; PG8_MMA(0, 0, At, B0); PG8_MMA(0, 1, At, B1); PG8_BAR; PG8_SCHED;
	s_setprio 1
	s_waitcnt lgkmcnt(0)
	v_mfma_f32_16x16x32_bf16 v[60:63], v[142:145], v[214:217], 0
	v_mfma_f32_16x16x32_bf16 v[56:59], v[180:183], v[214:217], 0
	v_mfma_f32_16x16x32_bf16 v[44:47], v[142:145], v[222:225], 0
	v_mfma_f32_16x16x32_bf16 v[40:43], v[180:183], v[222:225], 0
	v_mfma_f32_16x16x32_bf16 v[28:31], v[142:145], v[230:233], 0
	v_mfma_f32_16x16x32_bf16 v[24:27], v[180:183], v[230:233], 0
	v_mfma_f32_16x16x32_bf16 v[12:15], v[142:145], v[238:241], 0
	v_mfma_f32_16x16x32_bf16 v[8:11], v[180:183], v[238:241], 0
	v_mfma_f32_16x16x32_bf16 v[60:63], v[162:165], v[218:221], v[60:63]
	v_mfma_f32_16x16x32_bf16 v[56:59], v[184:187], v[218:221], v[56:59]
	v_mfma_f32_16x16x32_bf16 v[44:47], v[162:165], v[226:229], v[44:47]
	v_mfma_f32_16x16x32_bf16 v[40:43], v[184:187], v[226:229], v[40:43]
	v_mfma_f32_16x16x32_bf16 v[28:31], v[162:165], v[234:237], v[28:31]
	v_mfma_f32_16x16x32_bf16 v[24:27], v[184:187], v[234:237], v[24:27]
	v_mfma_f32_16x16x32_bf16 v[12:15], v[162:165], v[242:245], v[12:15]
	v_mfma_f32_16x16x32_bf16 v[8:11], v[184:187], v[242:245], v[8:11]
	s_setprio 0
	s_setprio 1
	v_mfma_f32_16x16x32_bf16 v[52:55], v[190:193], v[214:217], 0
	v_mfma_f32_16x16x32_bf16 v[48:51], v[206:209], v[214:217], 0
	v_mfma_f32_16x16x32_bf16 v[36:39], v[190:193], v[222:225], 0
	v_mfma_f32_16x16x32_bf16 v[32:35], v[206:209], v[222:225], 0
	v_mfma_f32_16x16x32_bf16 v[20:23], v[190:193], v[230:233], 0
	v_mfma_f32_16x16x32_bf16 v[16:19], v[206:209], v[230:233], 0
	v_mfma_f32_16x16x32_bf16 v[4:7], v[190:193], v[238:241], 0
	v_mfma_f32_16x16x32_bf16 v[0:3], v[206:209], v[238:241], 0
	v_mfma_f32_16x16x32_bf16 v[52:55], v[194:197], v[218:221], v[52:55]
	v_mfma_f32_16x16x32_bf16 v[48:51], v[210:213], v[218:221], v[48:51]
	v_mfma_f32_16x16x32_bf16 v[36:39], v[194:197], v[226:229], v[36:39]
	v_mfma_f32_16x16x32_bf16 v[32:35], v[210:213], v[226:229], v[32:35]
	v_mfma_f32_16x16x32_bf16 v[20:23], v[194:197], v[234:237], v[20:23]
	v_mfma_f32_16x16x32_bf16 v[16:19], v[210:213], v[234:237], v[16:19]
	v_mfma_f32_16x16x32_bf16 v[4:7], v[194:197], v[242:245], v[4:7]
	v_mfma_f32_16x16x32_bf16 v[0:3], v[210:213], v[242:245], v[0:3]
	s_setprio 0
	s_barrier
	s_add_i32 s14, 0, 0x18000
	v_add_u32_e32 v161, s14, v152
	s_add_i32 s15, 0, 0x1c000
	ds_read_b128 v[142:145], v161
	ds_read_b128 v[162:165], v161 offset:1024
	ds_read_b128 v[180:183], v161 offset:2048
	ds_read_b128 v[184:187], v161 offset:3072
	v_add_u32_e32 v161, s15, v152
	ds_read_b128 v[190:193], v161
	ds_read_b128 v[194:197], v161 offset:1024
	ds_read_b128 v[206:209], v161 offset:2048
	ds_read_b128 v[210:213], v161 offset:3072
	s_add_u32 s54, s54, 0x40000
	s_addc_u32 s55, s55, 0
	s_mov_b32 m0, s58
	v_lshl_add_u64 v[248:249], s[54:55], 0, v[128:129]
	ds_read_b128 v[214:217], v160 offset:32768
	ds_read_b128 v[218:221], v160 offset:33792
	ds_read_b128 v[222:225], v160 offset:34816
	ds_read_b128 v[226:229], v160 offset:35840
	ds_read_b128 v[230:233], v160 offset:36864
	ds_read_b128 v[234:237], v160 offset:37888
	ds_read_b128 v[238:241], v160 offset:38912
	ds_read_b128 v[242:245], v160 offset:39936
	global_load_lds_dwordx4 v[248:249], off
	v_lshl_add_u64 v[248:249], s[54:55], 0, v[132:133]
	s_mov_b32 m0, s59
	s_nop 0
	global_load_lds_dwordx4 v[248:249], off
	s_waitcnt vmcnt(8)
	s_waitcnt lgkmcnt(0)
	s_barrier
	s_setprio 1
	s_waitcnt lgkmcnt(0)
	v_mfma_f32_16x16x32_bf16 v[124:127], v[142:145], v[214:217], v[124:127]
	v_mfma_f32_16x16x32_bf16 v[120:123], v[180:183], v[214:217], v[120:123]
	v_mfma_f32_16x16x32_bf16 v[108:111], v[142:145], v[222:225], v[108:111]
	v_mfma_f32_16x16x32_bf16 v[104:107], v[180:183], v[222:225], v[104:107]
	v_mfma_f32_16x16x32_bf16 v[92:95], v[142:145], v[230:233], v[92:95]
	v_mfma_f32_16x16x32_bf16 v[88:91], v[180:183], v[230:233], v[88:91]
	v_mfma_f32_16x16x32_bf16 v[76:79], v[142:145], v[238:241], v[76:79]
	v_mfma_f32_16x16x32_bf16 v[72:75], v[180:183], v[238:241], v[72:75]
	v_mfma_f32_16x16x32_bf16 v[124:127], v[162:165], v[218:221], v[124:127]
	v_mfma_f32_16x16x32_bf16 v[120:123], v[184:187], v[218:221], v[120:123]
	v_mfma_f32_16x16x32_bf16 v[108:111], v[162:165], v[226:229], v[108:111]
	v_mfma_f32_16x16x32_bf16 v[104:107], v[184:187], v[226:229], v[104:107]
	v_mfma_f32_16x16x32_bf16 v[92:95], v[162:165], v[234:237], v[92:95]
	v_mfma_f32_16x16x32_bf16 v[88:91], v[184:187], v[234:237], v[88:91]
	v_mfma_f32_16x16x32_bf16 v[76:79], v[162:165], v[242:245], v[76:79]
	v_mfma_f32_16x16x32_bf16 v[72:75], v[184:187], v[242:245], v[72:75]
	s_setprio 0
	s_setprio 1
	v_mfma_f32_16x16x32_bf16 v[116:119], v[190:193], v[214:217], v[116:119]
	v_mfma_f32_16x16x32_bf16 v[112:115], v[206:209], v[214:217], v[112:115]
	v_mfma_f32_16x16x32_bf16 v[100:103], v[190:193], v[222:225], v[100:103]
	v_mfma_f32_16x16x32_bf16 v[96:99], v[206:209], v[222:225], v[96:99]
	v_mfma_f32_16x16x32_bf16 v[84:87], v[190:193], v[230:233], v[84:87]
	v_mfma_f32_16x16x32_bf16 v[80:83], v[206:209], v[230:233], v[80:83]
	v_mfma_f32_16x16x32_bf16 v[68:71], v[190:193], v[238:241], v[68:71]
	v_mfma_f32_16x16x32_bf16 v[64:67], v[206:209], v[238:241], v[64:67]
	v_mfma_f32_16x16x32_bf16 v[116:119], v[194:197], v[218:221], v[116:119]
	v_mfma_f32_16x16x32_bf16 v[112:115], v[210:213], v[218:221], v[112:115]
	v_mfma_f32_16x16x32_bf16 v[100:103], v[194:197], v[226:229], v[100:103]
	v_mfma_f32_16x16x32_bf16 v[96:99], v[210:213], v[226:229], v[96:99]
	v_mfma_f32_16x16x32_bf16 v[84:87], v[194:197], v[234:237], v[84:87]
	v_mfma_f32_16x16x32_bf16 v[80:83], v[210:213], v[234:237], v[80:83]
	v_mfma_f32_16x16x32_bf16 v[68:71], v[194:197], v[242:245], v[68:71]
	v_mfma_f32_16x16x32_bf16 v[64:67], v[210:213], v[242:245], v[64:67]
	s_setprio 0
	s_barrier
; #define PG8_STAGE(bufoff, gbase, voff) do { _Pragma("unroll") for (int _i = 0; _i < 2; ++_i) \
;         __builtin_amdgcn_global_load_lds((const unsigned*)((const char*)(gbase) + (voff)[_i]), (LAS unsigned*)(lds + (bufoff) + ldsw + _i * 8192), 16, 0, 0); } while (0)
; #define PG8_LDA(dst, b, h) do { _Pragma("unroll") for (int m = 0; m < 4; ++m) _Pragma("unroll") for (int k = 0; k < 2; ++k) dst[m][k] = *(const LAS bf16x8*)(lds + PG8_SA(b, h) + aoff + m * 2048 + k * 1024); } while (0)
; #define PG8_MMA(ai, bj, At, Bt) do { __builtin_amdgcn_s_setprio(1); _Pragma("unroll") for (int m = 0; m < 4; ++m) _Pragma("unroll") for (int n = 0; n < 2; ++n) _Pragma("unroll") for (int k = 0; k < 2; ++k) \
;         acc[ai][bj][m][n] = __builtin_amdgcn_mfma_f32_16x16x32_bf16(Bt[n][k], At[m][k], acc[ai][bj][m][n], 0, 0, 0); __builtin_amdgcn_s_setprio(0); } while (0)
; #define PG8_WAIT_V(n) asm volatile("s_waitcnt vmcnt(" #n ")" ::: "memory")
; #define PG8_WAIT_L(n) asm volatile("s_waitcnt lgkmcnt(" #n ")" ::: "memory")
; #define PG8_BAR __builtin_amdgcn_s_barrier()
; #define PG8_SCHED __builtin_amdgcn_sched_barrier(0)
; template <class Epi, class Sched>
; __device__ __forceinline__ void gemm_phase(const int tid, LAS unsigned char* lds, const int lda, const int ldb, const int K, const Sched& S, const Epi& E) {
;     ...
;         for (int t = 0; t < nt; t += 2) {
;             const bool last = (t == nt - 2);
;             const char* a1 = cA + (size_t)(t + 1) * kstep;
;             const char* a2 = last ? nA : cA + (size_t)(t + 2) * kstep; const char* b2 = last ? nB : cB + (size_t)(t + 2) * kstep;
;             const char* a3 = a2 + kstep; const char* b3 = b2 + kstep;
;     ...
;             PG8_LDA(At, 1, 1); PG8_STAGE(PG8_SB(1, 0), b3, voffB); PG8_STAGE(PG8_SB(1, 1), b3 + hstepB, voffB); PG8_STAGE(PG8_SA(1, 0), a3, voffA);
;             PG8_WAIT_V(8); PG8_WAIT_L(0); PG8_BAR; if (!cur.half) { PG8_MMA(1, 0, At, B0); PG8_MMA(1, 1, At, B1); } PG8_BAR; PG8_SCHED;
	s_add_i32 s14, s14, s31
	v_lshl_add_u64 v[146:147], v[146:147], 0, s[6:7]
	s_mov_b32 m0, s14
	ds_read_b128 v[214:217], v160 offset:49152
	ds_read_b128 v[218:221], v160 offset:50176
	ds_read_b128 v[222:225], v160 offset:51200
	ds_read_b128 v[226:229], v160 offset:52224
	ds_read_b128 v[230:233], v160 offset:53248
	ds_read_b128 v[234:237], v160 offset:54272
	ds_read_b128 v[238:241], v160 offset:55296
	ds_read_b128 v[242:245], v160 offset:56320
	global_load_lds_dwordx4 v[146:147], off
	s_add_i32 m0, s14, 0x2000
	s_add_u32 s52, s52, 0x40080
	v_lshl_add_u64 v[146:147], v[166:167], 0, s[6:7]
	s_addc_u32 s53, s53, 0
	s_add_i32 s14, s15, s31
	global_load_lds_dwordx4 v[146:147], off
	v_lshl_add_u64 v[146:147], s[52:53], 0, v[130:131]
	s_mov_b32 m0, s14
	s_nop 0
	global_load_lds_dwordx4 v[146:147], off
	v_lshl_add_u64 v[146:147], s[52:53], 0, v[134:135]
	s_add_i32 m0, s14, 0x2000
	s_nop 0
	global_load_lds_dwordx4 v[146:147], off
	v_lshl_add_u64 v[146:147], v[176:177], 0, s[6:7]
	s_mov_b32 m0, s60
	s_nop 0
	global_load_lds_dwordx4 v[146:147], off
	v_lshl_add_u64 v[146:147], v[246:247], 0, s[6:7]
	s_mov_b32 m0, s61
	s_nop 0
	global_load_lds_dwordx4 v[146:147], off
	s_waitcnt vmcnt(8)
	s_waitcnt lgkmcnt(0)
	s_barrier
	s_setprio 1
	s_waitcnt lgkmcnt(0)
	v_mfma_f32_16x16x32_bf16 v[60:63], v[142:145], v[214:217], v[60:63]
	v_mfma_f32_16x16x32_bf16 v[56:59], v[180:183], v[214:217], v[56:59]
	v_mfma_f32_16x16x32_bf16 v[44:47], v[142:145], v[222:225], v[44:47]
	v_mfma_f32_16x16x32_bf16 v[40:43], v[180:183], v[222:225], v[40:43]
	v_mfma_f32_16x16x32_bf16 v[28:31], v[142:145], v[230:233], v[28:31]
	v_mfma_f32_16x16x32_bf16 v[24:27], v[180:183], v[230:233], v[24:27]
	v_mfma_f32_16x16x32_bf16 v[12:15], v[142:145], v[238:241], v[12:15]
	v_mfma_f32_16x16x32_bf16 v[8:11], v[180:183], v[238:241], v[8:11]
	v_mfma_f32_16x16x32_bf16 v[60:63], v[162:165], v[218:221], v[60:63]
	v_mfma_f32_16x16x32_bf16 v[56:59], v[184:187], v[218:221], v[56:59]
	v_mfma_f32_16x16x32_bf16 v[44:47], v[162:165], v[226:229], v[44:47]
	v_mfma_f32_16x16x32_bf16 v[40:43], v[184:187], v[226:229], v[40:43]
	v_mfma_f32_16x16x32_bf16 v[28:31], v[162:165], v[234:237], v[28:31]
	v_mfma_f32_16x16x32_bf16 v[24:27], v[184:187], v[234:237], v[24:27]
	v_mfma_f32_16x16x32_bf16 v[12:15], v[162:165], v[242:245], v[12:15]
	v_mfma_f32_16x16x32_bf16 v[8:11], v[184:187], v[242:245], v[8:11]
	s_setprio 0
	s_setprio 1
	v_mfma_f32_16x16x32_bf16 v[52:55], v[190:193], v[214:217], v[52:55]
	v_mfma_f32_16x16x32_bf16 v[48:51], v[206:209], v[214:217], v[48:51]
	v_mfma_f32_16x16x32_bf16 v[36:39], v[190:193], v[222:225], v[36:39]
	v_mfma_f32_16x16x32_bf16 v[32:35], v[206:209], v[222:225], v[32:35]
	v_mfma_f32_16x16x32_bf16 v[20:23], v[190:193], v[230:233], v[20:23]
	v_mfma_f32_16x16x32_bf16 v[16:19], v[206:209], v[230:233], v[16:19]
	v_mfma_f32_16x16x32_bf16 v[4:7], v[190:193], v[238:241], v[4:7]
	v_mfma_f32_16x16x32_bf16 v[0:3], v[206:209], v[238:241], v[0:3]
	v_mfma_f32_16x16x32_bf16 v[52:55], v[194:197], v[218:221], v[52:55]
	v_mfma_f32_16x16x32_bf16 v[48:51], v[210:213], v[218:221], v[48:51]
	v_mfma_f32_16x16x32_bf16 v[36:39], v[194:197], v[226:229], v[36:39]
	v_mfma_f32_16x16x32_bf16 v[32:35], v[210:213], v[226:229], v[32:35]
	v_mfma_f32_16x16x32_bf16 v[20:23], v[194:197], v[234:237], v[20:23]
	v_mfma_f32_16x16x32_bf16 v[16:19], v[210:213], v[234:237], v[16:19]
	v_mfma_f32_16x16x32_bf16 v[4:7], v[194:197], v[242:245], v[4:7]
	v_mfma_f32_16x16x32_bf16 v[0:3], v[210:213], v[242:245], v[0:3]
	s_setprio 0
	s_barrier
	s_add_u32 s50, s50, 0x100
	s_addc_u32 s51, s51, 0
	s_add_u32 s26, s26, 0x100
	s_addc_u32 s27, s27, 0
	s_cmp_ge_i32 s67, s29
	s_mov_b32 s45, s67
	s_cbranch_scc1 .Lkexit_681

; #define PG8_BAR __builtin_amdgcn_s_barrier()
; template <class Epi, class Sched>
; __device__ __forceinline__ void gemm_phase(const int tid, LAS unsigned char* lds, const int lda, const int ldb, const int K, const Sched& S, const Epi& E) {
;     ...
;         if (wr == 0) PG8_BAR;
;         if (MK_EPI2 && Epi::IDEM) E(acc, cur, wr, wc, fr, fq, es0, es1);
;         E(acc, cur, wr, wc, fr, fq, es0, es1);
;         if (!has_next) break;
.Lkexit_681:
	v_readlane_b32 s68, v255, 13
	v_readlane_b32 s69, v255, 14
	s_mov_b32 s67, 0x18000
	s_and_b64 vcc, exec, s[42:43]
	s_cbranch_vccz .LBB0_684

; #define PG8_STAGE(bufoff, gbase, voff) do { _Pragma("unroll") for (int _i = 0; _i < 2; ++_i) \
;         __builtin_amdgcn_global_load_lds((const unsigned*)((const char*)(gbase) + (voff)[_i]), (LAS unsigned*)(lds + (bufoff) + ldsw + _i * 8192), 16, 0, 0); } while (0)
; #define PG8_LDA(dst, b, h) do { _Pragma("unroll") for (int m = 0; m < 4; ++m) _Pragma("unroll") for (int k = 0; k < 2; ++k) dst[m][k] = *(const LAS bf16x8*)(lds + PG8_SA(b, h) + aoff + m * 2048 + k * 1024); } while (0)
; #define PG8_LDB(dst, b, h) do { _Pragma("unroll") for (int n = 0; n < 2; ++n) _Pragma("unroll") for (int k = 0; k < 2; ++k) dst[n][k] = *(const LAS bf16x8*)(lds + PG8_SB(b, h) + boff + n * 2048 + k * 1024); } while (0)
; #define PG8_WAIT_V(n) asm volatile("s_waitcnt vmcnt(" #n ")" ::: "memory")
; #define PG8_WAIT_L(n) asm volatile("s_waitcnt lgkmcnt(" #n ")" ::: "memory")
; #define PG8_BAR __builtin_amdgcn_s_barrier()
; #define PG8_SCHED __builtin_amdgcn_sched_barrier(0)
; template <class Epi, class Sched>
; __device__ __forceinline__ void gemm_phase(const int tid, LAS unsigned char* lds, const int lda, const int ldb, const int K, const Sched& S, const Epi& E) {
;     ...
;             const bool last = (t == nt - 2);
;             const char* a1 = cA + (size_t)(t + 1) * kstep;
;             const char* a2 = last ? nA : cA + (size_t)(t + 2) * kstep; const char* b2 = last ? nB : cB + (size_t)(t + 2) * kstep;
;             const char* a3 = a2 + kstep; const char* b3 = b2 + kstep;
;             PG8_LDB(B0, 0, 0); PG8_LDB(B1, 0, 1); PG8_SCHED; PG8_LDA(At, 0, 0); PG8_STAGE(PG8_SA(1, 1), a1 + hstepA, voffA);
;             PG8_WAIT_V(8); PG8_WAIT_L(0); PG8_BAR; PG8_MMA(0, 0, At, B0); PG8_MMA(0, 1, At, B1); PG8_BAR; PG8_SCHED;
;             PG8_LDA(At, 0, 1); PG8_STAGE(PG8_SB(0, 0), b2, voffB); PG8_STAGE(PG8_SB(0, 1), b2 + hstepB, voffB); PG8_STAGE(PG8_SA(0, 0), a2, voffA);
;             PG8_WAIT_V(8); PG8_WAIT_L(0); PG8_BAR; if (!cur.half) { PG8_MMA(1, 0, At, B0); PG8_MMA(1, 1, At, B1); } PG8_BAR; PG8_SCHED;
; __device__ __forceinline__ void acc_zero(f32x4 (&acc)[2][2][4][2]) {
; #pragma unroll
;     for (int a = 0; a < 2; ++a)
; #pragma unroll
;         for (int b = 0; b < 2; ++b)
; #pragma unroll
;             for (int m = 0; m < 4; ++m)
; #pragma unroll
;                 for (int n = 0; n < 2; ++n) acc[a][b][m][n] = (f32x4){0.f, 0.f, 0.f, 0.f};
; }
.LBB0_752:
	s_andn2_b64 vcc, exec, s[52:53]
	s_cbranch_vccnz .LBB0_755
	s_add_u32 s64, s64, 0x40080
	s_addc_u32 s65, s65, 0
	s_add_u32 s26, s66, 0x100
	s_addc_u32 s27, s67, 0
	s_mov_b32 s57, 0
	s_waitcnt lgkmcnt(0)
	s_add_i32 vcc_lo, s57, 2
	s_add_u32 s14, s64, 0xfffc0080
	s_addc_u32 s15, s65, -1
	s_add_i32 s24, 0, 0x10000
	s_cmp_eq_u32 s75, s57
	s_cselect_b32 s69, s3, s15
	s_cselect_b32 s68, s2, s14
	s_cselect_b32 s67, s63, s27
	s_cselect_b32 s66, s62, s26
	s_add_i32 s14, 0, 0x14000
	v_add_u32_e32 v140, s24, v182
	v_add_u32_e32 v166, s14, v182
	ds_read_b128 v[128:131], v140
	ds_read_b128 v[132:135], v140 offset:1024
	ds_read_b128 v[136:139], v140 offset:2048
	ds_read_b128 v[140:143], v140 offset:3072
	ds_read_b128 v[144:147], v166
	ds_read_b128 v[148:151], v166 offset:1024
	ds_read_b128 v[190:193], v166 offset:2048
	ds_read_b128 v[194:197], v166 offset:3072
	v_lshl_add_u64 v[166:167], s[64:65], 0, v[162:163]
	s_add_i32 m0, s31, 0xc000
	ds_read_b128 v[206:209], v188
	ds_read_b128 v[210:213], v188 offset:1024
	ds_read_b128 v[214:217], v188 offset:2048
	ds_read_b128 v[218:221], v188 offset:3072
	ds_read_b128 v[222:225], v188 offset:4096
	ds_read_b128 v[226:229], v188 offset:5120
	ds_read_b128 v[230:233], v188 offset:6144
	ds_read_b128 v[234:237], v188 offset:7168
	global_load_lds_dwordx4 v[166:167], off
	v_lshl_add_u64 v[166:167], s[64:65], 0, v[164:165]
	s_add_i32 m0, s31, 0xe000
	s_nop 0
	global_load_lds_dwordx4 v[166:167], off
	s_waitcnt vmcnt(8)
	s_waitcnt lgkmcnt(0)
	s_barrier
	s_setprio 1
	s_waitcnt lgkmcnt(0)
	v_mfma_f32_16x16x32_bf16 v[116:119], v[128:131], v[206:209], 0
	v_mfma_f32_16x16x32_bf16 v[112:115], v[136:139], v[206:209], 0
	v_mfma_f32_16x16x32_bf16 v[100:103], v[128:131], v[214:217], 0
	v_mfma_f32_16x16x32_bf16 v[96:99], v[136:139], v[214:217], 0
	v_mfma_f32_16x16x32_bf16 v[84:87], v[128:131], v[222:225], 0
	v_mfma_f32_16x16x32_bf16 v[80:83], v[136:139], v[222:225], 0
	v_mfma_f32_16x16x32_bf16 v[68:71], v[128:131], v[230:233], 0
	v_mfma_f32_16x16x32_bf16 v[64:67], v[136:139], v[230:233], 0
	v_mfma_f32_16x16x32_bf16 v[116:119], v[132:135], v[210:213], v[116:119]
	v_mfma_f32_16x16x32_bf16 v[112:115], v[140:143], v[210:213], v[112:115]
	v_mfma_f32_16x16x32_bf16 v[100:103], v[132:135], v[218:221], v[100:103]
	v_mfma_f32_16x16x32_bf16 v[96:99], v[140:143], v[218:221], v[96:99]
	v_mfma_f32_16x16x32_bf16 v[84:87], v[132:135], v[226:229], v[84:87]
	v_mfma_f32_16x16x32_bf16 v[80:83], v[140:143], v[226:229], v[80:83]
	v_mfma_f32_16x16x32_bf16 v[68:71], v[132:135], v[234:237], v[68:71]
	v_mfma_f32_16x16x32_bf16 v[64:67], v[140:143], v[234:237], v[64:67]
	s_setprio 0
	s_setprio 1
	v_mfma_f32_16x16x32_bf16 v[124:127], v[144:147], v[206:209], 0
	v_mfma_f32_16x16x32_bf16 v[120:123], v[190:193], v[206:209], 0
	v_mfma_f32_16x16x32_bf16 v[108:111], v[144:147], v[214:217], 0
	v_mfma_f32_16x16x32_bf16 v[104:107], v[190:193], v[214:217], 0
	v_mfma_f32_16x16x32_bf16 v[92:95], v[144:147], v[222:225], 0
	v_mfma_f32_16x16x32_bf16 v[88:91], v[190:193], v[222:225], 0
	v_mfma_f32_16x16x32_bf16 v[76:79], v[144:147], v[230:233], 0
	v_mfma_f32_16x16x32_bf16 v[72:75], v[190:193], v[230:233], 0
	v_mfma_f32_16x16x32_bf16 v[124:127], v[148:151], v[210:213], v[124:127]
	v_mfma_f32_16x16x32_bf16 v[120:123], v[194:197], v[210:213], v[120:123]
	v_mfma_f32_16x16x32_bf16 v[108:111], v[148:151], v[218:221], v[108:111]
	v_mfma_f32_16x16x32_bf16 v[104:107], v[194:197], v[218:221], v[104:107]
	v_mfma_f32_16x16x32_bf16 v[92:95], v[148:151], v[226:229], v[92:95]
	v_mfma_f32_16x16x32_bf16 v[88:91], v[194:197], v[226:229], v[88:91]
	v_mfma_f32_16x16x32_bf16 v[76:79], v[148:151], v[234:237], v[76:79]
	v_mfma_f32_16x16x32_bf16 v[72:75], v[194:197], v[234:237], v[72:75]
	s_setprio 0
	s_barrier
	s_add_i32 s15, s24, s29
	v_lshl_add_u64 v[166:167], s[66:67], 0, v[168:169]
	s_mov_b32 m0, s15
	ds_read_b128 v[206:209], v188 offset:16384
	ds_read_b128 v[210:213], v188 offset:17408
	ds_read_b128 v[214:217], v188 offset:18432
	ds_read_b128 v[218:221], v188 offset:19456
	ds_read_b128 v[222:225], v188 offset:20480
	ds_read_b128 v[226:229], v188 offset:21504
	ds_read_b128 v[230:233], v188 offset:22528
	ds_read_b128 v[234:237], v188 offset:23552
	global_load_lds_dwordx4 v[166:167], off
	s_add_i32 m0, s15, 0x2000
	s_add_u32 s50, s66, 0x40000
	v_lshl_add_u64 v[180:181], s[66:67], 0, v[156:157]
	s_addc_u32 s51, s67, 0
	s_add_i32 s14, s14, s29
	global_load_lds_dwordx4 v[180:181], off
	v_lshl_add_u64 v[238:239], s[50:51], 0, v[168:169]
	s_mov_b32 m0, s14
	v_lshl_add_u64 v[240:241], s[68:69], 0, v[154:155]
	global_load_lds_dwordx4 v[238:239], off
	v_lshl_add_u64 v[238:239], s[50:51], 0, v[156:157]
	s_add_i32 m0, s14, 0x2000
	s_nop 0
	global_load_lds_dwordx4 v[238:239], off
	v_lshl_add_u64 v[238:239], s[68:69], 0, v[152:153]
	s_mov_b32 m0, s31
	s_nop 0
	global_load_lds_dwordx4 v[238:239], off
	s_mov_b32 m0, s41
	s_nop 0
	global_load_lds_dwordx4 v[240:241], off
	s_waitcnt vmcnt(8)
	s_waitcnt lgkmcnt(0)
	s_barrier
; #define PG8_STAGE(bufoff, gbase, voff) do { _Pragma("unroll") for (int _i = 0; _i < 2; ++_i) \
;         __builtin_amdgcn_global_load_lds((const unsigned*)((const char*)(gbase) + (voff)[_i]), (LAS unsigned*)(lds + (bufoff) + ldsw + _i * 8192), 16, 0, 0); } while (0)
; #define PG8_LDA(dst, b, h) do { _Pragma("unroll") for (int m = 0; m < 4; ++m) _Pragma("unroll") for (int k = 0; k < 2; ++k) dst[m][k] = *(const LAS bf16x8*)(lds + PG8_SA(b, h) + aoff + m * 2048 + k * 1024); } while (0)
; #define PG8_LDB(dst, b, h) do { _Pragma("unroll") for (int n = 0; n < 2; ++n) _Pragma("unroll") for (int k = 0; k < 2; ++k) dst[n][k] = *(const LAS bf16x8*)(lds + PG8_SB(b, h) + boff + n * 2048 + k * 1024); } while (0)
; #define PG8_MMA(ai, bj, At, Bt) do { __builtin_amdgcn_s_setprio(1); _Pragma("unroll") for (int m = 0; m < 4; ++m) _Pragma("unroll") for (int n = 0; n < 2; ++n) _Pragma("unroll") for (int k = 0; k < 2; ++k) \
;         acc[ai][bj][m][n] = __builtin_amdgcn_mfma_f32_16x16x32_bf16(Bt[n][k], At[m][k], acc[ai][bj][m][n], 0, 0, 0); __builtin_amdgcn_s_setprio(0); } while (0)
; #define PG8_WAIT_V(n) asm volatile("s_waitcnt vmcnt(" #n ")" ::: "memory")
; #define PG8_WAIT_L(n) asm volatile("s_waitcnt lgkmcnt(" #n ")" ::: "memory")
; #define PG8_BAR __builtin_amdgcn_s_barrier()
; #define PG8_SCHED __builtin_amdgcn_sched_barrier(0)
; template <class Epi, class Sched>
; __device__ __forceinline__ void gemm_phase(const int tid, LAS unsigned char* lds, const int lda, const int ldb, const int K, const Sched& S, const Epi& E) {
;     ...
;             PG8_WAIT_V(8); PG8_WAIT_L(0); PG8_BAR; if (!cur.half) { PG8_MMA(1, 0, At, B0); PG8_MMA(1, 1, At, B1); } PG8_BAR; PG8_SCHED;
;             PG8_LDB(B0, 1, 0); PG8_LDB(B1, 1, 1); PG8_SCHED; PG8_LDA(At, 1, 0); PG8_STAGE(PG8_SA(0, 1), a2 + hstepA, voffA);
;             PG8_WAIT_V(8); PG8_WAIT_L(0); PG8_BAR; PG8_MMA(0, 0, At, B0); PG8_MMA(0, 1, At, B1); PG8_BAR; PG8_SCHED;
	s_setprio 1
	s_waitcnt lgkmcnt(0)
	v_mfma_f32_16x16x32_bf16 v[52:55], v[128:131], v[206:209], 0
	v_mfma_f32_16x16x32_bf16 v[48:51], v[136:139], v[206:209], 0
	v_mfma_f32_16x16x32_bf16 v[36:39], v[128:131], v[214:217], 0
	v_mfma_f32_16x16x32_bf16 v[32:35], v[136:139], v[214:217], 0
	v_mfma_f32_16x16x32_bf16 v[20:23], v[128:131], v[222:225], 0
	v_mfma_f32_16x16x32_bf16 v[16:19], v[136:139], v[222:225], 0
	v_mfma_f32_16x16x32_bf16 v[4:7], v[128:131], v[230:233], 0
	v_mfma_f32_16x16x32_bf16 v[0:3], v[136:139], v[230:233], 0
	v_mfma_f32_16x16x32_bf16 v[52:55], v[132:135], v[210:213], v[52:55]
	v_mfma_f32_16x16x32_bf16 v[48:51], v[140:143], v[210:213], v[48:51]
	v_mfma_f32_16x16x32_bf16 v[36:39], v[132:135], v[218:221], v[36:39]
	v_mfma_f32_16x16x32_bf16 v[32:35], v[140:143], v[218:221], v[32:35]
	v_mfma_f32_16x16x32_bf16 v[20:23], v[132:135], v[226:229], v[20:23]
	v_mfma_f32_16x16x32_bf16 v[16:19], v[140:143], v[226:229], v[16:19]
	v_mfma_f32_16x16x32_bf16 v[4:7], v[132:135], v[234:237], v[4:7]
	v_mfma_f32_16x16x32_bf16 v[0:3], v[140:143], v[234:237], v[0:3]
	s_setprio 0
	s_setprio 1
	v_mfma_f32_16x16x32_bf16 v[60:63], v[144:147], v[206:209], 0
	v_mfma_f32_16x16x32_bf16 v[56:59], v[190:193], v[206:209], 0
	v_mfma_f32_16x16x32_bf16 v[44:47], v[144:147], v[214:217], 0
	v_mfma_f32_16x16x32_bf16 v[40:43], v[190:193], v[214:217], 0
	v_mfma_f32_16x16x32_bf16 v[28:31], v[144:147], v[222:225], 0
	v_mfma_f32_16x16x32_bf16 v[24:27], v[190:193], v[222:225], 0
	v_mfma_f32_16x16x32_bf16 v[12:15], v[144:147], v[230:233], 0
	v_mfma_f32_16x16x32_bf16 v[8:11], v[190:193], v[230:233], 0
	v_mfma_f32_16x16x32_bf16 v[60:63], v[148:151], v[210:213], v[60:63]
	v_mfma_f32_16x16x32_bf16 v[56:59], v[194:197], v[210:213], v[56:59]
	v_mfma_f32_16x16x32_bf16 v[44:47], v[148:151], v[218:221], v[44:47]
	v_mfma_f32_16x16x32_bf16 v[40:43], v[194:197], v[218:221], v[40:43]
	v_mfma_f32_16x16x32_bf16 v[28:31], v[148:151], v[226:229], v[28:31]
	v_mfma_f32_16x16x32_bf16 v[24:27], v[194:197], v[226:229], v[24:27]
	v_mfma_f32_16x16x32_bf16 v[12:15], v[148:151], v[234:237], v[12:15]
	v_mfma_f32_16x16x32_bf16 v[8:11], v[194:197], v[234:237], v[8:11]
	s_setprio 0
	s_barrier
	s_add_i32 s14, 0, 0x18000
	s_add_i32 s15, 0, 0x1c000
	v_add_u32_e32 v140, s14, v182
	v_add_u32_e32 v176, s15, v182
	ds_read_b128 v[128:131], v140
	ds_read_b128 v[132:135], v140 offset:1024
	ds_read_b128 v[136:139], v140 offset:2048
	ds_read_b128 v[140:143], v140 offset:3072
	ds_read_b128 v[144:147], v176
	ds_read_b128 v[148:151], v176 offset:1024
	ds_read_b128 v[190:193], v176 offset:2048
	ds_read_b128 v[194:197], v176 offset:3072
	s_add_u32 s50, s68, 0x40000
	s_addc_u32 s51, s69, 0
	s_mov_b32 m0, s47
	v_lshl_add_u64 v[242:243], s[50:51], 0, v[152:153]
	ds_read_b128 v[206:209], v188 offset:32768
	ds_read_b128 v[210:213], v188 offset:33792
	ds_read_b128 v[214:217], v188 offset:34816
	ds_read_b128 v[218:221], v188 offset:35840
	ds_read_b128 v[222:225], v188 offset:36864
	ds_read_b128 v[226:229], v188 offset:37888
	ds_read_b128 v[230:233], v188 offset:38912
	ds_read_b128 v[234:237], v188 offset:39936
	global_load_lds_dwordx4 v[242:243], off
	v_lshl_add_u64 v[242:243], s[50:51], 0, v[154:155]
	s_mov_b32 m0, s70
	s_nop 0
	global_load_lds_dwordx4 v[242:243], off
	s_waitcnt vmcnt(8)
	s_waitcnt lgkmcnt(0)
	s_barrier
	s_setprio 1
	s_waitcnt lgkmcnt(0)
	v_mfma_f32_16x16x32_bf16 v[116:119], v[128:131], v[206:209], v[116:119]
	v_mfma_f32_16x16x32_bf16 v[112:115], v[136:139], v[206:209], v[112:115]
	v_mfma_f32_16x16x32_bf16 v[100:103], v[128:131], v[214:217], v[100:103]
	v_mfma_f32_16x16x32_bf16 v[96:99], v[136:139], v[214:217], v[96:99]
	v_mfma_f32_16x16x32_bf16 v[84:87], v[128:131], v[222:225], v[84:87]
	v_mfma_f32_16x16x32_bf16 v[80:83], v[136:139], v[222:225], v[80:83]
	v_mfma_f32_16x16x32_bf16 v[68:71], v[128:131], v[230:233], v[68:71]
	v_mfma_f32_16x16x32_bf16 v[64:67], v[136:139], v[230:233], v[64:67]
	v_mfma_f32_16x16x32_bf16 v[116:119], v[132:135], v[210:213], v[116:119]
	v_mfma_f32_16x16x32_bf16 v[112:115], v[140:143], v[210:213], v[112:115]
	v_mfma_f32_16x16x32_bf16 v[100:103], v[132:135], v[218:221], v[100:103]
	v_mfma_f32_16x16x32_bf16 v[96:99], v[140:143], v[218:221], v[96:99]
	v_mfma_f32_16x16x32_bf16 v[84:87], v[132:135], v[226:229], v[84:87]
	v_mfma_f32_16x16x32_bf16 v[80:83], v[140:143], v[226:229], v[80:83]
	v_mfma_f32_16x16x32_bf16 v[68:71], v[132:135], v[234:237], v[68:71]
	v_mfma_f32_16x16x32_bf16 v[64:67], v[140:143], v[234:237], v[64:67]
	s_setprio 0
	s_setprio 1
	v_mfma_f32_16x16x32_bf16 v[124:127], v[144:147], v[206:209], v[124:127]
	v_mfma_f32_16x16x32_bf16 v[120:123], v[190:193], v[206:209], v[120:123]
	v_mfma_f32_16x16x32_bf16 v[108:111], v[144:147], v[214:217], v[108:111]
	v_mfma_f32_16x16x32_bf16 v[104:107], v[190:193], v[214:217], v[104:107]
	v_mfma_f32_16x16x32_bf16 v[92:95], v[144:147], v[222:225], v[92:95]
	v_mfma_f32_16x16x32_bf16 v[88:91], v[190:193], v[222:225], v[88:91]
	v_mfma_f32_16x16x32_bf16 v[76:79], v[144:147], v[230:233], v[76:79]
	v_mfma_f32_16x16x32_bf16 v[72:75], v[190:193], v[230:233], v[72:75]
	v_mfma_f32_16x16x32_bf16 v[124:127], v[148:151], v[210:213], v[124:127]
	v_mfma_f32_16x16x32_bf16 v[120:123], v[194:197], v[210:213], v[120:123]
	v_mfma_f32_16x16x32_bf16 v[108:111], v[148:151], v[218:221], v[108:111]
	v_mfma_f32_16x16x32_bf16 v[104:107], v[194:197], v[218:221], v[104:107]
	v_mfma_f32_16x16x32_bf16 v[92:95], v[148:151], v[226:229], v[92:95]
	v_mfma_f32_16x16x32_bf16 v[88:91], v[194:197], v[226:229], v[88:91]
	v_mfma_f32_16x16x32_bf16 v[76:79], v[148:151], v[234:237], v[76:79]
	v_mfma_f32_16x16x32_bf16 v[72:75], v[194:197], v[234:237], v[72:75]
	s_setprio 0
	s_barrier
; #define PG8_STAGE(bufoff, gbase, voff) do { _Pragma("unroll") for (int _i = 0; _i < 2; ++_i) \
;         __builtin_amdgcn_global_load_lds((const unsigned*)((const char*)(gbase) + (voff)[_i]), (LAS unsigned*)(lds + (bufoff) + ldsw + _i * 8192), 16, 0, 0); } while (0)
; #define PG8_LDA(dst, b, h) do { _Pragma("unroll") for (int m = 0; m < 4; ++m) _Pragma("unroll") for (int k = 0; k < 2; ++k) dst[m][k] = *(const LAS bf16x8*)(lds + PG8_SA(b, h) + aoff + m * 2048 + k * 1024); } while (0)
; #define PG8_LDB(dst, b, h) do { _Pragma("unroll") for (int n = 0; n < 2; ++n) _Pragma("unroll") for (int k = 0; k < 2; ++k) dst[n][k] = *(const LAS bf16x8*)(lds + PG8_SB(b, h) + boff + n * 2048 + k * 1024); } while (0)
; #define PG8_MMA(ai, bj, At, Bt) do { __builtin_amdgcn_s_setprio(1); _Pragma("unroll") for (int m = 0; m < 4; ++m) _Pragma("unroll") for (int n = 0; n < 2; ++n) _Pragma("unroll") for (int k = 0; k < 2; ++k) \
;         acc[ai][bj][m][n] = __builtin_amdgcn_mfma_f32_16x16x32_bf16(Bt[n][k], At[m][k], acc[ai][bj][m][n], 0, 0, 0); __builtin_amdgcn_s_setprio(0); } while (0)
; #define PG8_WAIT_V(n) asm volatile("s_waitcnt vmcnt(" #n ")" ::: "memory")
; #define PG8_WAIT_L(n) asm volatile("s_waitcnt lgkmcnt(" #n ")" ::: "memory")
; #define PG8_BAR __builtin_amdgcn_s_barrier()
; #define PG8_SCHED __builtin_amdgcn_sched_barrier(0)
; template <class Epi, class Sched>
; __device__ __forceinline__ void gemm_phase(const int tid, LAS unsigned char* lds, const int lda, const int ldb, const int K, const Sched& S, const Epi& E) {
;     ...
;         for (int t = 0; t < nt; t += 2) {
;             const bool last = (t == nt - 2);
;             const char* a1 = cA + (size_t)(t + 1) * kstep;
;             const char* a2 = last ? nA : cA + (size_t)(t + 2) * kstep; const char* b2 = last ? nB : cB + (size_t)(t + 2) * kstep;
;             const char* a3 = a2 + kstep; const char* b3 = b2 + kstep;
;             PG8_LDB(B0, 0, 0); PG8_LDB(B1, 0, 1); PG8_SCHED; PG8_LDA(At, 0, 0); PG8_STAGE(PG8_SA(1, 1), a1 + hstepA, voffA);
;     ...
;             PG8_LDA(At, 1, 1); PG8_STAGE(PG8_SB(1, 0), b3, voffB); PG8_STAGE(PG8_SB(1, 1), b3 + hstepB, voffB); PG8_STAGE(PG8_SA(1, 0), a3, voffA);
;             PG8_WAIT_V(8); PG8_WAIT_L(0); PG8_BAR; if (!cur.half) { PG8_MMA(1, 0, At, B0); PG8_MMA(1, 1, At, B1); } PG8_BAR; PG8_SCHED;
	s_add_i32 s14, s14, s29
	v_lshl_add_u64 v[166:167], v[166:167], 0, s[6:7]
	s_mov_b32 m0, s14
	ds_read_b128 v[206:209], v188 offset:49152
	ds_read_b128 v[210:213], v188 offset:50176
	ds_read_b128 v[214:217], v188 offset:51200
	ds_read_b128 v[218:221], v188 offset:52224
	ds_read_b128 v[222:225], v188 offset:53248
	ds_read_b128 v[226:229], v188 offset:54272
	ds_read_b128 v[230:233], v188 offset:55296
	ds_read_b128 v[234:237], v188 offset:56320
	global_load_lds_dwordx4 v[166:167], off
	s_add_i32 m0, s14, 0x2000
	s_add_u32 s50, s66, 0x40080
	v_lshl_add_u64 v[166:167], v[180:181], 0, s[6:7]
	s_addc_u32 s51, s67, 0
	s_add_i32 s14, s15, s29
	global_load_lds_dwordx4 v[166:167], off
	v_lshl_add_u64 v[166:167], s[50:51], 0, v[168:169]
	s_mov_b32 m0, s14
	s_nop 0
	global_load_lds_dwordx4 v[166:167], off
	v_lshl_add_u64 v[166:167], s[50:51], 0, v[156:157]
	s_add_i32 m0, s14, 0x2000
	s_nop 0
	global_load_lds_dwordx4 v[166:167], off
	v_lshl_add_u64 v[166:167], v[238:239], 0, s[6:7]
	s_mov_b32 m0, s72
	s_nop 0
	global_load_lds_dwordx4 v[166:167], off
	v_lshl_add_u64 v[166:167], v[240:241], 0, s[6:7]
	s_mov_b32 m0, s73
	s_nop 0
	global_load_lds_dwordx4 v[166:167], off
	s_waitcnt vmcnt(8)
	s_waitcnt lgkmcnt(0)
	s_barrier
	s_setprio 1
	s_waitcnt lgkmcnt(0)
	v_mfma_f32_16x16x32_bf16 v[52:55], v[128:131], v[206:209], v[52:55]
	v_mfma_f32_16x16x32_bf16 v[48:51], v[136:139], v[206:209], v[48:51]
	v_mfma_f32_16x16x32_bf16 v[36:39], v[128:131], v[214:217], v[36:39]
	v_mfma_f32_16x16x32_bf16 v[32:35], v[136:139], v[214:217], v[32:35]
	v_mfma_f32_16x16x32_bf16 v[20:23], v[128:131], v[222:225], v[20:23]
	v_mfma_f32_16x16x32_bf16 v[16:19], v[136:139], v[222:225], v[16:19]
	v_mfma_f32_16x16x32_bf16 v[4:7], v[128:131], v[230:233], v[4:7]
	v_mfma_f32_16x16x32_bf16 v[0:3], v[136:139], v[230:233], v[0:3]
	v_mfma_f32_16x16x32_bf16 v[52:55], v[132:135], v[210:213], v[52:55]
	v_mfma_f32_16x16x32_bf16 v[48:51], v[140:143], v[210:213], v[48:51]
	v_mfma_f32_16x16x32_bf16 v[36:39], v[132:135], v[218:221], v[36:39]
	v_mfma_f32_16x16x32_bf16 v[32:35], v[140:143], v[218:221], v[32:35]
	v_mfma_f32_16x16x32_bf16 v[20:23], v[132:135], v[226:229], v[20:23]
	v_mfma_f32_16x16x32_bf16 v[16:19], v[140:143], v[226:229], v[16:19]
	v_mfma_f32_16x16x32_bf16 v[4:7], v[132:135], v[234:237], v[4:7]
	v_mfma_f32_16x16x32_bf16 v[0:3], v[140:143], v[234:237], v[0:3]
	s_setprio 0
	s_setprio 1
	v_mfma_f32_16x16x32_bf16 v[60:63], v[144:147], v[206:209], v[60:63]
	v_mfma_f32_16x16x32_bf16 v[56:59], v[190:193], v[206:209], v[56:59]
	v_mfma_f32_16x16x32_bf16 v[44:47], v[144:147], v[214:217], v[44:47]
	v_mfma_f32_16x16x32_bf16 v[40:43], v[190:193], v[214:217], v[40:43]
	v_mfma_f32_16x16x32_bf16 v[28:31], v[144:147], v[222:225], v[28:31]
	v_mfma_f32_16x16x32_bf16 v[24:27], v[190:193], v[222:225], v[24:27]
	v_mfma_f32_16x16x32_bf16 v[12:15], v[144:147], v[230:233], v[12:15]
	v_mfma_f32_16x16x32_bf16 v[8:11], v[190:193], v[230:233], v[8:11]
	v_mfma_f32_16x16x32_bf16 v[60:63], v[148:151], v[210:213], v[60:63]
	v_mfma_f32_16x16x32_bf16 v[56:59], v[194:197], v[210:213], v[56:59]
	v_mfma_f32_16x16x32_bf16 v[44:47], v[148:151], v[218:221], v[44:47]
	v_mfma_f32_16x16x32_bf16 v[40:43], v[194:197], v[218:221], v[40:43]
	v_mfma_f32_16x16x32_bf16 v[28:31], v[148:151], v[226:229], v[28:31]
	v_mfma_f32_16x16x32_bf16 v[24:27], v[194:197], v[226:229], v[24:27]
	v_mfma_f32_16x16x32_bf16 v[12:15], v[148:151], v[234:237], v[12:15]
	v_mfma_f32_16x16x32_bf16 v[8:11], v[194:197], v[234:237], v[8:11]
	s_setprio 0
	s_barrier
	s_add_u32 s64, s64, 0x100
	s_addc_u32 s65, s65, 0
	s_add_u32 s26, s26, 0x100
	s_addc_u32 s27, s27, 0
	s_cmp_ge_i32 vcc_lo, s21
	s_mov_b32 s57, vcc_lo
	s_cbranch_scc1 .Lkexit_754
.LBB0_754:
	s_add_i32 vcc_lo, s57, 2
	s_add_u32 s14, s64, 0xfffc0080
	s_addc_u32 s15, s65, -1
	s_add_i32 s24, 0, 0x10000
	s_cmp_eq_u32 s75, s57
	s_cselect_b32 s69, s3, s15
	s_cselect_b32 s68, s2, s14
	s_cselect_b32 s67, s63, s27
	s_cselect_b32 s66, s62, s26
	s_add_i32 s14, 0, 0x14000
	v_add_u32_e32 v140, s24, v182
	v_add_u32_e32 v166, s14, v182
	ds_read_b128 v[128:131], v140
	ds_read_b128 v[132:135], v140 offset:1024
	ds_read_b128 v[136:139], v140 offset:2048
	ds_read_b128 v[140:143], v140 offset:3072
	ds_read_b128 v[144:147], v166
	ds_read_b128 v[148:151], v166 offset:1024
	ds_read_b128 v[190:193], v166 offset:2048
	ds_read_b128 v[194:197], v166 offset:3072
	v_lshl_add_u64 v[166:167], s[64:65], 0, v[162:163]
	s_add_i32 m0, s31, 0xc000
	ds_read_b128 v[206:209], v188
	ds_read_b128 v[210:213], v188 offset:1024
	ds_read_b128 v[214:217], v188 offset:2048
	ds_read_b128 v[218:221], v188 offset:3072
	ds_read_b128 v[222:225], v188 offset:4096
	ds_read_b128 v[226:229], v188 offset:5120
	ds_read_b128 v[230:233], v188 offset:6144
	ds_read_b128 v[234:237], v188 offset:7168
	global_load_lds_dwordx4 v[166:167], off
	v_lshl_add_u64 v[166:167], s[64:65], 0, v[164:165]
	s_add_i32 m0, s31, 0xe000
	s_nop 0
	global_load_lds_dwordx4 v[166:167], off
	s_waitcnt vmcnt(8)
	s_waitcnt lgkmcnt(0)
	s_barrier
; #define PG8_STAGE(bufoff, gbase, voff) do { _Pragma("unroll") for (int _i = 0; _i < 2; ++_i) \
;         __builtin_amdgcn_global_load_lds((const unsigned*)((const char*)(gbase) + (voff)[_i]), (LAS unsigned*)(lds + (bufoff) + ldsw + _i * 8192), 16, 0, 0); } while (0)
; #define PG8_LDA(dst, b, h) do { _Pragma("unroll") for (int m = 0; m < 4; ++m) _Pragma("unroll") for (int k = 0; k < 2; ++k) dst[m][k] = *(const LAS bf16x8*)(lds + PG8_SA(b, h) + aoff + m * 2048 + k * 1024); } while (0)
; #define PG8_LDB(dst, b, h) do { _Pragma("unroll") for (int n = 0; n < 2; ++n) _Pragma("unroll") for (int k = 0; k < 2; ++k) dst[n][k] = *(const LAS bf16x8*)(lds + PG8_SB(b, h) + boff + n * 2048 + k * 1024); } while (0)
; #define PG8_MMA(ai, bj, At, Bt) do { __builtin_amdgcn_s_setprio(1); _Pragma("unroll") for (int m = 0; m < 4; ++m) _Pragma("unroll") for (int n = 0; n < 2; ++n) _Pragma("unroll") for (int k = 0; k < 2; ++k) \
;         acc[ai][bj][m][n] = __builtin_amdgcn_mfma_f32_16x16x32_bf16(Bt[n][k], At[m][k], acc[ai][bj][m][n], 0, 0, 0); __builtin_amdgcn_s_setprio(0); } while (0)
; #define PG8_WAIT_V(n) asm volatile("s_waitcnt vmcnt(" #n ")" ::: "memory")
; #define PG8_WAIT_L(n) asm volatile("s_waitcnt lgkmcnt(" #n ")" ::: "memory")
; #define PG8_BAR __builtin_amdgcn_s_barrier()
; #define PG8_SCHED __builtin_amdgcn_sched_barrier(0)
; template <class Epi, class Sched>
; __device__ __forceinline__ void gemm_phase(const int tid, LAS unsigned char* lds, const int lda, const int ldb, const int K, const Sched& S, const Epi& E) {
;     ...
;             PG8_LDB(B0, 0, 0); PG8_LDB(B1, 0, 1); PG8_SCHED; PG8_LDA(At, 0, 0); PG8_STAGE(PG8_SA(1, 1), a1 + hstepA, voffA);
;             PG8_WAIT_V(8); PG8_WAIT_L(0); PG8_BAR; PG8_MMA(0, 0, At, B0); PG8_MMA(0, 1, At, B1); PG8_BAR; PG8_SCHED;
;             PG8_LDA(At, 0, 1); PG8_STAGE(PG8_SB(0, 0), b2, voffB); PG8_STAGE(PG8_SB(0, 1), b2 + hstepB, voffB); PG8_STAGE(PG8_SA(0, 0), a2, voffA);
;             PG8_WAIT_V(8); PG8_WAIT_L(0); PG8_BAR; if (!cur.half) { PG8_MMA(1, 0, At, B0); PG8_MMA(1, 1, At, B1); } PG8_BAR; PG8_SCHED;
	s_setprio 1
	s_waitcnt lgkmcnt(0)
	v_mfma_f32_16x16x32_bf16 v[116:119], v[128:131], v[206:209], v[116:119]
	v_mfma_f32_16x16x32_bf16 v[112:115], v[136:139], v[206:209], v[112:115]
	v_mfma_f32_16x16x32_bf16 v[100:103], v[128:131], v[214:217], v[100:103]
	v_mfma_f32_16x16x32_bf16 v[96:99], v[136:139], v[214:217], v[96:99]
	v_mfma_f32_16x16x32_bf16 v[84:87], v[128:131], v[222:225], v[84:87]
	v_mfma_f32_16x16x32_bf16 v[80:83], v[136:139], v[222:225], v[80:83]
	v_mfma_f32_16x16x32_bf16 v[68:71], v[128:131], v[230:233], v[68:71]
	v_mfma_f32_16x16x32_bf16 v[64:67], v[136:139], v[230:233], v[64:67]
	v_mfma_f32_16x16x32_bf16 v[116:119], v[132:135], v[210:213], v[116:119]
	v_mfma_f32_16x16x32_bf16 v[112:115], v[140:143], v[210:213], v[112:115]
	v_mfma_f32_16x16x32_bf16 v[100:103], v[132:135], v[218:221], v[100:103]
	v_mfma_f32_16x16x32_bf16 v[96:99], v[140:143], v[218:221], v[96:99]
	v_mfma_f32_16x16x32_bf16 v[84:87], v[132:135], v[226:229], v[84:87]
	v_mfma_f32_16x16x32_bf16 v[80:83], v[140:143], v[226:229], v[80:83]
	v_mfma_f32_16x16x32_bf16 v[68:71], v[132:135], v[234:237], v[68:71]
	v_mfma_f32_16x16x32_bf16 v[64:67], v[140:143], v[234:237], v[64:67]
	s_setprio 0
	s_setprio 1
	v_mfma_f32_16x16x32_bf16 v[124:127], v[144:147], v[206:209], v[124:127]
	v_mfma_f32_16x16x32_bf16 v[120:123], v[190:193], v[206:209], v[120:123]
	v_mfma_f32_16x16x32_bf16 v[108:111], v[144:147], v[214:217], v[108:111]
	v_mfma_f32_16x16x32_bf16 v[104:107], v[190:193], v[214:217], v[104:107]
	v_mfma_f32_16x16x32_bf16 v[92:95], v[144:147], v[222:225], v[92:95]
	v_mfma_f32_16x16x32_bf16 v[88:91], v[190:193], v[222:225], v[88:91]
	v_mfma_f32_16x16x32_bf16 v[76:79], v[144:147], v[230:233], v[76:79]
	v_mfma_f32_16x16x32_bf16 v[72:75], v[190:193], v[230:233], v[72:75]
	v_mfma_f32_16x16x32_bf16 v[124:127], v[148:151], v[210:213], v[124:127]
	v_mfma_f32_16x16x32_bf16 v[120:123], v[194:197], v[210:213], v[120:123]
	v_mfma_f32_16x16x32_bf16 v[108:111], v[148:151], v[218:221], v[108:111]
	v_mfma_f32_16x16x32_bf16 v[104:107], v[194:197], v[218:221], v[104:107]
	v_mfma_f32_16x16x32_bf16 v[92:95], v[148:151], v[226:229], v[92:95]
	v_mfma_f32_16x16x32_bf16 v[88:91], v[194:197], v[226:229], v[88:91]
	v_mfma_f32_16x16x32_bf16 v[76:79], v[148:151], v[234:237], v[76:79]
	v_mfma_f32_16x16x32_bf16 v[72:75], v[194:197], v[234:237], v[72:75]
	s_setprio 0
	s_barrier
	s_add_i32 s15, s24, s29
	v_lshl_add_u64 v[166:167], s[66:67], 0, v[168:169]
	s_mov_b32 m0, s15
	ds_read_b128 v[206:209], v188 offset:16384
	ds_read_b128 v[210:213], v188 offset:17408
	ds_read_b128 v[214:217], v188 offset:18432
	ds_read_b128 v[218:221], v188 offset:19456
	ds_read_b128 v[222:225], v188 offset:20480
	ds_read_b128 v[226:229], v188 offset:21504
	ds_read_b128 v[230:233], v188 offset:22528
	ds_read_b128 v[234:237], v188 offset:23552
	global_load_lds_dwordx4 v[166:167], off
	s_add_i32 m0, s15, 0x2000
	s_add_u32 s50, s66, 0x40000
	v_lshl_add_u64 v[180:181], s[66:67], 0, v[156:157]
	s_addc_u32 s51, s67, 0
	s_add_i32 s14, s14, s29
	global_load_lds_dwordx4 v[180:181], off
	v_lshl_add_u64 v[238:239], s[50:51], 0, v[168:169]
	s_mov_b32 m0, s14
	v_lshl_add_u64 v[240:241], s[68:69], 0, v[154:155]
	global_load_lds_dwordx4 v[238:239], off
	v_lshl_add_u64 v[238:239], s[50:51], 0, v[156:157]
	s_add_i32 m0, s14, 0x2000
	s_nop 0
	global_load_lds_dwordx4 v[238:239], off
	v_lshl_add_u64 v[238:239], s[68:69], 0, v[152:153]
	s_mov_b32 m0, s31
	s_nop 0
	global_load_lds_dwordx4 v[238:239], off
	s_mov_b32 m0, s41
	s_nop 0
	global_load_lds_dwordx4 v[240:241], off
	s_waitcnt vmcnt(8)
	s_waitcnt lgkmcnt(0)
	s_barrier
	s_setprio 1
	s_waitcnt lgkmcnt(0)
	v_mfma_f32_16x16x32_bf16 v[52:55], v[128:131], v[206:209], v[52:55]
	v_mfma_f32_16x16x32_bf16 v[48:51], v[136:139], v[206:209], v[48:51]
	v_mfma_f32_16x16x32_bf16 v[36:39], v[128:131], v[214:217], v[36:39]
	v_mfma_f32_16x16x32_bf16 v[32:35], v[136:139], v[214:217], v[32:35]
	v_mfma_f32_16x16x32_bf16 v[20:23], v[128:131], v[222:225], v[20:23]
	v_mfma_f32_16x16x32_bf16 v[16:19], v[136:139], v[222:225], v[16:19]
	v_mfma_f32_16x16x32_bf16 v[4:7], v[128:131], v[230:233], v[4:7]
	v_mfma_f32_16x16x32_bf16 v[0:3], v[136:139], v[230:233], v[0:3]
	v_mfma_f32_16x16x32_bf16 v[52:55], v[132:135], v[210:213], v[52:55]
	v_mfma_f32_16x16x32_bf16 v[48:51], v[140:143], v[210:213], v[48:51]
	v_mfma_f32_16x16x32_bf16 v[36:39], v[132:135], v[218:221], v[36:39]
	v_mfma_f32_16x16x32_bf16 v[32:35], v[140:143], v[218:221], v[32:35]
	v_mfma_f32_16x16x32_bf16 v[20:23], v[132:135], v[226:229], v[20:23]
	v_mfma_f32_16x16x32_bf16 v[16:19], v[140:143], v[226:229], v[16:19]
	v_mfma_f32_16x16x32_bf16 v[4:7], v[132:135], v[234:237], v[4:7]
	v_mfma_f32_16x16x32_bf16 v[0:3], v[140:143], v[234:237], v[0:3]
	s_setprio 0
	s_setprio 1
	v_mfma_f32_16x16x32_bf16 v[60:63], v[144:147], v[206:209], v[60:63]
	v_mfma_f32_16x16x32_bf16 v[56:59], v[190:193], v[206:209], v[56:59]
	v_mfma_f32_16x16x32_bf16 v[44:47], v[144:147], v[214:217], v[44:47]
	v_mfma_f32_16x16x32_bf16 v[40:43], v[190:193], v[214:217], v[40:43]
	v_mfma_f32_16x16x32_bf16 v[28:31], v[144:147], v[222:225], v[28:31]
	v_mfma_f32_16x16x32_bf16 v[24:27], v[190:193], v[222:225], v[24:27]
	v_mfma_f32_16x16x32_bf16 v[12:15], v[144:147], v[230:233], v[12:15]
	v_mfma_f32_16x16x32_bf16 v[8:11], v[190:193], v[230:233], v[8:11]
	v_mfma_f32_16x16x32_bf16 v[60:63], v[148:151], v[210:213], v[60:63]
	v_mfma_f32_16x16x32_bf16 v[56:59], v[194:197], v[210:213], v[56:59]
	v_mfma_f32_16x16x32_bf16 v[44:47], v[148:151], v[218:221], v[44:47]
	v_mfma_f32_16x16x32_bf16 v[40:43], v[194:197], v[218:221], v[40:43]
	v_mfma_f32_16x16x32_bf16 v[28:31], v[148:151], v[226:229], v[28:31]
	v_mfma_f32_16x16x32_bf16 v[24:27], v[194:197], v[226:229], v[24:27]
	v_mfma_f32_16x16x32_bf16 v[12:15], v[148:151], v[234:237], v[12:15]
	v_mfma_f32_16x16x32_bf16 v[8:11], v[194:197], v[234:237], v[8:11]
	s_setprio 0
	s_barrier
; #define PG8_STAGE(bufoff, gbase, voff) do { _Pragma("unroll") for (int _i = 0; _i < 2; ++_i) \
;         __builtin_amdgcn_global_load_lds((const unsigned*)((const char*)(gbase) + (voff)[_i]), (LAS unsigned*)(lds + (bufoff) + ldsw + _i * 8192), 16, 0, 0); } while (0)
; #define PG8_LDA(dst, b, h) do { _Pragma("unroll") for (int m = 0; m < 4; ++m) _Pragma("unroll") for (int k = 0; k < 2; ++k) dst[m][k] = *(const LAS bf16x8*)(lds + PG8_SA(b, h) + aoff + m * 2048 + k * 1024); } while (0)
; #define PG8_LDB(dst, b, h) do { _Pragma("unroll") for (int n = 0; n < 2; ++n) _Pragma("unroll") for (int k = 0; k < 2; ++k) dst[n][k] = *(const LAS bf16x8*)(lds + PG8_SB(b, h) + boff + n * 2048 + k * 1024); } while (0)
; #define PG8_MMA(ai, bj, At, Bt) do { __builtin_amdgcn_s_setprio(1); _Pragma("unroll") for (int m = 0; m < 4; ++m) _Pragma("unroll") for (int n = 0; n < 2; ++n) _Pragma("unroll") for (int k = 0; k < 2; ++k) \
;         acc[ai][bj][m][n] = __builtin_amdgcn_mfma_f32_16x16x32_bf16(Bt[n][k], At[m][k], acc[ai][bj][m][n], 0, 0, 0); __builtin_amdgcn_s_setprio(0); } while (0)
; #define PG8_WAIT_V(n) asm volatile("s_waitcnt vmcnt(" #n ")" ::: "memory")
; #define PG8_WAIT_L(n) asm volatile("s_waitcnt lgkmcnt(" #n ")" ::: "memory")
; #define PG8_BAR __builtin_amdgcn_s_barrier()
; #define PG8_SCHED __builtin_amdgcn_sched_barrier(0)
; template <class Epi, class Sched>
; __device__ __forceinline__ void gemm_phase(const int tid, LAS unsigned char* lds, const int lda, const int ldb, const int K, const Sched& S, const Epi& E) {
;     ...
;             PG8_LDB(B0, 1, 0); PG8_LDB(B1, 1, 1); PG8_SCHED; PG8_LDA(At, 1, 0); PG8_STAGE(PG8_SA(0, 1), a2 + hstepA, voffA);
;             PG8_WAIT_V(8); PG8_WAIT_L(0); PG8_BAR; PG8_MMA(0, 0, At, B0); PG8_MMA(0, 1, At, B1); PG8_BAR; PG8_SCHED;
;             PG8_LDA(At, 1, 1); PG8_STAGE(PG8_SB(1, 0), b3, voffB); PG8_STAGE(PG8_SB(1, 1), b3 + hstepB, voffB); PG8_STAGE(PG8_SA(1, 0), a3, voffA);
	s_add_i32 s14, 0, 0x18000
	s_add_i32 s15, 0, 0x1c000
	v_add_u32_e32 v140, s14, v182
	v_add_u32_e32 v176, s15, v182
	ds_read_b128 v[128:131], v140
	ds_read_b128 v[132:135], v140 offset:1024
	ds_read_b128 v[136:139], v140 offset:2048
	ds_read_b128 v[140:143], v140 offset:3072
	ds_read_b128 v[144:147], v176
	ds_read_b128 v[148:151], v176 offset:1024
	ds_read_b128 v[190:193], v176 offset:2048
	ds_read_b128 v[194:197], v176 offset:3072
	s_add_u32 s50, s68, 0x40000
	s_addc_u32 s51, s69, 0
	s_mov_b32 m0, s47
	v_lshl_add_u64 v[242:243], s[50:51], 0, v[152:153]
	ds_read_b128 v[206:209], v188 offset:32768
	ds_read_b128 v[210:213], v188 offset:33792
	ds_read_b128 v[214:217], v188 offset:34816
	ds_read_b128 v[218:221], v188 offset:35840
	ds_read_b128 v[222:225], v188 offset:36864
	ds_read_b128 v[226:229], v188 offset:37888
	ds_read_b128 v[230:233], v188 offset:38912
	ds_read_b128 v[234:237], v188 offset:39936
	global_load_lds_dwordx4 v[242:243], off
	v_lshl_add_u64 v[242:243], s[50:51], 0, v[154:155]
	s_mov_b32 m0, s70
	s_nop 0
	global_load_lds_dwordx4 v[242:243], off
	s_waitcnt vmcnt(8)
	s_waitcnt lgkmcnt(0)
	s_barrier
	s_setprio 1
	s_waitcnt lgkmcnt(0)
	v_mfma_f32_16x16x32_bf16 v[116:119], v[128:131], v[206:209], v[116:119]
	v_mfma_f32_16x16x32_bf16 v[112:115], v[136:139], v[206:209], v[112:115]
	v_mfma_f32_16x16x32_bf16 v[100:103], v[128:131], v[214:217], v[100:103]
	v_mfma_f32_16x16x32_bf16 v[96:99], v[136:139], v[214:217], v[96:99]
	v_mfma_f32_16x16x32_bf16 v[84:87], v[128:131], v[222:225], v[84:87]
	v_mfma_f32_16x16x32_bf16 v[80:83], v[136:139], v[222:225], v[80:83]
	v_mfma_f32_16x16x32_bf16 v[68:71], v[128:131], v[230:233], v[68:71]
	v_mfma_f32_16x16x32_bf16 v[64:67], v[136:139], v[230:233], v[64:67]
	v_mfma_f32_16x16x32_bf16 v[116:119], v[132:135], v[210:213], v[116:119]
	v_mfma_f32_16x16x32_bf16 v[112:115], v[140:143], v[210:213], v[112:115]
	v_mfma_f32_16x16x32_bf16 v[100:103], v[132:135], v[218:221], v[100:103]
	v_mfma_f32_16x16x32_bf16 v[96:99], v[140:143], v[218:221], v[96:99]
	v_mfma_f32_16x16x32_bf16 v[84:87], v[132:135], v[226:229], v[84:87]
	v_mfma_f32_16x16x32_bf16 v[80:83], v[140:143], v[226:229], v[80:83]
	v_mfma_f32_16x16x32_bf16 v[68:71], v[132:135], v[234:237], v[68:71]
	v_mfma_f32_16x16x32_bf16 v[64:67], v[140:143], v[234:237], v[64:67]
	s_setprio 0
	s_setprio 1
	v_mfma_f32_16x16x32_bf16 v[124:127], v[144:147], v[206:209], v[124:127]
	v_mfma_f32_16x16x32_bf16 v[120:123], v[190:193], v[206:209], v[120:123]
	v_mfma_f32_16x16x32_bf16 v[108:111], v[144:147], v[214:217], v[108:111]
	v_mfma_f32_16x16x32_bf16 v[104:107], v[190:193], v[214:217], v[104:107]
	v_mfma_f32_16x16x32_bf16 v[92:95], v[144:147], v[222:225], v[92:95]
	v_mfma_f32_16x16x32_bf16 v[88:91], v[190:193], v[222:225], v[88:91]
	v_mfma_f32_16x16x32_bf16 v[76:79], v[144:147], v[230:233], v[76:79]
	v_mfma_f32_16x16x32_bf16 v[72:75], v[190:193], v[230:233], v[72:75]
	v_mfma_f32_16x16x32_bf16 v[124:127], v[148:151], v[210:213], v[124:127]
	v_mfma_f32_16x16x32_bf16 v[120:123], v[194:197], v[210:213], v[120:123]
	v_mfma_f32_16x16x32_bf16 v[108:111], v[148:151], v[218:221], v[108:111]
	v_mfma_f32_16x16x32_bf16 v[104:107], v[194:197], v[218:221], v[104:107]
	v_mfma_f32_16x16x32_bf16 v[92:95], v[148:151], v[226:229], v[92:95]
	v_mfma_f32_16x16x32_bf16 v[88:91], v[194:197], v[226:229], v[88:91]
	v_mfma_f32_16x16x32_bf16 v[76:79], v[148:151], v[234:237], v[76:79]
	v_mfma_f32_16x16x32_bf16 v[72:75], v[194:197], v[234:237], v[72:75]
	s_setprio 0
	s_barrier
	s_add_i32 s14, s14, s29
	v_lshl_add_u64 v[166:167], v[166:167], 0, s[6:7]
	s_mov_b32 m0, s14
	ds_read_b128 v[206:209], v188 offset:49152
	ds_read_b128 v[210:213], v188 offset:50176
	ds_read_b128 v[214:217], v188 offset:51200
	ds_read_b128 v[218:221], v188 offset:52224
	ds_read_b128 v[222:225], v188 offset:53248
	ds_read_b128 v[226:229], v188 offset:54272
	ds_read_b128 v[230:233], v188 offset:55296
	ds_read_b128 v[234:237], v188 offset:56320
	global_load_lds_dwordx4 v[166:167], off
	s_add_i32 m0, s14, 0x2000
	s_add_u32 s50, s66, 0x40080
	v_lshl_add_u64 v[166:167], v[180:181], 0, s[6:7]
	s_addc_u32 s51, s67, 0
	s_add_i32 s14, s15, s29
	global_load_lds_dwordx4 v[166:167], off
	v_lshl_add_u64 v[166:167], s[50:51], 0, v[168:169]
	s_mov_b32 m0, s14
	s_nop 0
	global_load_lds_dwordx4 v[166:167], off
	v_lshl_add_u64 v[166:167], s[50:51], 0, v[156:157]
	s_add_i32 m0, s14, 0x2000
	s_nop 0
	global_load_lds_dwordx4 v[166:167], off
	v_lshl_add_u64 v[166:167], v[238:239], 0, s[6:7]
	s_mov_b32 m0, s72
	s_nop 0
	global_load_lds_dwordx4 v[166:167], off
	v_lshl_add_u64 v[166:167], v[240:241], 0, s[6:7]
	s_mov_b32 m0, s73
	s_nop 0
	global_load_lds_dwordx4 v[166:167], off
	s_waitcnt vmcnt(8)
	s_waitcnt lgkmcnt(0)
	s_barrier
; #define PG8_MMA(ai, bj, At, Bt) do { __builtin_amdgcn_s_setprio(1); _Pragma("unroll") for (int m = 0; m < 4; ++m) _Pragma("unroll") for (int n = 0; n < 2; ++n) _Pragma("unroll") for (int k = 0; k < 2; ++k) \
;         acc[ai][bj][m][n] = __builtin_amdgcn_mfma_f32_16x16x32_bf16(Bt[n][k], At[m][k], acc[ai][bj][m][n], 0, 0, 0); __builtin_amdgcn_s_setprio(0); } while (0)
; #define PG8_WAIT_V(n) asm volatile("s_waitcnt vmcnt(" #n ")" ::: "memory")
; #define PG8_WAIT_L(n) asm volatile("s_waitcnt lgkmcnt(" #n ")" ::: "memory")
; #define PG8_BAR __builtin_amdgcn_s_barrier()
; #define PG8_SCHED __builtin_amdgcn_sched_barrier(0)
; template <class Epi, class Sched>
; __device__ __forceinline__ void gemm_phase(const int tid, LAS unsigned char* lds, const int lda, const int ldb, const int K, const Sched& S, const Epi& E) {
;     ...
;         for (int t = 0; t < nt; t += 2) {
;     ...
;             PG8_WAIT_V(8); PG8_WAIT_L(0); PG8_BAR; if (!cur.half) { PG8_MMA(1, 0, At, B0); PG8_MMA(1, 1, At, B1); } PG8_BAR; PG8_SCHED;
; __device__ __forceinline__ void acc_zero(f32x4 (&acc)[2][2][4][2]) {
; #pragma unroll
;     for (int a = 0; a < 2; ++a)
; #pragma unroll
;         for (int b = 0; b < 2; ++b)
; #pragma unroll
;             for (int m = 0; m < 4; ++m)
; #pragma unroll
;                 for (int n = 0; n < 2; ++n) acc[a][b][m][n] = (f32x4){0.f, 0.f, 0.f, 0.f};
; }
	s_setprio 1
	s_waitcnt lgkmcnt(0)
	v_mfma_f32_16x16x32_bf16 v[52:55], v[128:131], v[206:209], v[52:55]
	v_mfma_f32_16x16x32_bf16 v[48:51], v[136:139], v[206:209], v[48:51]
	v_mfma_f32_16x16x32_bf16 v[36:39], v[128:131], v[214:217], v[36:39]
	v_mfma_f32_16x16x32_bf16 v[32:35], v[136:139], v[214:217], v[32:35]
	v_mfma_f32_16x16x32_bf16 v[20:23], v[128:131], v[222:225], v[20:23]
	v_mfma_f32_16x16x32_bf16 v[16:19], v[136:139], v[222:225], v[16:19]
	v_mfma_f32_16x16x32_bf16 v[4:7], v[128:131], v[230:233], v[4:7]
	v_mfma_f32_16x16x32_bf16 v[0:3], v[136:139], v[230:233], v[0:3]
	v_mfma_f32_16x16x32_bf16 v[52:55], v[132:135], v[210:213], v[52:55]
	v_mfma_f32_16x16x32_bf16 v[48:51], v[140:143], v[210:213], v[48:51]
	v_mfma_f32_16x16x32_bf16 v[36:39], v[132:135], v[218:221], v[36:39]
	v_mfma_f32_16x16x32_bf16 v[32:35], v[140:143], v[218:221], v[32:35]
	v_mfma_f32_16x16x32_bf16 v[20:23], v[132:135], v[226:229], v[20:23]
	v_mfma_f32_16x16x32_bf16 v[16:19], v[140:143], v[226:229], v[16:19]
	v_mfma_f32_16x16x32_bf16 v[4:7], v[132:135], v[234:237], v[4:7]
	v_mfma_f32_16x16x32_bf16 v[0:3], v[140:143], v[234:237], v[0:3]
	s_setprio 0
	s_setprio 1
	v_mfma_f32_16x16x32_bf16 v[60:63], v[144:147], v[206:209], v[60:63]
	v_mfma_f32_16x16x32_bf16 v[56:59], v[190:193], v[206:209], v[56:59]
	v_mfma_f32_16x16x32_bf16 v[44:47], v[144:147], v[214:217], v[44:47]
	v_mfma_f32_16x16x32_bf16 v[40:43], v[190:193], v[214:217], v[40:43]
	v_mfma_f32_16x16x32_bf16 v[28:31], v[144:147], v[222:225], v[28:31]
	v_mfma_f32_16x16x32_bf16 v[24:27], v[190:193], v[222:225], v[24:27]
	v_mfma_f32_16x16x32_bf16 v[12:15], v[144:147], v[230:233], v[12:15]
	v_mfma_f32_16x16x32_bf16 v[8:11], v[190:193], v[230:233], v[8:11]
	v_mfma_f32_16x16x32_bf16 v[60:63], v[148:151], v[210:213], v[60:63]
	v_mfma_f32_16x16x32_bf16 v[56:59], v[194:197], v[210:213], v[56:59]
	v_mfma_f32_16x16x32_bf16 v[44:47], v[148:151], v[218:221], v[44:47]
	v_mfma_f32_16x16x32_bf16 v[40:43], v[194:197], v[218:221], v[40:43]
	v_mfma_f32_16x16x32_bf16 v[28:31], v[148:151], v[226:229], v[28:31]
	v_mfma_f32_16x16x32_bf16 v[24:27], v[194:197], v[226:229], v[24:27]
	v_mfma_f32_16x16x32_bf16 v[12:15], v[148:151], v[234:237], v[12:15]
	v_mfma_f32_16x16x32_bf16 v[8:11], v[194:197], v[234:237], v[8:11]
	s_setprio 0
	s_barrier
	s_add_u32 s64, s64, 0x100
	s_addc_u32 s65, s65, 0
	s_add_u32 s26, s26, 0x100
	s_addc_u32 s27, s27, 0
	s_cmp_ge_i32 vcc_lo, s21
	s_mov_b32 s57, vcc_lo
	s_cbranch_scc0 .LBB0_754
.Lkexit_754:
	s_branch .LBB0_756
.LBB0_755:
	v_mov_b32_e32 v119, 0
	v_mov_b32_e32 v118, v119
	v_mov_b32_e32 v117, v119
	v_mov_b32_e32 v116, v119
	v_mov_b32_e32 v115, v119
	v_mov_b32_e32 v114, v119
	v_mov_b32_e32 v113, v119
	v_mov_b32_e32 v112, v119
	v_mov_b32_e32 v103, v119
	v_mov_b32_e32 v102, v119
	v_mov_b32_e32 v101, v119
	v_mov_b32_e32 v100, v119
	v_mov_b32_e32 v99, v119
	v_mov_b32_e32 v98, v119
	v_mov_b32_e32 v97, v119
	v_mov_b32_e32 v96, v119
	v_mov_b32_e32 v87, v119
	v_mov_b32_e32 v86, v119
	v_mov_b32_e32 v85, v119
	v_mov_b32_e32 v84, v119
	v_mov_b32_e32 v83, v119
	v_mov_b32_e32 v82, v119
	v_mov_b32_e32 v81, v119
	v_mov_b32_e32 v80, v119
	v_mov_b32_e32 v71, v119
	v_mov_b32_e32 v70, v119
	v_mov_b32_e32 v69, v119
	v_mov_b32_e32 v68, v119
	v_mov_b32_e32 v67, v119
	v_mov_b32_e32 v66, v119
	v_mov_b32_e32 v65, v119
	v_mov_b32_e32 v64, v119
	v_mov_b32_e32 v127, v119
	v_mov_b32_e32 v126, v119
	v_mov_b32_e32 v125, v119
	v_mov_b32_e32 v124, v119
	v_mov_b32_e32 v123, v119
	v_mov_b32_e32 v122, v119
	v_mov_b32_e32 v121, v119
	v_mov_b32_e32 v120, v119
	v_mov_b32_e32 v111, v119
	v_mov_b32_e32 v110, v119
	v_mov_b32_e32 v109, v119
	v_mov_b32_e32 v108, v119
	v_mov_b32_e32 v107, v119
	v_mov_b32_e32 v106, v119
	v_mov_b32_e32 v105, v119
	v_mov_b32_e32 v104, v119
	v_mov_b32_e32 v95, v119
	v_mov_b32_e32 v94, v119
	v_mov_b32_e32 v93, v119
	v_mov_b32_e32 v92, v119
	v_mov_b32_e32 v91, v119
	v_mov_b32_e32 v90, v119
	v_mov_b32_e32 v89, v119
	v_mov_b32_e32 v88, v119
	v_mov_b32_e32 v79, v119
	v_mov_b32_e32 v78, v119
	v_mov_b32_e32 v77, v119
	v_mov_b32_e32 v76, v119
	v_mov_b32_e32 v75, v119
	v_mov_b32_e32 v74, v119
	v_mov_b32_e32 v73, v119
	v_mov_b32_e32 v72, v119
	v_mov_b32_e32 v55, v119
	v_mov_b32_e32 v54, v119
	v_mov_b32_e32 v53, v119
	v_mov_b32_e32 v52, v119
	v_mov_b32_e32 v51, v119
	v_mov_b32_e32 v50, v119
	v_mov_b32_e32 v49, v119
	v_mov_b32_e32 v48, v119
	v_mov_b32_e32 v39, v119
	v_mov_b32_e32 v38, v119
	v_mov_b32_e32 v37, v119
	v_mov_b32_e32 v36, v119
	v_mov_b32_e32 v35, v119
	v_mov_b32_e32 v34, v119
	v_mov_b32_e32 v33, v119
	v_mov_b32_e32 v32, v119
	v_mov_b32_e32 v23, v119
	v_mov_b32_e32 v22, v119
	v_mov_b32_e32 v21, v119
	v_mov_b32_e32 v20, v119
	v_mov_b32_e32 v19, v119
	v_mov_b32_e32 v18, v119
	v_mov_b32_e32 v17, v119
	v_mov_b32_e32 v16, v119
	v_mov_b32_e32 v7, v119
	v_mov_b32_e32 v6, v119
	v_mov_b32_e32 v5, v119
	v_mov_b32_e32 v4, v119
	v_mov_b32_e32 v3, v119
	v_mov_b32_e32 v2, v119
	s_waitcnt lgkmcnt(0)
	v_mov_b32_e32 v1, v119
	v_mov_b32_e32 v0, v119
	v_mov_b32_e32 v63, v119
	v_mov_b32_e32 v62, v119
	v_mov_b32_e32 v61, v119
	v_mov_b32_e32 v60, v119
	v_mov_b32_e32 v59, v119
	v_mov_b32_e32 v58, v119
	v_mov_b32_e32 v57, v119
	v_mov_b32_e32 v56, v119
	v_mov_b32_e32 v47, v119
	v_mov_b32_e32 v46, v119
	v_mov_b32_e32 v45, v119
	v_mov_b32_e32 v44, v119
	v_mov_b32_e32 v43, v119
	v_mov_b32_e32 v42, v119
	v_mov_b32_e32 v41, v119
	v_mov_b32_e32 v40, v119
	v_mov_b32_e32 v31, v119
	v_mov_b32_e32 v30, v119
	v_mov_b32_e32 v29, v119
	v_mov_b32_e32 v28, v119
	v_mov_b32_e32 v27, v119
	v_mov_b32_e32 v26, v119
	v_mov_b32_e32 v25, v119
	v_mov_b32_e32 v24, v119
	v_mov_b32_e32 v15, v119
	v_mov_b32_e32 v14, v119
	v_mov_b32_e32 v13, v119
	v_mov_b32_e32 v12, v119
	v_mov_b32_e32 v11, v119
	v_mov_b32_e32 v10, v119
	v_mov_b32_e32 v9, v119
	v_mov_b32_e32 v8, v119

; #define PG8_STAGE(bufoff, gbase, voff) do { _Pragma("unroll") for (int _i = 0; _i < 2; ++_i) \
;         __builtin_amdgcn_global_load_lds((const unsigned*)((const char*)(gbase) + (voff)[_i]), (LAS unsigned*)(lds + (bufoff) + ldsw + _i * 8192), 16, 0, 0); } while (0)
; #define PG8_LDA(dst, b, h) do { _Pragma("unroll") for (int m = 0; m < 4; ++m) _Pragma("unroll") for (int k = 0; k < 2; ++k) dst[m][k] = *(const LAS bf16x8*)(lds + PG8_SA(b, h) + aoff + m * 2048 + k * 1024); } while (0)
; #define PG8_LDB(dst, b, h) do { _Pragma("unroll") for (int n = 0; n < 2; ++n) _Pragma("unroll") for (int k = 0; k < 2; ++k) dst[n][k] = *(const LAS bf16x8*)(lds + PG8_SB(b, h) + boff + n * 2048 + k * 1024); } while (0)
; #define PG8_MMA(ai, bj, At, Bt) do { __builtin_amdgcn_s_setprio(1); _Pragma("unroll") for (int m = 0; m < 4; ++m) _Pragma("unroll") for (int n = 0; n < 2; ++n) _Pragma("unroll") for (int k = 0; k < 2; ++k) \
;         acc[ai][bj][m][n] = __builtin_amdgcn_mfma_f32_16x16x32_bf16(Bt[n][k], At[m][k], acc[ai][bj][m][n], 0, 0, 0); __builtin_amdgcn_s_setprio(0); } while (0)
; #define PG8_WAIT_V(n) asm volatile("s_waitcnt vmcnt(" #n ")" ::: "memory")
; #define PG8_WAIT_L(n) asm volatile("s_waitcnt lgkmcnt(" #n ")" ::: "memory")
; #define PG8_BAR __builtin_amdgcn_s_barrier()
; #define PG8_SCHED __builtin_amdgcn_sched_barrier(0)
; template <class Epi, class Sched>
; __device__ __forceinline__ void gemm_phase(const int tid, LAS unsigned char* lds, const int lda, const int ldb, const int K, const Sched& S, const Epi& E) {
;     ...
;             const bool last = (t == nt - 2);
;             const char* a1 = cA + (size_t)(t + 1) * kstep;
;             const char* a2 = last ? nA : cA + (size_t)(t + 2) * kstep; const char* b2 = last ? nB : cB + (size_t)(t + 2) * kstep;
;             const char* a3 = a2 + kstep; const char* b3 = b2 + kstep;
;             PG8_LDB(B0, 0, 0); PG8_LDB(B1, 0, 1); PG8_SCHED; PG8_LDA(At, 0, 0); PG8_STAGE(PG8_SA(1, 1), a1 + hstepA, voffA);
;             PG8_WAIT_V(8); PG8_WAIT_L(0); PG8_BAR; PG8_MMA(0, 0, At, B0); PG8_MMA(0, 1, At, B1); PG8_BAR; PG8_SCHED;
;             PG8_LDA(At, 0, 1); PG8_STAGE(PG8_SB(0, 0), b2, voffB); PG8_STAGE(PG8_SB(0, 1), b2 + hstepB, voffB); PG8_STAGE(PG8_SA(0, 0), a2, voffA);
;             PG8_WAIT_V(8); PG8_WAIT_L(0); PG8_BAR; if (!cur.half) { PG8_MMA(1, 0, At, B0); PG8_MMA(1, 1, At, B1); } PG8_BAR; PG8_SCHED;
.LBB0_791:
	s_andn2_b64 vcc, exec, s[50:51]
	s_cbranch_vccnz .LBB0_799
	s_add_u32 s26, s64, 0x100
	s_addc_u32 s27, s65, 0
	s_mov_b32 s42, 0
	s_add_i32 s43, s42, 2
	s_add_u32 s64, s62, 0x100
	s_addc_u32 s65, s63, 0
	s_add_i32 s14, 0, 0x10000
	s_cmp_eq_u32 s72, s42
	s_cselect_b32 s69, s3, s65
	s_cselect_b32 s68, s2, s64
	s_cselect_b32 s67, s61, s27
	s_cselect_b32 s66, s60, s26
	s_add_i32 s15, 0, 0x14000
	v_add_u32_e32 v124, s14, v206
	v_add_u32_e32 v156, s15, v206
	ds_read_b128 v[104:107], v124
	ds_read_b128 v[108:111], v124 offset:1024
	ds_read_b128 v[120:123], v124 offset:2048
	ds_read_b128 v[124:127], v124 offset:3072
	ds_read_b128 v[136:139], v156
	ds_read_b128 v[144:147], v156 offset:1024
	ds_read_b128 v[152:155], v156 offset:2048
	ds_read_b128 v[156:159], v156 offset:3072
	v_lshl_add_u64 v[196:197], s[62:63], 0, v[192:193]
	s_add_i32 m0, s23, 0xc000
	ds_read_b128 v[160:163], v211
	ds_read_b128 v[164:167], v211 offset:1024
	ds_read_b128 v[212:215], v211 offset:2048
	ds_read_b128 v[216:219], v211 offset:3072
	ds_read_b128 v[220:223], v211 offset:4096
	ds_read_b128 v[224:227], v211 offset:5120
	ds_read_b128 v[228:231], v211 offset:6144
	ds_read_b128 v[232:235], v211 offset:7168
	global_load_lds_dwordx4 v[196:197], off
	v_lshl_add_u64 v[196:197], s[62:63], 0, v[194:195]
	s_add_i32 m0, s23, 0xe000
	s_nop 0
	global_load_lds_dwordx4 v[196:197], off
	s_waitcnt vmcnt(8)
	s_waitcnt lgkmcnt(0)
	s_barrier
	s_setprio 1
	s_waitcnt lgkmcnt(0)
	v_mfma_f32_16x16x32_bf16 v[148:151], v[104:107], v[160:163], 0
	v_mfma_f32_16x16x32_bf16 v[140:143], v[120:123], v[160:163], 0
	v_mfma_f32_16x16x32_bf16 v[132:135], v[104:107], v[212:215], 0
	v_mfma_f32_16x16x32_bf16 v[128:131], v[120:123], v[212:215], 0
	v_mfma_f32_16x16x32_bf16 v[116:119], v[104:107], v[220:223], 0
	v_mfma_f32_16x16x32_bf16 v[112:115], v[120:123], v[220:223], 0
	v_mfma_f32_16x16x32_bf16 v[100:103], v[104:107], v[228:231], 0
	v_mfma_f32_16x16x32_bf16 v[96:99], v[120:123], v[228:231], 0
	v_mfma_f32_16x16x32_bf16 v[148:151], v[108:111], v[164:167], v[148:151]
	v_mfma_f32_16x16x32_bf16 v[140:143], v[124:127], v[164:167], v[140:143]
	v_mfma_f32_16x16x32_bf16 v[132:135], v[108:111], v[216:219], v[132:135]
	v_mfma_f32_16x16x32_bf16 v[128:131], v[124:127], v[216:219], v[128:131]
	v_mfma_f32_16x16x32_bf16 v[116:119], v[108:111], v[224:227], v[116:119]
	v_mfma_f32_16x16x32_bf16 v[112:115], v[124:127], v[224:227], v[112:115]
	v_mfma_f32_16x16x32_bf16 v[100:103], v[108:111], v[232:235], v[100:103]
	v_mfma_f32_16x16x32_bf16 v[96:99], v[124:127], v[232:235], v[96:99]
	s_setprio 0
	s_setprio 1
	v_mfma_f32_16x16x32_bf16 v[60:63], v[136:139], v[160:163], 0
	v_mfma_f32_16x16x32_bf16 v[56:59], v[152:155], v[160:163], 0
	v_mfma_f32_16x16x32_bf16 v[52:55], v[136:139], v[212:215], 0
	v_mfma_f32_16x16x32_bf16 v[48:51], v[152:155], v[212:215], 0
	v_mfma_f32_16x16x32_bf16 v[44:47], v[136:139], v[220:223], 0
	v_mfma_f32_16x16x32_bf16 v[40:43], v[152:155], v[220:223], 0
	v_mfma_f32_16x16x32_bf16 v[36:39], v[136:139], v[228:231], 0
	v_mfma_f32_16x16x32_bf16 v[32:35], v[152:155], v[228:231], 0
	v_mfma_f32_16x16x32_bf16 v[60:63], v[144:147], v[164:167], v[60:63]
	v_mfma_f32_16x16x32_bf16 v[56:59], v[156:159], v[164:167], v[56:59]
	v_mfma_f32_16x16x32_bf16 v[52:55], v[144:147], v[216:219], v[52:55]
	v_mfma_f32_16x16x32_bf16 v[48:51], v[156:159], v[216:219], v[48:51]
	v_mfma_f32_16x16x32_bf16 v[44:47], v[144:147], v[224:227], v[44:47]
	v_mfma_f32_16x16x32_bf16 v[40:43], v[156:159], v[224:227], v[40:43]
	v_mfma_f32_16x16x32_bf16 v[36:39], v[144:147], v[232:235], v[36:39]
	v_mfma_f32_16x16x32_bf16 v[32:35], v[156:159], v[232:235], v[32:35]
	s_setprio 0
	s_barrier
	s_add_i32 s14, s14, s21
	v_lshl_add_u64 v[196:197], s[66:67], 0, v[182:183]
	s_mov_b32 m0, s14
	ds_read_b128 v[160:163], v211 offset:16384
	ds_read_b128 v[164:167], v211 offset:17408
	ds_read_b128 v[212:215], v211 offset:18432
	ds_read_b128 v[216:219], v211 offset:19456
	ds_read_b128 v[220:223], v211 offset:20480
	ds_read_b128 v[224:227], v211 offset:21504
	ds_read_b128 v[228:231], v211 offset:22528
	ds_read_b128 v[232:235], v211 offset:23552
	global_load_lds_dwordx4 v[196:197], off
	s_add_i32 m0, s14, 0x2000
	s_add_u32 s62, s66, 0x28000
	v_lshl_add_u64 v[236:237], s[66:67], 0, v[186:187]
	s_addc_u32 s63, s67, 0
	s_add_i32 s14, s15, s21
	global_load_lds_dwordx4 v[236:237], off
	v_lshl_add_u64 v[238:239], s[62:63], 0, v[182:183]
	s_mov_b32 m0, s14
	v_lshl_add_u64 v[240:241], s[68:69], 0, v[184:185]
	global_load_lds_dwordx4 v[238:239], off
	v_lshl_add_u64 v[238:239], s[62:63], 0, v[186:187]
	s_add_i32 m0, s14, 0x2000
	s_nop 0
	global_load_lds_dwordx4 v[238:239], off
	v_lshl_add_u64 v[238:239], s[68:69], 0, v[180:181]
	s_mov_b32 m0, s23
	s_nop 0
	global_load_lds_dwordx4 v[238:239], off
	s_mov_b32 m0, s29
	s_nop 0
	global_load_lds_dwordx4 v[240:241], off
	s_waitcnt vmcnt(8)
	s_waitcnt lgkmcnt(0)
	s_barrier
; #define PG8_STAGE(bufoff, gbase, voff) do { _Pragma("unroll") for (int _i = 0; _i < 2; ++_i) \
;         __builtin_amdgcn_global_load_lds((const unsigned*)((const char*)(gbase) + (voff)[_i]), (LAS unsigned*)(lds + (bufoff) + ldsw + _i * 8192), 16, 0, 0); } while (0)
; #define PG8_LDA(dst, b, h) do { _Pragma("unroll") for (int m = 0; m < 4; ++m) _Pragma("unroll") for (int k = 0; k < 2; ++k) dst[m][k] = *(const LAS bf16x8*)(lds + PG8_SA(b, h) + aoff + m * 2048 + k * 1024); } while (0)
; #define PG8_LDB(dst, b, h) do { _Pragma("unroll") for (int n = 0; n < 2; ++n) _Pragma("unroll") for (int k = 0; k < 2; ++k) dst[n][k] = *(const LAS bf16x8*)(lds + PG8_SB(b, h) + boff + n * 2048 + k * 1024); } while (0)
; #define PG8_MMA(ai, bj, At, Bt) do { __builtin_amdgcn_s_setprio(1); _Pragma("unroll") for (int m = 0; m < 4; ++m) _Pragma("unroll") for (int n = 0; n < 2; ++n) _Pragma("unroll") for (int k = 0; k < 2; ++k) \
;         acc[ai][bj][m][n] = __builtin_amdgcn_mfma_f32_16x16x32_bf16(Bt[n][k], At[m][k], acc[ai][bj][m][n], 0, 0, 0); __builtin_amdgcn_s_setprio(0); } while (0)
; #define PG8_WAIT_V(n) asm volatile("s_waitcnt vmcnt(" #n ")" ::: "memory")
; #define PG8_WAIT_L(n) asm volatile("s_waitcnt lgkmcnt(" #n ")" ::: "memory")
; #define PG8_BAR __builtin_amdgcn_s_barrier()
; #define PG8_SCHED __builtin_amdgcn_sched_barrier(0)
; template <class Epi, class Sched>
; __device__ __forceinline__ void gemm_phase(const int tid, LAS unsigned char* lds, const int lda, const int ldb, const int K, const Sched& S, const Epi& E) {
;     ...
;             PG8_WAIT_V(8); PG8_WAIT_L(0); PG8_BAR; if (!cur.half) { PG8_MMA(1, 0, At, B0); PG8_MMA(1, 1, At, B1); } PG8_BAR; PG8_SCHED;
;             PG8_LDB(B0, 1, 0); PG8_LDB(B1, 1, 1); PG8_SCHED; PG8_LDA(At, 1, 0); PG8_STAGE(PG8_SA(0, 1), a2 + hstepA, voffA);
;             PG8_WAIT_V(8); PG8_WAIT_L(0); PG8_BAR; PG8_MMA(0, 0, At, B0); PG8_MMA(0, 1, At, B1); PG8_BAR; PG8_SCHED;
	s_setprio 1
	s_waitcnt lgkmcnt(0)
	v_mfma_f32_16x16x32_bf16 v[92:95], v[104:107], v[160:163], 0
	v_mfma_f32_16x16x32_bf16 v[88:91], v[120:123], v[160:163], 0
	v_mfma_f32_16x16x32_bf16 v[84:87], v[104:107], v[212:215], 0
	v_mfma_f32_16x16x32_bf16 v[80:83], v[120:123], v[212:215], 0
	v_mfma_f32_16x16x32_bf16 v[76:79], v[104:107], v[220:223], 0
	v_mfma_f32_16x16x32_bf16 v[72:75], v[120:123], v[220:223], 0
	v_mfma_f32_16x16x32_bf16 v[68:71], v[104:107], v[228:231], 0
	v_mfma_f32_16x16x32_bf16 v[64:67], v[120:123], v[228:231], 0
	v_mfma_f32_16x16x32_bf16 v[92:95], v[108:111], v[164:167], v[92:95]
	v_mfma_f32_16x16x32_bf16 v[88:91], v[124:127], v[164:167], v[88:91]
	v_mfma_f32_16x16x32_bf16 v[84:87], v[108:111], v[216:219], v[84:87]
	v_mfma_f32_16x16x32_bf16 v[80:83], v[124:127], v[216:219], v[80:83]
	v_mfma_f32_16x16x32_bf16 v[76:79], v[108:111], v[224:227], v[76:79]
	v_mfma_f32_16x16x32_bf16 v[72:75], v[124:127], v[224:227], v[72:75]
	v_mfma_f32_16x16x32_bf16 v[68:71], v[108:111], v[232:235], v[68:71]
	v_mfma_f32_16x16x32_bf16 v[64:67], v[124:127], v[232:235], v[64:67]
	s_setprio 0
	s_setprio 1
	v_mfma_f32_16x16x32_bf16 v[28:31], v[136:139], v[160:163], 0
	v_mfma_f32_16x16x32_bf16 v[24:27], v[152:155], v[160:163], 0
	v_mfma_f32_16x16x32_bf16 v[20:23], v[136:139], v[212:215], 0
	v_mfma_f32_16x16x32_bf16 v[16:19], v[152:155], v[212:215], 0
	v_mfma_f32_16x16x32_bf16 v[12:15], v[136:139], v[220:223], 0
	v_mfma_f32_16x16x32_bf16 v[8:11], v[152:155], v[220:223], 0
	v_mfma_f32_16x16x32_bf16 v[4:7], v[136:139], v[228:231], 0
	v_mfma_f32_16x16x32_bf16 v[0:3], v[152:155], v[228:231], 0
	v_mfma_f32_16x16x32_bf16 v[28:31], v[144:147], v[164:167], v[28:31]
	v_mfma_f32_16x16x32_bf16 v[24:27], v[156:159], v[164:167], v[24:27]
	v_mfma_f32_16x16x32_bf16 v[20:23], v[144:147], v[216:219], v[20:23]
	v_mfma_f32_16x16x32_bf16 v[16:19], v[156:159], v[216:219], v[16:19]
	v_mfma_f32_16x16x32_bf16 v[12:15], v[144:147], v[224:227], v[12:15]
	v_mfma_f32_16x16x32_bf16 v[8:11], v[156:159], v[224:227], v[8:11]
	v_mfma_f32_16x16x32_bf16 v[4:7], v[144:147], v[232:235], v[4:7]
	v_mfma_f32_16x16x32_bf16 v[0:3], v[156:159], v[232:235], v[0:3]
	s_setprio 0
	s_barrier
	s_add_i32 s14, 0, 0x18000
	s_add_i32 s15, 0, 0x1c000
	v_add_u32_e32 v124, s14, v206
	v_add_u32_e32 v156, s15, v206
	ds_read_b128 v[104:107], v124
	ds_read_b128 v[108:111], v124 offset:1024
	ds_read_b128 v[120:123], v124 offset:2048
	ds_read_b128 v[124:127], v124 offset:3072
	ds_read_b128 v[136:139], v156
	ds_read_b128 v[144:147], v156 offset:1024
	ds_read_b128 v[152:155], v156 offset:2048
	ds_read_b128 v[156:159], v156 offset:3072
	s_add_u32 s62, s68, 0x28000
	s_addc_u32 s63, s69, 0
	s_mov_b32 m0, s31
	v_lshl_add_u64 v[242:243], s[62:63], 0, v[180:181]
	ds_read_b128 v[160:163], v211 offset:32768
	ds_read_b128 v[164:167], v211 offset:33792
	ds_read_b128 v[212:215], v211 offset:34816
	ds_read_b128 v[216:219], v211 offset:35840
	ds_read_b128 v[220:223], v211 offset:36864
	ds_read_b128 v[224:227], v211 offset:37888
	ds_read_b128 v[228:231], v211 offset:38912
	ds_read_b128 v[232:235], v211 offset:39936
	global_load_lds_dwordx4 v[242:243], off
	v_lshl_add_u64 v[242:243], s[62:63], 0, v[184:185]
	s_mov_b32 m0, s41
	s_nop 0
	global_load_lds_dwordx4 v[242:243], off
	s_waitcnt vmcnt(8)
	s_waitcnt lgkmcnt(0)
	s_barrier
	s_setprio 1
	s_waitcnt lgkmcnt(0)
	v_mfma_f32_16x16x32_bf16 v[148:151], v[104:107], v[160:163], v[148:151]
	v_mfma_f32_16x16x32_bf16 v[140:143], v[120:123], v[160:163], v[140:143]
	v_mfma_f32_16x16x32_bf16 v[132:135], v[104:107], v[212:215], v[132:135]
	v_mfma_f32_16x16x32_bf16 v[128:131], v[120:123], v[212:215], v[128:131]
	v_mfma_f32_16x16x32_bf16 v[116:119], v[104:107], v[220:223], v[116:119]
	v_mfma_f32_16x16x32_bf16 v[112:115], v[120:123], v[220:223], v[112:115]
	v_mfma_f32_16x16x32_bf16 v[100:103], v[104:107], v[228:231], v[100:103]
	v_mfma_f32_16x16x32_bf16 v[96:99], v[120:123], v[228:231], v[96:99]
	v_mfma_f32_16x16x32_bf16 v[148:151], v[108:111], v[164:167], v[148:151]
	v_mfma_f32_16x16x32_bf16 v[140:143], v[124:127], v[164:167], v[140:143]
	v_mfma_f32_16x16x32_bf16 v[132:135], v[108:111], v[216:219], v[132:135]
	v_mfma_f32_16x16x32_bf16 v[128:131], v[124:127], v[216:219], v[128:131]
	v_mfma_f32_16x16x32_bf16 v[116:119], v[108:111], v[224:227], v[116:119]
	v_mfma_f32_16x16x32_bf16 v[112:115], v[124:127], v[224:227], v[112:115]
	v_mfma_f32_16x16x32_bf16 v[100:103], v[108:111], v[232:235], v[100:103]
	v_mfma_f32_16x16x32_bf16 v[96:99], v[124:127], v[232:235], v[96:99]
	s_setprio 0
	s_setprio 1
	v_mfma_f32_16x16x32_bf16 v[60:63], v[136:139], v[160:163], v[60:63]
	v_mfma_f32_16x16x32_bf16 v[56:59], v[152:155], v[160:163], v[56:59]
	v_mfma_f32_16x16x32_bf16 v[52:55], v[136:139], v[212:215], v[52:55]
	v_mfma_f32_16x16x32_bf16 v[48:51], v[152:155], v[212:215], v[48:51]
	v_mfma_f32_16x16x32_bf16 v[44:47], v[136:139], v[220:223], v[44:47]
	v_mfma_f32_16x16x32_bf16 v[40:43], v[152:155], v[220:223], v[40:43]
	v_mfma_f32_16x16x32_bf16 v[36:39], v[136:139], v[228:231], v[36:39]
	v_mfma_f32_16x16x32_bf16 v[32:35], v[152:155], v[228:231], v[32:35]
	v_mfma_f32_16x16x32_bf16 v[60:63], v[144:147], v[164:167], v[60:63]
	v_mfma_f32_16x16x32_bf16 v[56:59], v[156:159], v[164:167], v[56:59]
	v_mfma_f32_16x16x32_bf16 v[52:55], v[144:147], v[216:219], v[52:55]
	v_mfma_f32_16x16x32_bf16 v[48:51], v[156:159], v[216:219], v[48:51]
	v_mfma_f32_16x16x32_bf16 v[44:47], v[144:147], v[224:227], v[44:47]
	v_mfma_f32_16x16x32_bf16 v[40:43], v[156:159], v[224:227], v[40:43]
	v_mfma_f32_16x16x32_bf16 v[36:39], v[144:147], v[232:235], v[36:39]
	v_mfma_f32_16x16x32_bf16 v[32:35], v[156:159], v[232:235], v[32:35]
	s_setprio 0
	s_barrier
; #define PG8_STAGE(bufoff, gbase, voff) do { _Pragma("unroll") for (int _i = 0; _i < 2; ++_i) \
;         __builtin_amdgcn_global_load_lds((const unsigned*)((const char*)(gbase) + (voff)[_i]), (LAS unsigned*)(lds + (bufoff) + ldsw + _i * 8192), 16, 0, 0); } while (0)
; #define PG8_LDA(dst, b, h) do { _Pragma("unroll") for (int m = 0; m < 4; ++m) _Pragma("unroll") for (int k = 0; k < 2; ++k) dst[m][k] = *(const LAS bf16x8*)(lds + PG8_SA(b, h) + aoff + m * 2048 + k * 1024); } while (0)
; #define PG8_MMA(ai, bj, At, Bt) do { __builtin_amdgcn_s_setprio(1); _Pragma("unroll") for (int m = 0; m < 4; ++m) _Pragma("unroll") for (int n = 0; n < 2; ++n) _Pragma("unroll") for (int k = 0; k < 2; ++k) \
;         acc[ai][bj][m][n] = __builtin_amdgcn_mfma_f32_16x16x32_bf16(Bt[n][k], At[m][k], acc[ai][bj][m][n], 0, 0, 0); __builtin_amdgcn_s_setprio(0); } while (0)
; #define PG8_WAIT_V(n) asm volatile("s_waitcnt vmcnt(" #n ")" ::: "memory")
; #define PG8_WAIT_L(n) asm volatile("s_waitcnt lgkmcnt(" #n ")" ::: "memory")
; #define PG8_BAR __builtin_amdgcn_s_barrier()
; #define PG8_SCHED __builtin_amdgcn_sched_barrier(0)
; template <class Epi, class Sched>
; __device__ __forceinline__ void gemm_phase(const int tid, LAS unsigned char* lds, const int lda, const int ldb, const int K, const Sched& S, const Epi& E) {
;     ...
;         for (int t = 0; t < nt; t += 2) {
;     ...
;             PG8_LDA(At, 1, 1); PG8_STAGE(PG8_SB(1, 0), b3, voffB); PG8_STAGE(PG8_SB(1, 1), b3 + hstepB, voffB); PG8_STAGE(PG8_SA(1, 0), a3, voffA);
;             PG8_WAIT_V(8); PG8_WAIT_L(0); PG8_BAR; if (!cur.half) { PG8_MMA(1, 0, At, B0); PG8_MMA(1, 1, At, B1); } PG8_BAR; PG8_SCHED;
	s_add_i32 s14, s14, s21
	v_lshl_add_u64 v[196:197], v[196:197], 0, s[6:7]
	s_mov_b32 m0, s14
	ds_read_b128 v[160:163], v211 offset:49152
	ds_read_b128 v[164:167], v211 offset:50176
	ds_read_b128 v[212:215], v211 offset:51200
	ds_read_b128 v[216:219], v211 offset:52224
	ds_read_b128 v[220:223], v211 offset:53248
	ds_read_b128 v[224:227], v211 offset:54272
	ds_read_b128 v[228:231], v211 offset:55296
	ds_read_b128 v[232:235], v211 offset:56320
	global_load_lds_dwordx4 v[196:197], off
	s_add_i32 m0, s14, 0x2000
	s_add_u32 s62, s66, 0x28080
	v_lshl_add_u64 v[196:197], v[236:237], 0, s[6:7]
	s_addc_u32 s63, s67, 0
	s_add_i32 s14, s15, s21
	global_load_lds_dwordx4 v[196:197], off
	v_lshl_add_u64 v[196:197], s[62:63], 0, v[182:183]
	s_mov_b32 m0, s14
	s_nop 0
	global_load_lds_dwordx4 v[196:197], off
	v_lshl_add_u64 v[196:197], s[62:63], 0, v[186:187]
	s_add_i32 m0, s14, 0x2000
	s_nop 0
	global_load_lds_dwordx4 v[196:197], off
	v_lshl_add_u64 v[196:197], v[238:239], 0, s[6:7]
	s_mov_b32 m0, s47
	s_nop 0
	global_load_lds_dwordx4 v[196:197], off
	v_lshl_add_u64 v[196:197], v[240:241], 0, s[6:7]
	s_mov_b32 m0, s70
	s_nop 0
	global_load_lds_dwordx4 v[196:197], off
	s_waitcnt vmcnt(8)
	s_waitcnt lgkmcnt(0)
	s_barrier
	s_setprio 1
	s_waitcnt lgkmcnt(0)
	v_mfma_f32_16x16x32_bf16 v[92:95], v[104:107], v[160:163], v[92:95]
	v_mfma_f32_16x16x32_bf16 v[88:91], v[120:123], v[160:163], v[88:91]
	v_mfma_f32_16x16x32_bf16 v[84:87], v[104:107], v[212:215], v[84:87]
	v_mfma_f32_16x16x32_bf16 v[80:83], v[120:123], v[212:215], v[80:83]
	v_mfma_f32_16x16x32_bf16 v[76:79], v[104:107], v[220:223], v[76:79]
	v_mfma_f32_16x16x32_bf16 v[72:75], v[120:123], v[220:223], v[72:75]
	v_mfma_f32_16x16x32_bf16 v[68:71], v[104:107], v[228:231], v[68:71]
	v_mfma_f32_16x16x32_bf16 v[64:67], v[120:123], v[228:231], v[64:67]
	v_mfma_f32_16x16x32_bf16 v[92:95], v[108:111], v[164:167], v[92:95]
	v_mfma_f32_16x16x32_bf16 v[88:91], v[124:127], v[164:167], v[88:91]
	v_mfma_f32_16x16x32_bf16 v[84:87], v[108:111], v[216:219], v[84:87]
	v_mfma_f32_16x16x32_bf16 v[80:83], v[124:127], v[216:219], v[80:83]
	v_mfma_f32_16x16x32_bf16 v[76:79], v[108:111], v[224:227], v[76:79]
	v_mfma_f32_16x16x32_bf16 v[72:75], v[124:127], v[224:227], v[72:75]
	v_mfma_f32_16x16x32_bf16 v[68:71], v[108:111], v[232:235], v[68:71]
	v_mfma_f32_16x16x32_bf16 v[64:67], v[124:127], v[232:235], v[64:67]
	s_setprio 0
	s_setprio 1
	v_mfma_f32_16x16x32_bf16 v[28:31], v[136:139], v[160:163], v[28:31]
	v_mfma_f32_16x16x32_bf16 v[24:27], v[152:155], v[160:163], v[24:27]
	v_mfma_f32_16x16x32_bf16 v[20:23], v[136:139], v[212:215], v[20:23]
	v_mfma_f32_16x16x32_bf16 v[16:19], v[152:155], v[212:215], v[16:19]
	v_mfma_f32_16x16x32_bf16 v[12:15], v[136:139], v[220:223], v[12:15]
	v_mfma_f32_16x16x32_bf16 v[8:11], v[152:155], v[220:223], v[8:11]
	v_mfma_f32_16x16x32_bf16 v[4:7], v[136:139], v[228:231], v[4:7]
	v_mfma_f32_16x16x32_bf16 v[0:3], v[152:155], v[228:231], v[0:3]
	v_mfma_f32_16x16x32_bf16 v[28:31], v[144:147], v[164:167], v[28:31]
	v_mfma_f32_16x16x32_bf16 v[24:27], v[156:159], v[164:167], v[24:27]
	v_mfma_f32_16x16x32_bf16 v[20:23], v[144:147], v[216:219], v[20:23]
	v_mfma_f32_16x16x32_bf16 v[16:19], v[156:159], v[216:219], v[16:19]
	v_mfma_f32_16x16x32_bf16 v[12:15], v[144:147], v[224:227], v[12:15]
	v_mfma_f32_16x16x32_bf16 v[8:11], v[156:159], v[224:227], v[8:11]
	v_mfma_f32_16x16x32_bf16 v[4:7], v[144:147], v[232:235], v[4:7]
	v_mfma_f32_16x16x32_bf16 v[0:3], v[156:159], v[232:235], v[0:3]
	s_setprio 0
	s_barrier
	s_add_u32 s26, s26, 0x100
	s_addc_u32 s27, s27, 0
	s_cmp_ge_i32 s43, s4
	s_mov_b64 s[62:63], s[64:65]
	s_mov_b32 s42, s43
	s_cbranch_scc1 .Lkexit_793

; #define PG8_BAR __builtin_amdgcn_s_barrier()
; template <class Epi, class Sched>
; __device__ __forceinline__ void gemm_phase(const int tid, LAS unsigned char* lds, const int lda, const int ldb, const int K, const Sched& S, const Epi& E) {
;     ...
;         if (wr == 0) PG8_BAR;
;         if (MK_EPI2 && Epi::IDEM) E(acc, cur, wr, wc, fr, fq, es0, es1);
;         E(acc, cur, wr, wc, fr, fq, es0, es1);
;         if (!has_next) break;
.Lkexit_793:
	v_readlane_b32 s68, v255, 13
	v_readlane_b32 s69, v255, 14
	s_mov_b32 s66, 0x16000
	s_mov_b32 s67, 0x18000
	s_movk_i32 s14, 0x500
	s_and_b64 vcc, exec, s[52:53]
	s_cbranch_vccz .LBB0_796

; #define PG8_STAGE(bufoff, gbase, voff) do { _Pragma("unroll") for (int _i = 0; _i < 2; ++_i) \
;         __builtin_amdgcn_global_load_lds((const unsigned*)((const char*)(gbase) + (voff)[_i]), (LAS unsigned*)(lds + (bufoff) + ldsw + _i * 8192), 16, 0, 0); } while (0)
; #define PG8_LDA(dst, b, h) do { _Pragma("unroll") for (int m = 0; m < 4; ++m) _Pragma("unroll") for (int k = 0; k < 2; ++k) dst[m][k] = *(const LAS bf16x8*)(lds + PG8_SA(b, h) + aoff + m * 2048 + k * 1024); } while (0)
; #define PG8_LDB(dst, b, h) do { _Pragma("unroll") for (int n = 0; n < 2; ++n) _Pragma("unroll") for (int k = 0; k < 2; ++k) dst[n][k] = *(const LAS bf16x8*)(lds + PG8_SB(b, h) + boff + n * 2048 + k * 1024); } while (0)
; #define PG8_MMA(ai, bj, At, Bt) do { __builtin_amdgcn_s_setprio(1); _Pragma("unroll") for (int m = 0; m < 4; ++m) _Pragma("unroll") for (int n = 0; n < 2; ++n) _Pragma("unroll") for (int k = 0; k < 2; ++k) \
;         acc[ai][bj][m][n] = __builtin_amdgcn_mfma_f32_16x16x32_bf16(Bt[n][k], At[m][k], acc[ai][bj][m][n], 0, 0, 0); __builtin_amdgcn_s_setprio(0); } while (0)
; #define PG8_WAIT_V(n) asm volatile("s_waitcnt vmcnt(" #n ")" ::: "memory")
; #define PG8_WAIT_L(n) asm volatile("s_waitcnt lgkmcnt(" #n ")" ::: "memory")
; #define PG8_BAR __builtin_amdgcn_s_barrier()
; #define PG8_SCHED __builtin_amdgcn_sched_barrier(0)
; template <class Epi, class Sched>
; __device__ __forceinline__ void gemm_phase(const int tid, LAS unsigned char* lds, const int lda, const int ldb, const int K, const Sched& S, const Epi& E) {
;     ...
;             const bool last = (t == nt - 2);
;             const char* a1 = cA + (size_t)(t + 1) * kstep;
;             const char* a2 = last ? nA : cA + (size_t)(t + 2) * kstep; const char* b2 = last ? nB : cB + (size_t)(t + 2) * kstep;
;             const char* a3 = a2 + kstep; const char* b3 = b2 + kstep;
;             PG8_LDB(B0, 0, 0); PG8_LDB(B1, 0, 1); PG8_SCHED; PG8_LDA(At, 0, 0); PG8_STAGE(PG8_SA(1, 1), a1 + hstepA, voffA);
;             PG8_WAIT_V(8); PG8_WAIT_L(0); PG8_BAR; PG8_MMA(0, 0, At, B0); PG8_MMA(0, 1, At, B1); PG8_BAR; PG8_SCHED;
;             PG8_LDA(At, 0, 1); PG8_STAGE(PG8_SB(0, 0), b2, voffB); PG8_STAGE(PG8_SB(0, 1), b2 + hstepB, voffB); PG8_STAGE(PG8_SA(0, 0), a2, voffA);
;             PG8_WAIT_V(8); PG8_WAIT_L(0); PG8_BAR; if (!cur.half) { PG8_MMA(1, 0, At, B0); PG8_MMA(1, 1, At, B1); } PG8_BAR; PG8_SCHED;
.LBB0_872:
	s_andn2_b64 vcc, exec, s[40:41]
	s_cbranch_vccnz .LBB0_880
	s_add_u32 s50, s50, 0x40080
	s_addc_u32 s51, s51, 0
	s_add_u32 s45, s52, 0x100
	s_addc_u32 s63, s53, 0
	s_mov_b32 s52, 0
	s_add_i32 s64, s52, 2
	s_add_u32 s14, s50, 0xfffc0080
	s_addc_u32 s15, s51, -1
	s_add_i32 s24, 0, 0x10000
	s_cmp_eq_u32 s60, s52
	s_cselect_b32 s55, s3, s15
	s_cselect_b32 s54, s2, s14
	v_add_u32_e32 v141, s24, v148
	s_cselect_b32 s53, s39, s63
	s_cselect_b32 s52, s38, s45
	s_add_i32 s14, 0, 0x14000
	ds_read_b128 v[158:161], v141
	ds_read_b128 v[162:165], v141 offset:1024
	ds_read_b128 v[180:183], v141 offset:2048
	ds_read_b128 v[184:187], v141 offset:3072
	v_add_u32_e32 v141, s14, v148
	ds_read_b128 v[190:193], v141
	ds_read_b128 v[194:197], v141 offset:1024
	ds_read_b128 v[204:207], v141 offset:2048
	ds_read_b128 v[208:211], v141 offset:3072
	v_lshl_add_u64 v[166:167], s[50:51], 0, v[136:137]
	s_add_i32 m0, s21, 0xc000
	ds_read_b128 v[212:215], v155
	ds_read_b128 v[216:219], v155 offset:1024
	ds_read_b128 v[220:223], v155 offset:2048
	ds_read_b128 v[224:227], v155 offset:3072
	ds_read_b128 v[228:231], v155 offset:4096
	ds_read_b128 v[232:235], v155 offset:5120
	ds_read_b128 v[236:239], v155 offset:6144
	ds_read_b128 v[240:243], v155 offset:7168
	global_load_lds_dwordx4 v[166:167], off
	v_lshl_add_u64 v[166:167], s[50:51], 0, v[138:139]
	s_add_i32 m0, s21, 0xe000
	s_nop 0
	global_load_lds_dwordx4 v[166:167], off
	s_waitcnt vmcnt(8)
	s_waitcnt lgkmcnt(0)
	s_barrier
	s_setprio 1
	s_waitcnt lgkmcnt(0)
	v_mfma_f32_16x16x32_bf16 v[124:127], v[158:161], v[212:215], 0
	v_mfma_f32_16x16x32_bf16 v[120:123], v[180:183], v[212:215], 0
	v_mfma_f32_16x16x32_bf16 v[108:111], v[158:161], v[220:223], 0
	v_mfma_f32_16x16x32_bf16 v[104:107], v[180:183], v[220:223], 0
	v_mfma_f32_16x16x32_bf16 v[92:95], v[158:161], v[228:231], 0
	v_mfma_f32_16x16x32_bf16 v[88:91], v[180:183], v[228:231], 0
	v_mfma_f32_16x16x32_bf16 v[76:79], v[158:161], v[236:239], 0
	v_mfma_f32_16x16x32_bf16 v[72:75], v[180:183], v[236:239], 0
	v_mfma_f32_16x16x32_bf16 v[124:127], v[162:165], v[216:219], v[124:127]
	v_mfma_f32_16x16x32_bf16 v[120:123], v[184:187], v[216:219], v[120:123]
	v_mfma_f32_16x16x32_bf16 v[108:111], v[162:165], v[224:227], v[108:111]
	v_mfma_f32_16x16x32_bf16 v[104:107], v[184:187], v[224:227], v[104:107]
	v_mfma_f32_16x16x32_bf16 v[92:95], v[162:165], v[232:235], v[92:95]
	v_mfma_f32_16x16x32_bf16 v[88:91], v[184:187], v[232:235], v[88:91]
	v_mfma_f32_16x16x32_bf16 v[76:79], v[162:165], v[240:243], v[76:79]
	v_mfma_f32_16x16x32_bf16 v[72:75], v[184:187], v[240:243], v[72:75]
	s_setprio 0
	s_setprio 1
	v_mfma_f32_16x16x32_bf16 v[116:119], v[190:193], v[212:215], 0
	v_mfma_f32_16x16x32_bf16 v[112:115], v[204:207], v[212:215], 0
	v_mfma_f32_16x16x32_bf16 v[100:103], v[190:193], v[220:223], 0
	v_mfma_f32_16x16x32_bf16 v[96:99], v[204:207], v[220:223], 0
	v_mfma_f32_16x16x32_bf16 v[84:87], v[190:193], v[228:231], 0
	v_mfma_f32_16x16x32_bf16 v[80:83], v[204:207], v[228:231], 0
	v_mfma_f32_16x16x32_bf16 v[68:71], v[190:193], v[236:239], 0
	v_mfma_f32_16x16x32_bf16 v[64:67], v[204:207], v[236:239], 0
	v_mfma_f32_16x16x32_bf16 v[116:119], v[194:197], v[216:219], v[116:119]
	v_mfma_f32_16x16x32_bf16 v[112:115], v[208:211], v[216:219], v[112:115]
	v_mfma_f32_16x16x32_bf16 v[100:103], v[194:197], v[224:227], v[100:103]
	v_mfma_f32_16x16x32_bf16 v[96:99], v[208:211], v[224:227], v[96:99]
	v_mfma_f32_16x16x32_bf16 v[84:87], v[194:197], v[232:235], v[84:87]
	v_mfma_f32_16x16x32_bf16 v[80:83], v[208:211], v[232:235], v[80:83]
	v_mfma_f32_16x16x32_bf16 v[68:71], v[194:197], v[240:243], v[68:71]
	v_mfma_f32_16x16x32_bf16 v[64:67], v[208:211], v[240:243], v[64:67]
	s_setprio 0
	s_barrier
	s_add_i32 s15, s24, s20
	v_lshl_add_u64 v[166:167], s[52:53], 0, v[130:131]
	s_mov_b32 m0, s15
	ds_read_b128 v[212:215], v155 offset:16384
	ds_read_b128 v[216:219], v155 offset:17408
	ds_read_b128 v[220:223], v155 offset:18432
	ds_read_b128 v[224:227], v155 offset:19456
	ds_read_b128 v[228:231], v155 offset:20480
	ds_read_b128 v[232:235], v155 offset:21504
	ds_read_b128 v[236:239], v155 offset:22528
	ds_read_b128 v[240:243], v155 offset:23552
	global_load_lds_dwordx4 v[166:167], off
	s_add_i32 m0, s15, 0x2000
	s_add_u32 s66, s52, 0x40000
	v_lshl_add_u64 v[244:245], s[52:53], 0, v[134:135]
	s_addc_u32 s67, s53, 0
	s_add_i32 s14, s14, s20
	global_load_lds_dwordx4 v[244:245], off
	v_lshl_add_u64 v[246:247], s[66:67], 0, v[130:131]
	s_mov_b32 m0, s14
	v_lshl_add_u64 v[248:249], s[54:55], 0, v[132:133]
	global_load_lds_dwordx4 v[246:247], off
	v_lshl_add_u64 v[246:247], s[66:67], 0, v[134:135]
	s_add_i32 m0, s14, 0x2000
	s_nop 0
	global_load_lds_dwordx4 v[246:247], off
	v_lshl_add_u64 v[246:247], s[54:55], 0, v[128:129]
	s_mov_b32 m0, s21
	s_nop 0
	global_load_lds_dwordx4 v[246:247], off
	s_mov_b32 m0, s29
	s_nop 0
	global_load_lds_dwordx4 v[248:249], off
	s_waitcnt vmcnt(8)
	s_waitcnt lgkmcnt(0)
	s_barrier
; #define PG8_STAGE(bufoff, gbase, voff) do { _Pragma("unroll") for (int _i = 0; _i < 2; ++_i) \
;         __builtin_amdgcn_global_load_lds((const unsigned*)((const char*)(gbase) + (voff)[_i]), (LAS unsigned*)(lds + (bufoff) + ldsw + _i * 8192), 16, 0, 0); } while (0)
; #define PG8_LDA(dst, b, h) do { _Pragma("unroll") for (int m = 0; m < 4; ++m) _Pragma("unroll") for (int k = 0; k < 2; ++k) dst[m][k] = *(const LAS bf16x8*)(lds + PG8_SA(b, h) + aoff + m * 2048 + k * 1024); } while (0)
; #define PG8_LDB(dst, b, h) do { _Pragma("unroll") for (int n = 0; n < 2; ++n) _Pragma("unroll") for (int k = 0; k < 2; ++k) dst[n][k] = *(const LAS bf16x8*)(lds + PG8_SB(b, h) + boff + n * 2048 + k * 1024); } while (0)
; #define PG8_MMA(ai, bj, At, Bt) do { __builtin_amdgcn_s_setprio(1); _Pragma("unroll") for (int m = 0; m < 4; ++m) _Pragma("unroll") for (int n = 0; n < 2; ++n) _Pragma("unroll") for (int k = 0; k < 2; ++k) \
;         acc[ai][bj][m][n] = __builtin_amdgcn_mfma_f32_16x16x32_bf16(Bt[n][k], At[m][k], acc[ai][bj][m][n], 0, 0, 0); __builtin_amdgcn_s_setprio(0); } while (0)
; #define PG8_WAIT_V(n) asm volatile("s_waitcnt vmcnt(" #n ")" ::: "memory")
; #define PG8_WAIT_L(n) asm volatile("s_waitcnt lgkmcnt(" #n ")" ::: "memory")
; #define PG8_BAR __builtin_amdgcn_s_barrier()
; #define PG8_SCHED __builtin_amdgcn_sched_barrier(0)
; template <class Epi, class Sched>
; __device__ __forceinline__ void gemm_phase(const int tid, LAS unsigned char* lds, const int lda, const int ldb, const int K, const Sched& S, const Epi& E) {
;     ...
;             PG8_WAIT_V(8); PG8_WAIT_L(0); PG8_BAR; if (!cur.half) { PG8_MMA(1, 0, At, B0); PG8_MMA(1, 1, At, B1); } PG8_BAR; PG8_SCHED;
;             PG8_LDB(B0, 1, 0); PG8_LDB(B1, 1, 1); PG8_SCHED; PG8_LDA(At, 1, 0); PG8_STAGE(PG8_SA(0, 1), a2 + hstepA, voffA);
;             PG8_WAIT_V(8); PG8_WAIT_L(0); PG8_BAR; PG8_MMA(0, 0, At, B0); PG8_MMA(0, 1, At, B1); PG8_BAR; PG8_SCHED;
	s_setprio 1
	s_waitcnt lgkmcnt(0)
	v_mfma_f32_16x16x32_bf16 v[60:63], v[158:161], v[212:215], 0
	v_mfma_f32_16x16x32_bf16 v[56:59], v[180:183], v[212:215], 0
	v_mfma_f32_16x16x32_bf16 v[44:47], v[158:161], v[220:223], 0
	v_mfma_f32_16x16x32_bf16 v[40:43], v[180:183], v[220:223], 0
	v_mfma_f32_16x16x32_bf16 v[28:31], v[158:161], v[228:231], 0
	v_mfma_f32_16x16x32_bf16 v[24:27], v[180:183], v[228:231], 0
	v_mfma_f32_16x16x32_bf16 v[12:15], v[158:161], v[236:239], 0
	v_mfma_f32_16x16x32_bf16 v[8:11], v[180:183], v[236:239], 0
	v_mfma_f32_16x16x32_bf16 v[60:63], v[162:165], v[216:219], v[60:63]
	v_mfma_f32_16x16x32_bf16 v[56:59], v[184:187], v[216:219], v[56:59]
	v_mfma_f32_16x16x32_bf16 v[44:47], v[162:165], v[224:227], v[44:47]
	v_mfma_f32_16x16x32_bf16 v[40:43], v[184:187], v[224:227], v[40:43]
	v_mfma_f32_16x16x32_bf16 v[28:31], v[162:165], v[232:235], v[28:31]
	v_mfma_f32_16x16x32_bf16 v[24:27], v[184:187], v[232:235], v[24:27]
	v_mfma_f32_16x16x32_bf16 v[12:15], v[162:165], v[240:243], v[12:15]
	v_mfma_f32_16x16x32_bf16 v[8:11], v[184:187], v[240:243], v[8:11]
	s_setprio 0
	s_setprio 1
	v_mfma_f32_16x16x32_bf16 v[52:55], v[190:193], v[212:215], 0
	v_mfma_f32_16x16x32_bf16 v[48:51], v[204:207], v[212:215], 0
	v_mfma_f32_16x16x32_bf16 v[36:39], v[190:193], v[220:223], 0
	v_mfma_f32_16x16x32_bf16 v[32:35], v[204:207], v[220:223], 0
	v_mfma_f32_16x16x32_bf16 v[20:23], v[190:193], v[228:231], 0
	v_mfma_f32_16x16x32_bf16 v[16:19], v[204:207], v[228:231], 0
	v_mfma_f32_16x16x32_bf16 v[4:7], v[190:193], v[236:239], 0
	v_mfma_f32_16x16x32_bf16 v[0:3], v[204:207], v[236:239], 0
	v_mfma_f32_16x16x32_bf16 v[52:55], v[194:197], v[216:219], v[52:55]
	v_mfma_f32_16x16x32_bf16 v[48:51], v[208:211], v[216:219], v[48:51]
	v_mfma_f32_16x16x32_bf16 v[36:39], v[194:197], v[224:227], v[36:39]
	v_mfma_f32_16x16x32_bf16 v[32:35], v[208:211], v[224:227], v[32:35]
	v_mfma_f32_16x16x32_bf16 v[20:23], v[194:197], v[232:235], v[20:23]
	v_mfma_f32_16x16x32_bf16 v[16:19], v[208:211], v[232:235], v[16:19]
	v_mfma_f32_16x16x32_bf16 v[4:7], v[194:197], v[240:243], v[4:7]
	v_mfma_f32_16x16x32_bf16 v[0:3], v[208:211], v[240:243], v[0:3]
	s_setprio 0
	s_barrier
	s_add_i32 s14, 0, 0x18000
	v_add_u32_e32 v141, s14, v148
	s_add_i32 s15, 0, 0x1c000
	ds_read_b128 v[158:161], v141
	ds_read_b128 v[162:165], v141 offset:1024
	ds_read_b128 v[180:183], v141 offset:2048
	ds_read_b128 v[184:187], v141 offset:3072
	v_add_u32_e32 v141, s15, v148
	ds_read_b128 v[190:193], v141
	ds_read_b128 v[194:197], v141 offset:1024
	ds_read_b128 v[204:207], v141 offset:2048
	ds_read_b128 v[208:211], v141 offset:3072
	s_add_u32 s54, s54, 0x40000
	s_addc_u32 s55, s55, 0
	s_mov_b32 m0, s31
	v_lshl_add_u64 v[250:251], s[54:55], 0, v[128:129]
	ds_read_b128 v[212:215], v155 offset:32768
	ds_read_b128 v[216:219], v155 offset:33792
	ds_read_b128 v[220:223], v155 offset:34816
	ds_read_b128 v[224:227], v155 offset:35840
	ds_read_b128 v[228:231], v155 offset:36864
	ds_read_b128 v[232:235], v155 offset:37888
	ds_read_b128 v[236:239], v155 offset:38912
	ds_read_b128 v[240:243], v155 offset:39936
	global_load_lds_dwordx4 v[250:251], off
	v_lshl_add_u64 v[250:251], s[54:55], 0, v[132:133]
	s_mov_b32 m0, s56
	s_nop 0
	global_load_lds_dwordx4 v[250:251], off
	s_waitcnt vmcnt(8)
	s_waitcnt lgkmcnt(0)
	s_barrier
	s_setprio 1
	s_waitcnt lgkmcnt(0)
	v_mfma_f32_16x16x32_bf16 v[124:127], v[158:161], v[212:215], v[124:127]
	v_mfma_f32_16x16x32_bf16 v[120:123], v[180:183], v[212:215], v[120:123]
	v_mfma_f32_16x16x32_bf16 v[108:111], v[158:161], v[220:223], v[108:111]
	v_mfma_f32_16x16x32_bf16 v[104:107], v[180:183], v[220:223], v[104:107]
	v_mfma_f32_16x16x32_bf16 v[92:95], v[158:161], v[228:231], v[92:95]
	v_mfma_f32_16x16x32_bf16 v[88:91], v[180:183], v[228:231], v[88:91]
	v_mfma_f32_16x16x32_bf16 v[76:79], v[158:161], v[236:239], v[76:79]
	v_mfma_f32_16x16x32_bf16 v[72:75], v[180:183], v[236:239], v[72:75]
	v_mfma_f32_16x16x32_bf16 v[124:127], v[162:165], v[216:219], v[124:127]
	v_mfma_f32_16x16x32_bf16 v[120:123], v[184:187], v[216:219], v[120:123]
	v_mfma_f32_16x16x32_bf16 v[108:111], v[162:165], v[224:227], v[108:111]
	v_mfma_f32_16x16x32_bf16 v[104:107], v[184:187], v[224:227], v[104:107]
	v_mfma_f32_16x16x32_bf16 v[92:95], v[162:165], v[232:235], v[92:95]
	v_mfma_f32_16x16x32_bf16 v[88:91], v[184:187], v[232:235], v[88:91]
	v_mfma_f32_16x16x32_bf16 v[76:79], v[162:165], v[240:243], v[76:79]
	v_mfma_f32_16x16x32_bf16 v[72:75], v[184:187], v[240:243], v[72:75]
	s_setprio 0
	s_setprio 1
	v_mfma_f32_16x16x32_bf16 v[116:119], v[190:193], v[212:215], v[116:119]
	v_mfma_f32_16x16x32_bf16 v[112:115], v[204:207], v[212:215], v[112:115]
	v_mfma_f32_16x16x32_bf16 v[100:103], v[190:193], v[220:223], v[100:103]
	v_mfma_f32_16x16x32_bf16 v[96:99], v[204:207], v[220:223], v[96:99]
	v_mfma_f32_16x16x32_bf16 v[84:87], v[190:193], v[228:231], v[84:87]
	v_mfma_f32_16x16x32_bf16 v[80:83], v[204:207], v[228:231], v[80:83]
	v_mfma_f32_16x16x32_bf16 v[68:71], v[190:193], v[236:239], v[68:71]
	v_mfma_f32_16x16x32_bf16 v[64:67], v[204:207], v[236:239], v[64:67]
	v_mfma_f32_16x16x32_bf16 v[116:119], v[194:197], v[216:219], v[116:119]
	v_mfma_f32_16x16x32_bf16 v[112:115], v[208:211], v[216:219], v[112:115]
	v_mfma_f32_16x16x32_bf16 v[100:103], v[194:197], v[224:227], v[100:103]
	v_mfma_f32_16x16x32_bf16 v[96:99], v[208:211], v[224:227], v[96:99]
	v_mfma_f32_16x16x32_bf16 v[84:87], v[194:197], v[232:235], v[84:87]
	v_mfma_f32_16x16x32_bf16 v[80:83], v[208:211], v[232:235], v[80:83]
	v_mfma_f32_16x16x32_bf16 v[68:71], v[194:197], v[240:243], v[68:71]
	v_mfma_f32_16x16x32_bf16 v[64:67], v[208:211], v[240:243], v[64:67]
	s_setprio 0
	s_barrier
; #define PG8_STAGE(bufoff, gbase, voff) do { _Pragma("unroll") for (int _i = 0; _i < 2; ++_i) \
;         __builtin_amdgcn_global_load_lds((const unsigned*)((const char*)(gbase) + (voff)[_i]), (LAS unsigned*)(lds + (bufoff) + ldsw + _i * 8192), 16, 0, 0); } while (0)
; #define PG8_LDA(dst, b, h) do { _Pragma("unroll") for (int m = 0; m < 4; ++m) _Pragma("unroll") for (int k = 0; k < 2; ++k) dst[m][k] = *(const LAS bf16x8*)(lds + PG8_SA(b, h) + aoff + m * 2048 + k * 1024); } while (0)
; #define PG8_MMA(ai, bj, At, Bt) do { __builtin_amdgcn_s_setprio(1); _Pragma("unroll") for (int m = 0; m < 4; ++m) _Pragma("unroll") for (int n = 0; n < 2; ++n) _Pragma("unroll") for (int k = 0; k < 2; ++k) \
;         acc[ai][bj][m][n] = __builtin_amdgcn_mfma_f32_16x16x32_bf16(Bt[n][k], At[m][k], acc[ai][bj][m][n], 0, 0, 0); __builtin_amdgcn_s_setprio(0); } while (0)
; #define PG8_WAIT_V(n) asm volatile("s_waitcnt vmcnt(" #n ")" ::: "memory")
; #define PG8_WAIT_L(n) asm volatile("s_waitcnt lgkmcnt(" #n ")" ::: "memory")
; #define PG8_BAR __builtin_amdgcn_s_barrier()
; #define PG8_SCHED __builtin_amdgcn_sched_barrier(0)
; template <class Epi, class Sched>
; __device__ __forceinline__ void gemm_phase(const int tid, LAS unsigned char* lds, const int lda, const int ldb, const int K, const Sched& S, const Epi& E) {
;     ...
;         for (int t = 0; t < nt; t += 2) {
;     ...
;             PG8_LDA(At, 1, 1); PG8_STAGE(PG8_SB(1, 0), b3, voffB); PG8_STAGE(PG8_SB(1, 1), b3 + hstepB, voffB); PG8_STAGE(PG8_SA(1, 0), a3, voffA);
;             PG8_WAIT_V(8); PG8_WAIT_L(0); PG8_BAR; if (!cur.half) { PG8_MMA(1, 0, At, B0); PG8_MMA(1, 1, At, B1); } PG8_BAR; PG8_SCHED;
	s_add_i32 s14, s14, s20
	v_lshl_add_u64 v[166:167], v[166:167], 0, s[6:7]
	s_mov_b32 m0, s14
	ds_read_b128 v[212:215], v155 offset:49152
	ds_read_b128 v[216:219], v155 offset:50176
	ds_read_b128 v[220:223], v155 offset:51200
	ds_read_b128 v[224:227], v155 offset:52224
	ds_read_b128 v[228:231], v155 offset:53248
	ds_read_b128 v[232:235], v155 offset:54272
	ds_read_b128 v[236:239], v155 offset:55296
	ds_read_b128 v[240:243], v155 offset:56320
	global_load_lds_dwordx4 v[166:167], off
	s_add_i32 m0, s14, 0x2000
	s_add_u32 s52, s52, 0x40080
	v_lshl_add_u64 v[166:167], v[244:245], 0, s[6:7]
	s_addc_u32 s53, s53, 0
	s_add_i32 s14, s15, s20
	global_load_lds_dwordx4 v[166:167], off
	v_lshl_add_u64 v[166:167], s[52:53], 0, v[130:131]
	s_mov_b32 m0, s14
	s_nop 0
	global_load_lds_dwordx4 v[166:167], off
	v_lshl_add_u64 v[166:167], s[52:53], 0, v[134:135]
	s_add_i32 m0, s14, 0x2000
	s_nop 0
	global_load_lds_dwordx4 v[166:167], off
	v_lshl_add_u64 v[166:167], v[246:247], 0, s[6:7]
	s_mov_b32 m0, s57
	s_nop 0
	global_load_lds_dwordx4 v[166:167], off
	v_lshl_add_u64 v[166:167], v[248:249], 0, s[6:7]
	s_mov_b32 m0, s58
	s_nop 0
	global_load_lds_dwordx4 v[166:167], off
	s_waitcnt vmcnt(8)
	s_waitcnt lgkmcnt(0)
	s_barrier
	s_setprio 1
	s_waitcnt lgkmcnt(0)
	v_mfma_f32_16x16x32_bf16 v[60:63], v[158:161], v[212:215], v[60:63]
	v_mfma_f32_16x16x32_bf16 v[56:59], v[180:183], v[212:215], v[56:59]
	v_mfma_f32_16x16x32_bf16 v[44:47], v[158:161], v[220:223], v[44:47]
	v_mfma_f32_16x16x32_bf16 v[40:43], v[180:183], v[220:223], v[40:43]
	v_mfma_f32_16x16x32_bf16 v[28:31], v[158:161], v[228:231], v[28:31]
	v_mfma_f32_16x16x32_bf16 v[24:27], v[180:183], v[228:231], v[24:27]
	v_mfma_f32_16x16x32_bf16 v[12:15], v[158:161], v[236:239], v[12:15]
	v_mfma_f32_16x16x32_bf16 v[8:11], v[180:183], v[236:239], v[8:11]
	v_mfma_f32_16x16x32_bf16 v[60:63], v[162:165], v[216:219], v[60:63]
	v_mfma_f32_16x16x32_bf16 v[56:59], v[184:187], v[216:219], v[56:59]
	v_mfma_f32_16x16x32_bf16 v[44:47], v[162:165], v[224:227], v[44:47]
	v_mfma_f32_16x16x32_bf16 v[40:43], v[184:187], v[224:227], v[40:43]
	v_mfma_f32_16x16x32_bf16 v[28:31], v[162:165], v[232:235], v[28:31]
	v_mfma_f32_16x16x32_bf16 v[24:27], v[184:187], v[232:235], v[24:27]
	v_mfma_f32_16x16x32_bf16 v[12:15], v[162:165], v[240:243], v[12:15]
	v_mfma_f32_16x16x32_bf16 v[8:11], v[184:187], v[240:243], v[8:11]
	s_setprio 0
	s_setprio 1
	v_mfma_f32_16x16x32_bf16 v[52:55], v[190:193], v[212:215], v[52:55]
	v_mfma_f32_16x16x32_bf16 v[48:51], v[204:207], v[212:215], v[48:51]
	v_mfma_f32_16x16x32_bf16 v[36:39], v[190:193], v[220:223], v[36:39]
	v_mfma_f32_16x16x32_bf16 v[32:35], v[204:207], v[220:223], v[32:35]
	v_mfma_f32_16x16x32_bf16 v[20:23], v[190:193], v[228:231], v[20:23]
	v_mfma_f32_16x16x32_bf16 v[16:19], v[204:207], v[228:231], v[16:19]
	v_mfma_f32_16x16x32_bf16 v[4:7], v[190:193], v[236:239], v[4:7]
	v_mfma_f32_16x16x32_bf16 v[0:3], v[204:207], v[236:239], v[0:3]
	v_mfma_f32_16x16x32_bf16 v[52:55], v[194:197], v[216:219], v[52:55]
	v_mfma_f32_16x16x32_bf16 v[48:51], v[208:211], v[216:219], v[48:51]
	v_mfma_f32_16x16x32_bf16 v[36:39], v[194:197], v[224:227], v[36:39]
	v_mfma_f32_16x16x32_bf16 v[32:35], v[208:211], v[224:227], v[32:35]
	v_mfma_f32_16x16x32_bf16 v[20:23], v[194:197], v[232:235], v[20:23]
	v_mfma_f32_16x16x32_bf16 v[16:19], v[208:211], v[232:235], v[16:19]
	v_mfma_f32_16x16x32_bf16 v[4:7], v[194:197], v[240:243], v[4:7]
	v_mfma_f32_16x16x32_bf16 v[0:3], v[208:211], v[240:243], v[0:3]
	s_setprio 0
	s_barrier
	s_add_u32 s50, s50, 0x100
	s_addc_u32 s51, s51, 0
	s_add_u32 s45, s45, 0x100
	s_addc_u32 s63, s63, 0
	s_cmp_ge_i32 s64, s4
	s_mov_b32 s52, s64
	s_cbranch_scc1 .Lkexit_874

; #define PG8_BAR __builtin_amdgcn_s_barrier()
; template <class Epi, class Sched>
; __device__ __forceinline__ void gemm_phase(const int tid, LAS unsigned char* lds, const int lda, const int ldb, const int K, const Sched& S, const Epi& E) {
;     ...
;         if (wr == 0) PG8_BAR;
;         if (MK_EPI2 && Epi::IDEM) E(acc, cur, wr, wc, fr, fq, es0, es1);
;         E(acc, cur, wr, wc, fr, fq, es0, es1);
;         if (!has_next) break;
.Lkexit_874:
	s_mov_b32 s64, 0x14000
	s_mov_b32 s66, 0x16000
	s_mov_b32 s67, 0x18000
	s_and_b64 vcc, exec, s[42:43]
	s_cbranch_vccz .LBB0_877

; #define PG8_STAGE(bufoff, gbase, voff) do { _Pragma("unroll") for (int _i = 0; _i < 2; ++_i) \
;         __builtin_amdgcn_global_load_lds((const unsigned*)((const char*)(gbase) + (voff)[_i]), (LAS unsigned*)(lds + (bufoff) + ldsw + _i * 8192), 16, 0, 0); } while (0)
; #define PG8_LDA(dst, b, h) do { _Pragma("unroll") for (int m = 0; m < 4; ++m) _Pragma("unroll") for (int k = 0; k < 2; ++k) dst[m][k] = *(const LAS bf16x8*)(lds + PG8_SA(b, h) + aoff + m * 2048 + k * 1024); } while (0)
; #define PG8_LDB(dst, b, h) do { _Pragma("unroll") for (int n = 0; n < 2; ++n) _Pragma("unroll") for (int k = 0; k < 2; ++k) dst[n][k] = *(const LAS bf16x8*)(lds + PG8_SB(b, h) + boff + n * 2048 + k * 1024); } while (0)
; #define PG8_MMA(ai, bj, At, Bt) do { __builtin_amdgcn_s_setprio(1); _Pragma("unroll") for (int m = 0; m < 4; ++m) _Pragma("unroll") for (int n = 0; n < 2; ++n) _Pragma("unroll") for (int k = 0; k < 2; ++k) \
;         acc[ai][bj][m][n] = __builtin_amdgcn_mfma_f32_16x16x32_bf16(Bt[n][k], At[m][k], acc[ai][bj][m][n], 0, 0, 0); __builtin_amdgcn_s_setprio(0); } while (0)
; #define PG8_WAIT_V(n) asm volatile("s_waitcnt vmcnt(" #n ")" ::: "memory")
; #define PG8_WAIT_L(n) asm volatile("s_waitcnt lgkmcnt(" #n ")" ::: "memory")
; #define PG8_BAR __builtin_amdgcn_s_barrier()
; #define PG8_SCHED __builtin_amdgcn_sched_barrier(0)
; template <class Epi, class Sched>
; __device__ __forceinline__ void gemm_phase(const int tid, LAS unsigned char* lds, const int lda, const int ldb, const int K, const Sched& S, const Epi& E) {
;     ...
;             const bool last = (t == nt - 2);
;             const char* a1 = cA + (size_t)(t + 1) * kstep;
;             const char* a2 = last ? nA : cA + (size_t)(t + 2) * kstep; const char* b2 = last ? nB : cB + (size_t)(t + 2) * kstep;
;             const char* a3 = a2 + kstep; const char* b3 = b2 + kstep;
;             PG8_LDB(B0, 0, 0); PG8_LDB(B1, 0, 1); PG8_SCHED; PG8_LDA(At, 0, 0); PG8_STAGE(PG8_SA(1, 1), a1 + hstepA, voffA);
;             PG8_WAIT_V(8); PG8_WAIT_L(0); PG8_BAR; PG8_MMA(0, 0, At, B0); PG8_MMA(0, 1, At, B1); PG8_BAR; PG8_SCHED;
;             PG8_LDA(At, 0, 1); PG8_STAGE(PG8_SB(0, 0), b2, voffB); PG8_STAGE(PG8_SB(0, 1), b2 + hstepB, voffB); PG8_STAGE(PG8_SA(0, 0), a2, voffA);
;             PG8_WAIT_V(8); PG8_WAIT_L(0); PG8_BAR; if (!cur.half) { PG8_MMA(1, 0, At, B0); PG8_MMA(1, 1, At, B1); } PG8_BAR; PG8_SCHED;
.LBB0_894:
	s_andn2_b64 vcc, exec, s[40:41]
	s_cbranch_vccnz .LBB0_902
	s_add_u32 s50, s50, 0x40080
	s_addc_u32 s51, s51, 0
	s_add_u32 s45, s52, 0x100
	s_addc_u32 s64, s53, 0
	s_mov_b32 s52, 0
	s_add_i32 s65, s52, 2
	s_add_u32 s24, s50, 0xfffc0080
	s_addc_u32 s53, s51, -1
	s_add_i32 s66, 0, 0x10000
	s_cmp_eq_u32 s61, s52
	s_cselect_b32 s55, s3, s53
	s_cselect_b32 s54, s2, s24
	v_add_u32_e32 v166, s66, v146
	s_cselect_b32 s53, s39, s64
	s_cselect_b32 s52, s38, s45
	s_add_i32 s24, 0, 0x14000
	ds_read_b128 v[154:157], v166
	ds_read_b128 v[158:161], v166 offset:1024
	ds_read_b128 v[162:165], v166 offset:2048
	ds_read_b128 v[180:183], v166 offset:3072
	v_add_u32_e32 v166, s24, v146
	ds_read_b128 v[184:187], v166
	ds_read_b128 v[190:193], v166 offset:1024
	ds_read_b128 v[194:197], v166 offset:2048
	ds_read_b128 v[204:207], v166 offset:3072
	v_lshl_add_u64 v[166:167], s[50:51], 0, v[136:137]
	s_add_i32 m0, s29, 0xc000
	ds_read_b128 v[208:211], v153
	ds_read_b128 v[212:215], v153 offset:1024
	ds_read_b128 v[216:219], v153 offset:2048
	ds_read_b128 v[220:223], v153 offset:3072
	ds_read_b128 v[224:227], v153 offset:4096
	ds_read_b128 v[228:231], v153 offset:5120
	ds_read_b128 v[232:235], v153 offset:6144
	ds_read_b128 v[236:239], v153 offset:7168
	global_load_lds_dwordx4 v[166:167], off
	v_lshl_add_u64 v[166:167], s[50:51], 0, v[138:139]
	s_add_i32 m0, s29, 0xe000
	s_nop 0
	global_load_lds_dwordx4 v[166:167], off
	s_waitcnt vmcnt(8)
	s_waitcnt lgkmcnt(0)
	s_barrier
	s_setprio 1
	s_waitcnt lgkmcnt(0)
	v_mfma_f32_16x16x32_bf16 v[124:127], v[154:157], v[208:211], 0
	v_mfma_f32_16x16x32_bf16 v[116:119], v[162:165], v[208:211], 0
	v_mfma_f32_16x16x32_bf16 v[108:111], v[154:157], v[216:219], 0
	v_mfma_f32_16x16x32_bf16 v[100:103], v[162:165], v[216:219], 0
	v_mfma_f32_16x16x32_bf16 v[92:95], v[154:157], v[224:227], 0
	v_mfma_f32_16x16x32_bf16 v[84:87], v[162:165], v[224:227], 0
	v_mfma_f32_16x16x32_bf16 v[76:79], v[154:157], v[232:235], 0
	v_mfma_f32_16x16x32_bf16 v[68:71], v[162:165], v[232:235], 0
	v_mfma_f32_16x16x32_bf16 v[124:127], v[158:161], v[212:215], v[124:127]
	v_mfma_f32_16x16x32_bf16 v[116:119], v[180:183], v[212:215], v[116:119]
	v_mfma_f32_16x16x32_bf16 v[108:111], v[158:161], v[220:223], v[108:111]
	v_mfma_f32_16x16x32_bf16 v[100:103], v[180:183], v[220:223], v[100:103]
	v_mfma_f32_16x16x32_bf16 v[92:95], v[158:161], v[228:231], v[92:95]
	v_mfma_f32_16x16x32_bf16 v[84:87], v[180:183], v[228:231], v[84:87]
	v_mfma_f32_16x16x32_bf16 v[76:79], v[158:161], v[236:239], v[76:79]
	v_mfma_f32_16x16x32_bf16 v[68:71], v[180:183], v[236:239], v[68:71]
	s_setprio 0
	s_setprio 1
	v_mfma_f32_16x16x32_bf16 v[120:123], v[184:187], v[208:211], 0
	v_mfma_f32_16x16x32_bf16 v[112:115], v[194:197], v[208:211], 0
	v_mfma_f32_16x16x32_bf16 v[104:107], v[184:187], v[216:219], 0
	v_mfma_f32_16x16x32_bf16 v[96:99], v[194:197], v[216:219], 0
	v_mfma_f32_16x16x32_bf16 v[88:91], v[184:187], v[224:227], 0
	v_mfma_f32_16x16x32_bf16 v[80:83], v[194:197], v[224:227], 0
	v_mfma_f32_16x16x32_bf16 v[72:75], v[184:187], v[232:235], 0
	v_mfma_f32_16x16x32_bf16 v[64:67], v[194:197], v[232:235], 0
	v_mfma_f32_16x16x32_bf16 v[120:123], v[190:193], v[212:215], v[120:123]
	v_mfma_f32_16x16x32_bf16 v[112:115], v[204:207], v[212:215], v[112:115]
	v_mfma_f32_16x16x32_bf16 v[104:107], v[190:193], v[220:223], v[104:107]
	v_mfma_f32_16x16x32_bf16 v[96:99], v[204:207], v[220:223], v[96:99]
	v_mfma_f32_16x16x32_bf16 v[88:91], v[190:193], v[228:231], v[88:91]
	v_mfma_f32_16x16x32_bf16 v[80:83], v[204:207], v[228:231], v[80:83]
	v_mfma_f32_16x16x32_bf16 v[72:75], v[190:193], v[236:239], v[72:75]
	v_mfma_f32_16x16x32_bf16 v[64:67], v[204:207], v[236:239], v[64:67]
	s_setprio 0
	s_barrier
	s_add_i32 s66, s66, s20
	v_lshl_add_u64 v[166:167], s[52:53], 0, v[132:133]
	s_mov_b32 m0, s66
	ds_read_b128 v[208:211], v153 offset:16384
	ds_read_b128 v[212:215], v153 offset:17408
	ds_read_b128 v[216:219], v153 offset:18432
	ds_read_b128 v[220:223], v153 offset:19456
	ds_read_b128 v[224:227], v153 offset:20480
	ds_read_b128 v[228:231], v153 offset:21504
	ds_read_b128 v[232:235], v153 offset:22528
	ds_read_b128 v[236:239], v153 offset:23552
	global_load_lds_dwordx4 v[166:167], off
	s_add_i32 m0, s66, 0x2000
	s_add_u32 s66, s52, 0x40000
	v_lshl_add_u64 v[240:241], s[52:53], 0, v[128:129]
	s_addc_u32 s67, s53, 0
	s_add_i32 s24, s24, s20
	global_load_lds_dwordx4 v[240:241], off
	v_lshl_add_u64 v[242:243], s[66:67], 0, v[132:133]
	s_mov_b32 m0, s24
	v_lshl_add_u64 v[244:245], s[54:55], 0, v[130:131]
	global_load_lds_dwordx4 v[242:243], off
	v_lshl_add_u64 v[242:243], s[66:67], 0, v[128:129]
	s_add_i32 m0, s24, 0x2000
	s_nop 0
	global_load_lds_dwordx4 v[242:243], off
	v_lshl_add_u64 v[242:243], s[54:55], 0, v[134:135]
	s_waitcnt vmcnt(6)
	s_waitcnt lgkmcnt(0)
	s_barrier
; #define PG8_STAGE(bufoff, gbase, voff) do { _Pragma("unroll") for (int _i = 0; _i < 2; ++_i) \
;         __builtin_amdgcn_global_load_lds((const unsigned*)((const char*)(gbase) + (voff)[_i]), (LAS unsigned*)(lds + (bufoff) + ldsw + _i * 8192), 16, 0, 0); } while (0)
; #define PG8_LDA(dst, b, h) do { _Pragma("unroll") for (int m = 0; m < 4; ++m) _Pragma("unroll") for (int k = 0; k < 2; ++k) dst[m][k] = *(const LAS bf16x8*)(lds + PG8_SA(b, h) + aoff + m * 2048 + k * 1024); } while (0)
; #define PG8_LDB(dst, b, h) do { _Pragma("unroll") for (int n = 0; n < 2; ++n) _Pragma("unroll") for (int k = 0; k < 2; ++k) dst[n][k] = *(const LAS bf16x8*)(lds + PG8_SB(b, h) + boff + n * 2048 + k * 1024); } while (0)
; #define PG8_MMA(ai, bj, At, Bt) do { __builtin_amdgcn_s_setprio(1); _Pragma("unroll") for (int m = 0; m < 4; ++m) _Pragma("unroll") for (int n = 0; n < 2; ++n) _Pragma("unroll") for (int k = 0; k < 2; ++k) \
;         acc[ai][bj][m][n] = __builtin_amdgcn_mfma_f32_16x16x32_bf16(Bt[n][k], At[m][k], acc[ai][bj][m][n], 0, 0, 0); __builtin_amdgcn_s_setprio(0); } while (0)
; #define PG8_WAIT_V(n) asm volatile("s_waitcnt vmcnt(" #n ")" ::: "memory")
; #define PG8_WAIT_L(n) asm volatile("s_waitcnt lgkmcnt(" #n ")" ::: "memory")
; #define PG8_BAR __builtin_amdgcn_s_barrier()
; #define PG8_SCHED __builtin_amdgcn_sched_barrier(0)
; template <class Epi, class Sched>
; __device__ __forceinline__ void gemm_phase(const int tid, LAS unsigned char* lds, const int lda, const int ldb, const int K, const Sched& S, const Epi& E) {
;     ...
;             PG8_WAIT_V(8); PG8_WAIT_L(0); PG8_BAR; if (!cur.half) { PG8_MMA(1, 0, At, B0); PG8_MMA(1, 1, At, B1); } PG8_BAR; PG8_SCHED;
;             PG8_LDB(B0, 1, 0); PG8_LDB(B1, 1, 1); PG8_SCHED; PG8_LDA(At, 1, 0); PG8_STAGE(PG8_SA(0, 1), a2 + hstepA, voffA);
;             PG8_WAIT_V(8); PG8_WAIT_L(0); PG8_BAR; PG8_MMA(0, 0, At, B0); PG8_MMA(0, 1, At, B1); PG8_BAR; PG8_SCHED;
	s_setprio 1
	s_waitcnt lgkmcnt(0)
	v_mfma_f32_16x16x32_bf16 v[60:63], v[154:157], v[208:211], 0
	v_mfma_f32_16x16x32_bf16 v[52:55], v[162:165], v[208:211], 0
	v_mfma_f32_16x16x32_bf16 v[44:47], v[154:157], v[216:219], 0
	v_mfma_f32_16x16x32_bf16 v[36:39], v[162:165], v[216:219], 0
	v_mfma_f32_16x16x32_bf16 v[28:31], v[154:157], v[224:227], 0
	v_mfma_f32_16x16x32_bf16 v[20:23], v[162:165], v[224:227], 0
	v_mfma_f32_16x16x32_bf16 v[12:15], v[154:157], v[232:235], 0
	v_mfma_f32_16x16x32_bf16 v[4:7], v[162:165], v[232:235], 0
	v_mfma_f32_16x16x32_bf16 v[60:63], v[158:161], v[212:215], v[60:63]
	v_mfma_f32_16x16x32_bf16 v[52:55], v[180:183], v[212:215], v[52:55]
	v_mfma_f32_16x16x32_bf16 v[44:47], v[158:161], v[220:223], v[44:47]
	v_mfma_f32_16x16x32_bf16 v[36:39], v[180:183], v[220:223], v[36:39]
	v_mfma_f32_16x16x32_bf16 v[28:31], v[158:161], v[228:231], v[28:31]
	v_mfma_f32_16x16x32_bf16 v[20:23], v[180:183], v[228:231], v[20:23]
	v_mfma_f32_16x16x32_bf16 v[12:15], v[158:161], v[236:239], v[12:15]
	v_mfma_f32_16x16x32_bf16 v[4:7], v[180:183], v[236:239], v[4:7]
	s_setprio 0
	s_setprio 1
	v_mfma_f32_16x16x32_bf16 v[56:59], v[184:187], v[208:211], 0
	v_mfma_f32_16x16x32_bf16 v[48:51], v[194:197], v[208:211], 0
	v_mfma_f32_16x16x32_bf16 v[40:43], v[184:187], v[216:219], 0
	v_mfma_f32_16x16x32_bf16 v[32:35], v[194:197], v[216:219], 0
	v_mfma_f32_16x16x32_bf16 v[24:27], v[184:187], v[224:227], 0
	v_mfma_f32_16x16x32_bf16 v[16:19], v[194:197], v[224:227], 0
	v_mfma_f32_16x16x32_bf16 v[8:11], v[184:187], v[232:235], 0
	v_mfma_f32_16x16x32_bf16 v[0:3], v[194:197], v[232:235], 0
	v_mfma_f32_16x16x32_bf16 v[56:59], v[190:193], v[212:215], v[56:59]
	v_mfma_f32_16x16x32_bf16 v[48:51], v[204:207], v[212:215], v[48:51]
	v_mfma_f32_16x16x32_bf16 v[40:43], v[190:193], v[220:223], v[40:43]
	v_mfma_f32_16x16x32_bf16 v[32:35], v[204:207], v[220:223], v[32:35]
	v_mfma_f32_16x16x32_bf16 v[24:27], v[190:193], v[228:231], v[24:27]
	v_mfma_f32_16x16x32_bf16 v[16:19], v[204:207], v[228:231], v[16:19]
	v_mfma_f32_16x16x32_bf16 v[8:11], v[190:193], v[236:239], v[8:11]
	v_mfma_f32_16x16x32_bf16 v[0:3], v[204:207], v[236:239], v[0:3]
	s_setprio 0
	s_barrier
	s_add_i32 s24, 0, 0x18000
	v_add_u32_e32 v176, s24, v146
	s_add_i32 s66, 0, 0x1c000
	ds_read_b128 v[154:157], v176
	ds_read_b128 v[158:161], v176 offset:1024
	ds_read_b128 v[162:165], v176 offset:2048
	ds_read_b128 v[180:183], v176 offset:3072
	v_add_u32_e32 v176, s66, v146
	ds_read_b128 v[184:187], v176
	ds_read_b128 v[190:193], v176 offset:1024
	ds_read_b128 v[194:197], v176 offset:2048
	ds_read_b128 v[204:207], v176 offset:3072
	s_mov_b32 m0, s29
	s_nop 0
	global_load_lds_dwordx4 v[242:243], off
	s_mov_b32 m0, s31
	s_nop 0
	global_load_lds_dwordx4 v[244:245], off
	s_add_u32 s54, s54, 0x40000
	s_addc_u32 s55, s55, 0
	s_mov_b32 m0, s56
	v_lshl_add_u64 v[246:247], s[54:55], 0, v[134:135]
	ds_read_b128 v[208:211], v153 offset:32768
	ds_read_b128 v[212:215], v153 offset:33792
	ds_read_b128 v[216:219], v153 offset:34816
	ds_read_b128 v[220:223], v153 offset:35840
	ds_read_b128 v[224:227], v153 offset:36864
	ds_read_b128 v[228:231], v153 offset:37888
	ds_read_b128 v[232:235], v153 offset:38912
	ds_read_b128 v[236:239], v153 offset:39936
	global_load_lds_dwordx4 v[246:247], off
	v_lshl_add_u64 v[246:247], s[54:55], 0, v[130:131]
	s_mov_b32 m0, s57
	s_nop 0
	global_load_lds_dwordx4 v[246:247], off
	s_waitcnt vmcnt(8)
	s_waitcnt lgkmcnt(0)
	s_barrier
	s_setprio 1
	s_waitcnt lgkmcnt(0)
	v_mfma_f32_16x16x32_bf16 v[124:127], v[154:157], v[208:211], v[124:127]
	v_mfma_f32_16x16x32_bf16 v[116:119], v[162:165], v[208:211], v[116:119]
	v_mfma_f32_16x16x32_bf16 v[108:111], v[154:157], v[216:219], v[108:111]
	v_mfma_f32_16x16x32_bf16 v[100:103], v[162:165], v[216:219], v[100:103]
	v_mfma_f32_16x16x32_bf16 v[92:95], v[154:157], v[224:227], v[92:95]
	v_mfma_f32_16x16x32_bf16 v[84:87], v[162:165], v[224:227], v[84:87]
	v_mfma_f32_16x16x32_bf16 v[76:79], v[154:157], v[232:235], v[76:79]
	v_mfma_f32_16x16x32_bf16 v[68:71], v[162:165], v[232:235], v[68:71]
	v_mfma_f32_16x16x32_bf16 v[124:127], v[158:161], v[212:215], v[124:127]
	v_mfma_f32_16x16x32_bf16 v[116:119], v[180:183], v[212:215], v[116:119]
	v_mfma_f32_16x16x32_bf16 v[108:111], v[158:161], v[220:223], v[108:111]
	v_mfma_f32_16x16x32_bf16 v[100:103], v[180:183], v[220:223], v[100:103]
	v_mfma_f32_16x16x32_bf16 v[92:95], v[158:161], v[228:231], v[92:95]
	v_mfma_f32_16x16x32_bf16 v[84:87], v[180:183], v[228:231], v[84:87]
	v_mfma_f32_16x16x32_bf16 v[76:79], v[158:161], v[236:239], v[76:79]
	v_mfma_f32_16x16x32_bf16 v[68:71], v[180:183], v[236:239], v[68:71]
	s_setprio 0
	s_setprio 1
	v_mfma_f32_16x16x32_bf16 v[120:123], v[184:187], v[208:211], v[120:123]
	v_mfma_f32_16x16x32_bf16 v[112:115], v[194:197], v[208:211], v[112:115]
	v_mfma_f32_16x16x32_bf16 v[104:107], v[184:187], v[216:219], v[104:107]
	v_mfma_f32_16x16x32_bf16 v[96:99], v[194:197], v[216:219], v[96:99]
	v_mfma_f32_16x16x32_bf16 v[88:91], v[184:187], v[224:227], v[88:91]
	v_mfma_f32_16x16x32_bf16 v[80:83], v[194:197], v[224:227], v[80:83]
	v_mfma_f32_16x16x32_bf16 v[72:75], v[184:187], v[232:235], v[72:75]
	v_mfma_f32_16x16x32_bf16 v[64:67], v[194:197], v[232:235], v[64:67]
	v_mfma_f32_16x16x32_bf16 v[120:123], v[190:193], v[212:215], v[120:123]
	v_mfma_f32_16x16x32_bf16 v[112:115], v[204:207], v[212:215], v[112:115]
	v_mfma_f32_16x16x32_bf16 v[104:107], v[190:193], v[220:223], v[104:107]
	v_mfma_f32_16x16x32_bf16 v[96:99], v[204:207], v[220:223], v[96:99]
	v_mfma_f32_16x16x32_bf16 v[88:91], v[190:193], v[228:231], v[88:91]
	v_mfma_f32_16x16x32_bf16 v[80:83], v[204:207], v[228:231], v[80:83]
	v_mfma_f32_16x16x32_bf16 v[72:75], v[190:193], v[236:239], v[72:75]
	v_mfma_f32_16x16x32_bf16 v[64:67], v[204:207], v[236:239], v[64:67]
	s_setprio 0
	s_barrier
; #define PG8_STAGE(bufoff, gbase, voff) do { _Pragma("unroll") for (int _i = 0; _i < 2; ++_i) \
;         __builtin_amdgcn_global_load_lds((const unsigned*)((const char*)(gbase) + (voff)[_i]), (LAS unsigned*)(lds + (bufoff) + ldsw + _i * 8192), 16, 0, 0); } while (0)
; #define PG8_LDA(dst, b, h) do { _Pragma("unroll") for (int m = 0; m < 4; ++m) _Pragma("unroll") for (int k = 0; k < 2; ++k) dst[m][k] = *(const LAS bf16x8*)(lds + PG8_SA(b, h) + aoff + m * 2048 + k * 1024); } while (0)
; #define PG8_MMA(ai, bj, At, Bt) do { __builtin_amdgcn_s_setprio(1); _Pragma("unroll") for (int m = 0; m < 4; ++m) _Pragma("unroll") for (int n = 0; n < 2; ++n) _Pragma("unroll") for (int k = 0; k < 2; ++k) \
;         acc[ai][bj][m][n] = __builtin_amdgcn_mfma_f32_16x16x32_bf16(Bt[n][k], At[m][k], acc[ai][bj][m][n], 0, 0, 0); __builtin_amdgcn_s_setprio(0); } while (0)
; #define PG8_WAIT_V(n) asm volatile("s_waitcnt vmcnt(" #n ")" ::: "memory")
; #define PG8_WAIT_L(n) asm volatile("s_waitcnt lgkmcnt(" #n ")" ::: "memory")
; #define PG8_BAR __builtin_amdgcn_s_barrier()
; #define PG8_SCHED __builtin_amdgcn_sched_barrier(0)
; template <class Epi, class Sched>
; __device__ __forceinline__ void gemm_phase(const int tid, LAS unsigned char* lds, const int lda, const int ldb, const int K, const Sched& S, const Epi& E) {
;     ...
;         for (int t = 0; t < nt; t += 2) {
;     ...
;             PG8_LDA(At, 1, 1); PG8_STAGE(PG8_SB(1, 0), b3, voffB); PG8_STAGE(PG8_SB(1, 1), b3 + hstepB, voffB); PG8_STAGE(PG8_SA(1, 0), a3, voffA);
;             PG8_WAIT_V(8); PG8_WAIT_L(0); PG8_BAR; if (!cur.half) { PG8_MMA(1, 0, At, B0); PG8_MMA(1, 1, At, B1); } PG8_BAR; PG8_SCHED;
	s_add_i32 s24, s24, s20
	v_lshl_add_u64 v[166:167], v[166:167], 0, s[6:7]
	s_mov_b32 m0, s24
	ds_read_b128 v[208:211], v153 offset:49152
	ds_read_b128 v[212:215], v153 offset:50176
	ds_read_b128 v[216:219], v153 offset:51200
	ds_read_b128 v[220:223], v153 offset:52224
	ds_read_b128 v[224:227], v153 offset:53248
	ds_read_b128 v[228:231], v153 offset:54272
	ds_read_b128 v[232:235], v153 offset:55296
	ds_read_b128 v[236:239], v153 offset:56320
	global_load_lds_dwordx4 v[166:167], off
	s_add_i32 m0, s24, 0x2000
	s_add_u32 s52, s52, 0x40080
	v_lshl_add_u64 v[166:167], v[240:241], 0, s[6:7]
	s_addc_u32 s53, s53, 0
	s_add_i32 s24, s66, s20
	global_load_lds_dwordx4 v[166:167], off
	v_lshl_add_u64 v[166:167], s[52:53], 0, v[132:133]
	s_mov_b32 m0, s24
	s_nop 0
	global_load_lds_dwordx4 v[166:167], off
	v_lshl_add_u64 v[166:167], s[52:53], 0, v[128:129]
	s_add_i32 m0, s24, 0x2000
	s_nop 0
	global_load_lds_dwordx4 v[166:167], off
	v_lshl_add_u64 v[166:167], v[242:243], 0, s[6:7]
	s_mov_b32 m0, s58
	s_nop 0
	global_load_lds_dwordx4 v[166:167], off
	v_lshl_add_u64 v[166:167], v[244:245], 0, s[6:7]
	s_mov_b32 m0, s59
	s_nop 0
	global_load_lds_dwordx4 v[166:167], off
	s_waitcnt vmcnt(8)
	s_waitcnt lgkmcnt(0)
	s_barrier
	s_setprio 1
	s_waitcnt lgkmcnt(0)
	v_mfma_f32_16x16x32_bf16 v[60:63], v[154:157], v[208:211], v[60:63]
	v_mfma_f32_16x16x32_bf16 v[52:55], v[162:165], v[208:211], v[52:55]
	v_mfma_f32_16x16x32_bf16 v[44:47], v[154:157], v[216:219], v[44:47]
	v_mfma_f32_16x16x32_bf16 v[36:39], v[162:165], v[216:219], v[36:39]
	v_mfma_f32_16x16x32_bf16 v[28:31], v[154:157], v[224:227], v[28:31]
	v_mfma_f32_16x16x32_bf16 v[20:23], v[162:165], v[224:227], v[20:23]
	v_mfma_f32_16x16x32_bf16 v[12:15], v[154:157], v[232:235], v[12:15]
	v_mfma_f32_16x16x32_bf16 v[4:7], v[162:165], v[232:235], v[4:7]
	v_mfma_f32_16x16x32_bf16 v[60:63], v[158:161], v[212:215], v[60:63]
	v_mfma_f32_16x16x32_bf16 v[52:55], v[180:183], v[212:215], v[52:55]
	v_mfma_f32_16x16x32_bf16 v[44:47], v[158:161], v[220:223], v[44:47]
	v_mfma_f32_16x16x32_bf16 v[36:39], v[180:183], v[220:223], v[36:39]
	v_mfma_f32_16x16x32_bf16 v[28:31], v[158:161], v[228:231], v[28:31]
	v_mfma_f32_16x16x32_bf16 v[20:23], v[180:183], v[228:231], v[20:23]
	v_mfma_f32_16x16x32_bf16 v[12:15], v[158:161], v[236:239], v[12:15]
	v_mfma_f32_16x16x32_bf16 v[4:7], v[180:183], v[236:239], v[4:7]
	s_setprio 0
	s_setprio 1
	v_mfma_f32_16x16x32_bf16 v[56:59], v[184:187], v[208:211], v[56:59]
	v_mfma_f32_16x16x32_bf16 v[48:51], v[194:197], v[208:211], v[48:51]
	v_mfma_f32_16x16x32_bf16 v[40:43], v[184:187], v[216:219], v[40:43]
	v_mfma_f32_16x16x32_bf16 v[32:35], v[194:197], v[216:219], v[32:35]
	v_mfma_f32_16x16x32_bf16 v[24:27], v[184:187], v[224:227], v[24:27]
	v_mfma_f32_16x16x32_bf16 v[16:19], v[194:197], v[224:227], v[16:19]
	v_mfma_f32_16x16x32_bf16 v[8:11], v[184:187], v[232:235], v[8:11]
	v_mfma_f32_16x16x32_bf16 v[0:3], v[194:197], v[232:235], v[0:3]
	v_mfma_f32_16x16x32_bf16 v[56:59], v[190:193], v[212:215], v[56:59]
	v_mfma_f32_16x16x32_bf16 v[48:51], v[204:207], v[212:215], v[48:51]
	v_mfma_f32_16x16x32_bf16 v[40:43], v[190:193], v[220:223], v[40:43]
	v_mfma_f32_16x16x32_bf16 v[32:35], v[204:207], v[220:223], v[32:35]
	v_mfma_f32_16x16x32_bf16 v[24:27], v[190:193], v[228:231], v[24:27]
	v_mfma_f32_16x16x32_bf16 v[16:19], v[204:207], v[228:231], v[16:19]
	v_mfma_f32_16x16x32_bf16 v[8:11], v[190:193], v[236:239], v[8:11]
	v_mfma_f32_16x16x32_bf16 v[0:3], v[204:207], v[236:239], v[0:3]
	s_setprio 0
	s_barrier
	s_add_u32 s50, s50, 0x100
	s_addc_u32 s51, s51, 0
	s_add_u32 s45, s45, 0x100
	s_addc_u32 s64, s64, 0
	s_cmp_ge_i32 s65, s13
	s_mov_b32 s52, s65
	s_cbranch_scc1 .Lkexit_896

; #define PG8_BAR __builtin_amdgcn_s_barrier()
; template <class Epi, class Sched>
; __device__ __forceinline__ void gemm_phase(const int tid, LAS unsigned char* lds, const int lda, const int ldb, const int K, const Sched& S, const Epi& E) {
;     ...
;         if (wr == 0) PG8_BAR;
;         if (MK_EPI2 && Epi::IDEM) E(acc, cur, wr, wc, fr, fq, es0, es1);
;         E(acc, cur, wr, wc, fr, fq, es0, es1);
;         if (!has_next) break;
.Lkexit_896:
	s_mov_b32 s65, 0x12000
	s_mov_b32 s64, 0x14000
	s_mov_b32 s66, 0x16000
	s_mov_b32 s67, 0x18000
	s_and_b64 vcc, exec, s[42:43]
	s_cbranch_vccz .LBB0_899
